# conformer conv inputs fetched a pass ahead; RG-LRU bias float4 loaded once per direction (borrowing constant registers in the outputs pass)
# baseline (speedup 1.0000x reference)
.LBB0_895:
	v_mov_b32_e32 v14, v222
	v_readlane_b32 s0, v252, 46
	v_ashrrev_i32_e32 v2, 6, v14
	v_bfe_u32 v16, v14, 4, 2
	v_add_u32_e32 v0, s0, v2
	v_readlane_b32 s0, v252, 47
	v_ashrrev_i32_e32 v1, 31, v0
	v_lshlrev_b64 v[0:1], 13, v[0:1]
	v_add_u32_e32 v4, s0, v2
	v_ashrrev_i32_e32 v5, 31, v4
	v_and_b32_e32 v15, 15, v14
	v_lshl_add_u64 v[0:1], s[84:85], 0, v[0:1]
	v_lshlrev_b64 v[4:5], 13, v[4:5]
	v_lshlrev_b32_e32 v2, 4, v16
	v_lshl_add_u64 v[4:5], s[84:85], 0, v[4:5]
	v_lshl_add_u64 v[0:1], v[0:1], 0, v[2:3]
	v_lshlrev_b32_e32 v6, 7, v15
	v_mov_b32_e32 v7, v3
	v_lshl_add_u64 v[4:5], v[4:5], 0, v[2:3]
	v_lshl_add_u64 v[8:9], v[0:1], 0, v[6:7]
	v_lshl_add_u64 v[10:11], v[4:5], 0, v[6:7]
	global_load_dwordx4 v[120:123], v[8:9], off
	global_load_dwordx4 v[116:119], v[10:11], off
	global_load_dwordx4 v[162:165], v[8:9], off offset:64
	global_load_dwordx4 v[124:127], v[10:11], off offset:64
	global_load_dwordx4 v[104:107], v[8:9], off offset:2048
	global_load_dwordx4 v[100:103], v[10:11], off offset:2048
	global_load_dwordx4 v[112:115], v[8:9], off offset:2112
	global_load_dwordx4 v[108:111], v[10:11], off offset:2112
	v_or_b32_e32 v8, 0x1000, v6
	v_mov_b32_e32 v9, v3
	v_lshl_add_u64 v[10:11], v[0:1], 0, v[8:9]
	v_lshl_add_u64 v[8:9], v[4:5], 0, v[8:9]
	global_load_dwordx4 v[88:91], v[10:11], off
	global_load_dwordx4 v[84:87], v[8:9], off
	global_load_dwordx4 v[96:99], v[10:11], off offset:64
	global_load_dwordx4 v[92:95], v[8:9], off offset:64
	v_or_b32_e32 v6, 0x1800, v6
	v_and_b32_e32 v8, 0xffffffc0, v14
	v_lshl_add_u64 v[0:1], v[0:1], 0, v[6:7]
	v_ashrrev_i32_e32 v9, 31, v8
	v_readlane_b32 s0, v252, 48
	v_lshl_add_u64 v[4:5], v[4:5], 0, v[6:7]
	global_load_dwordx4 v[72:75], v[0:1], off
	global_load_dwordx4 v[68:71], v[4:5], off
	global_load_dwordx4 v[80:83], v[0:1], off offset:64
	global_load_dwordx4 v[76:79], v[4:5], off offset:64
	v_lshlrev_b64 v[0:1], 2, v[8:9]
	v_readlane_b32 s1, v252, 49
	s_movk_i32 s6, 0x88
	v_lshl_or_b32 v33, v16, 2, v8
	v_lshl_add_u64 v[10:11], s[0:1], 0, v[0:1]
	v_readlane_b32 s0, v252, 50
	v_readlane_b32 s1, v252, 51
	v_lshlrev_b32_e32 v34, 3, v15
	v_lshlrev_b32_e32 v17, 3, v16
	v_lshl_add_u64 v[4:5], s[0:1], 0, v[0:1]
	v_lshl_add_u64 v[12:13], v[4:5], 0, v[2:3]
	v_readlane_b32 s0, v252, 52
	v_readlane_b32 s1, v252, 53
	s_mov_b32 s7, 0x1f000
	s_movk_i32 s22, 0xd000
	v_lshl_add_u64 v[0:1], s[0:1], 0, v[0:1]
	v_lshl_add_u64 v[170:171], v[0:1], 0, v[2:3]
	v_lshl_add_u64 v[0:1], v[10:11], 0, v[2:3]
	v_readlane_b32 s0, v252, 54
	s_movk_i32 s13, 0xb000
	s_movk_i32 s12, 0x9000
	s_mov_b32 s33, 0xffff6000
	s_mov_b32 s38, 0xffff4000
	s_mov_b32 s39, 0xffff2000
	s_mov_b32 s42, 0xffff1000
	s_mov_b32 s43, 0xfffef000
	s_mov_b32 s56, 0xfffed000
	s_mov_b32 s57, 0xfffeb000
	s_mov_b32 s58, 0xfffea000
	s_mov_b32 s59, 0xfffe6000
	s_waitcnt vmcnt(0)
	s_lshl_b32 s98, s16, 11
	s_add_u32 s98, s98, 0x8000
	s_add_u32 s98, s30, s98
	s_addc_u32 s99, s31, 0
	v_lshrrev_b32_e32 v187, 4, v222
	v_and_b32_e32 v186, 3, v187
	v_lshrrev_b32_e32 v187, 2, v187
	v_lshlrev_b32_e32 v186, 4, v186
	v_lshl_or_b32 v187, v187, 8, v186
	global_load_dword v172, v187, s[98:99]
	global_load_dword v173, v187, s[98:99] offset:4
	global_load_dword v174, v187, s[98:99] offset:8
	global_load_dword v175, v187, s[98:99] offset:12
	global_load_dword v176, v187, s[98:99] offset:64
	global_load_dword v177, v187, s[98:99] offset:68
	global_load_dword v179, v187, s[98:99] offset:72
	global_load_dword v181, v187, s[98:99] offset:76
	global_load_dword v178, v187, s[98:99] offset:128
	global_load_dword v180, v187, s[98:99] offset:132
	global_load_dword v182, v187, s[98:99] offset:136
	global_load_dword v183, v187, s[98:99] offset:140
	global_load_dword v184, v187, s[98:99] offset:192
	global_load_dword v185, v187, s[98:99] offset:196
	global_load_dword v186, v187, s[98:99] offset:200
	global_load_dword v187, v187, s[98:99] offset:204
	v_mul_lo_u32 v5, v14, s6
	v_add_u32_e32 v32, 32, v5
	v_mul_u32_u24_e32 v5, 0x220, v15
	v_add_u32_e32 v188, 0x8800, v32
	v_lshl_add_u32 v4, v8, 1, 32
	v_add3_u32 v166, v4, v5, v2
	ds_read_b128 v[4:7], v166
	ds_read_b128 v[8:11], v166 offset:64
	global_load_dwordx4 v[240:243], v[170:171], off
	global_load_dwordx4 v[244:247], v[0:1], off
	global_load_dwordx4 v[248:251], v[170:171], off offset:64
	global_load_dwordx4 v[224:227], v[0:1], off offset:64
	global_load_dword v223, v[170:171], off offset:128
	global_load_dword v229, v[170:171], off offset:132
	global_load_dword v230, v[170:171], off offset:136
	global_load_dword v231, v[170:171], off offset:140
	global_load_dword v232, v[0:1], off offset:128
	global_load_dword v237, v[0:1], off offset:132
	global_load_dword v238, v[0:1], off offset:136
	global_load_dword v239, v[0:1], off offset:140
	s_waitcnt vmcnt(0)
	v_mov_b32_e32 v20, v240
	v_mov_b32_e32 v21, v241
	v_mov_b32_e32 v22, v242
	v_mov_b32_e32 v23, v243
	v_mov_b32_e32 v24, v244
	v_mov_b32_e32 v25, v245
	v_mov_b32_e32 v26, v246
	v_mov_b32_e32 v27, v247
	s_waitcnt lgkmcnt(1)
	v_mfma_f32_16x16x32_bf16 v[12:15], v[120:123], v[4:7], 0
	v_sub_u32_e32 v2, v166, v17
	ds_read_b64 v[28:29], v2
	s_waitcnt lgkmcnt(0)
	v_lshlrev_b32_e32 v31, 16, v28
	v_mfma_f32_16x16x32_bf16 v[16:19], v[162:165], v[8:11], v[12:15]
	v_and_b32_e32 v35, 0xffff0000, v28
	v_lshlrev_b32_e32 v36, 16, v29
	v_and_b32_e32 v29, 0xffff0000, v29
	v_mfma_f32_16x16x32_bf16 v[12:15], v[116:119], v[4:7], 0
	v_mfma_f32_16x16x32_bf16 v[12:15], v[124:127], v[8:11], v[12:15]
	s_waitcnt vmcnt(1)
	s_nop 1
	v_add_f32_e32 v16, v16, v20
	v_mul_f32_e32 v16, 0xbfb8aa3b, v16
	v_exp_f32_e32 v16, v16
	s_waitcnt vmcnt(0)
	s_nop 0
	v_add_f32_e32 v12, v12, v24
	v_mul_f32_e32 v12, 0xbfb8aa3b, v12
	v_exp_f32_e32 v12, v12
	v_add_f32_e32 v16, 1.0, v16
	v_rcp_f32_e32 v16, v16
	v_add_f32_e32 v13, v13, v25
	v_add_f32_e32 v12, 1.0, v12
	v_rcp_f32_e32 v12, v12
	v_mul_f32_e32 v16, 0xc1000000, v16
	s_waitcnt vmcnt(0)
	v_mul_f32_e32 v16, v16, v172
	v_mul_f32_e32 v16, 0x3fb8aa3b, v16
	v_exp_f32_e32 v30, v16
	v_mul_f32_e32 v13, 0xbfb8aa3b, v13
	v_exp_f32_e32 v13, v13
	v_add_f32_e32 v15, v15, v27
	v_sub_f32_e32 v16, 1.0, v30
	v_add_f32_e32 v20, 1.0, v30
	v_mul_f32_e32 v16, v16, v20
	v_max_f32_e32 v16, 0, v16
	v_sqrt_f32_e32 v16, v16
	v_add_f32_e32 v13, 1.0, v13
	v_rcp_f32_e32 v13, v13
	v_mul_f32_e32 v15, 0xbfb8aa3b, v15
	v_mul_f32_e32 v12, v12, v16
	v_mul_f32_e32 v31, v12, v31
	v_mul_lo_u32 v12, v33, s6
	v_add3_u32 v28, 32, v34, v12
	v_add_f32_e32 v12, v17, v21
	v_mul_f32_e32 v12, 0xbfb8aa3b, v12
	v_exp_f32_e32 v12, v12
	v_add_u32_e32 v190, 0x8800, v28
	v_exp_f32_e32 v15, v15
	v_add_u32_e32 v191, 0x9000, v28
	v_add_f32_e32 v12, 1.0, v12
	v_rcp_f32_e32 v12, v12
	v_add_f32_e32 v15, 1.0, v15
	v_rcp_f32_e32 v15, v15
	v_add_u32_e32 v192, 0x9800, v28
	v_mul_f32_e32 v12, 0xc1000000, v12
	v_mul_f32_e32 v12, v12, v173
	v_mul_f32_e32 v12, 0x3fb8aa3b, v12
	v_exp_f32_e32 v12, v12
	v_add_u32_e32 v189, 0xa000, v28
	v_sub_f32_e32 v16, 1.0, v12
	v_add_f32_e32 v17, 1.0, v12
	v_mul_f32_e32 v16, v16, v17
	v_max_f32_e32 v16, 0, v16
	v_sqrt_f32_e32 v16, v16
	s_nop 0
	v_mul_f32_e32 v13, v13, v16
	v_mul_f32_e32 v13, v13, v35
	ds_write2_b64 v190, v[30:31], v[12:13] offset1:17
	v_add_f32_e32 v12, v18, v22
	v_mul_f32_e32 v12, 0xbfb8aa3b, v12
	v_exp_f32_e32 v12, v12
	v_add_f32_e32 v13, v14, v26
	v_mul_f32_e32 v13, 0xbfb8aa3b, v13
	v_exp_f32_e32 v13, v13
	v_add_f32_e32 v12, 1.0, v12
	v_rcp_f32_e32 v12, v12
	v_add_f32_e32 v13, 1.0, v13
	v_rcp_f32_e32 v13, v13
	v_mul_f32_e32 v12, 0xc1000000, v12
	v_mul_f32_e32 v12, v12, v174
	v_mul_f32_e32 v12, 0x3fb8aa3b, v12
	v_exp_f32_e32 v12, v12
	s_nop 0
	v_sub_f32_e32 v14, 1.0, v12
	v_add_f32_e32 v16, 1.0, v12
	v_mul_f32_e32 v14, v14, v16
	v_max_f32_e32 v14, 0, v14
	v_sqrt_f32_e32 v14, v14
	s_nop 0
	v_mul_f32_e32 v13, v13, v14
	v_add_f32_e32 v14, v19, v23
	v_mul_f32_e32 v14, 0xbfb8aa3b, v14
	v_exp_f32_e32 v14, v14
	v_mul_f32_e32 v13, v13, v36
	v_add_f32_e32 v14, 1.0, v14
	v_rcp_f32_e32 v14, v14
	s_nop 0
	v_mul_f32_e32 v14, 0xc1000000, v14
	v_mul_f32_e32 v14, v14, v175
	v_mul_f32_e32 v14, 0x3fb8aa3b, v14
	v_exp_f32_e32 v14, v14
	s_nop 0
	v_sub_f32_e32 v16, 1.0, v14
	v_add_f32_e32 v17, 1.0, v14
	v_mul_f32_e32 v16, v16, v17
	v_max_f32_e32 v16, 0, v16
	v_sqrt_f32_e32 v16, v16
	s_nop 0
	v_mul_f32_e32 v15, v15, v16
	v_mul_f32_e32 v15, v15, v29
	ds_write2_b64 v190, v[12:13], v[14:15] offset0:34 offset1:51
	v_mov_b32_e32 v20, v248
	v_mov_b32_e32 v21, v249
	v_mov_b32_e32 v22, v250
	v_mov_b32_e32 v23, v251
	v_mov_b32_e32 v24, v224
	v_mov_b32_e32 v25, v225
	v_mov_b32_e32 v26, v226
	v_mov_b32_e32 v27, v227
	v_mfma_f32_16x16x32_bf16 v[12:15], v[104:107], v[4:7], 0
	ds_read_b64 v[30:31], v2 offset:32
	s_waitcnt lgkmcnt(0)
	v_lshlrev_b32_e32 v29, 16, v30
	v_mfma_f32_16x16x32_bf16 v[16:19], v[112:115], v[8:11], v[12:15]
	v_and_b32_e32 v33, 0xffff0000, v30
	v_lshlrev_b32_e32 v34, 16, v31
	v_and_b32_e32 v35, 0xffff0000, v31
	v_mfma_f32_16x16x32_bf16 v[12:15], v[100:103], v[4:7], 0
	v_mfma_f32_16x16x32_bf16 v[12:15], v[108:111], v[8:11], v[12:15]
	s_waitcnt vmcnt(1)
	s_nop 1
	v_add_f32_e32 v16, v16, v20
	v_mul_f32_e32 v16, 0xbfb8aa3b, v16
	v_exp_f32_e32 v16, v16
	s_waitcnt vmcnt(0)
	s_nop 0
	v_add_f32_e32 v12, v12, v24
	v_mul_f32_e32 v12, 0xbfb8aa3b, v12
	v_exp_f32_e32 v12, v12
	v_add_f32_e32 v16, 1.0, v16
	v_rcp_f32_e32 v16, v16
	v_add_f32_e32 v13, v13, v25
	v_add_f32_e32 v12, 1.0, v12
	v_rcp_f32_e32 v12, v12
	v_mul_f32_e32 v16, 0xc1000000, v16
	v_mul_f32_e32 v16, v16, v176
	v_mul_f32_e32 v16, 0x3fb8aa3b, v16
	v_exp_f32_e32 v30, v16
	v_mul_f32_e32 v13, 0xbfb8aa3b, v13
	v_exp_f32_e32 v13, v13
	v_add_f32_e32 v15, v15, v27
	v_sub_f32_e32 v16, 1.0, v30
	v_add_f32_e32 v20, 1.0, v30
	v_mul_f32_e32 v16, v16, v20
	v_max_f32_e32 v16, 0, v16
	v_sqrt_f32_e32 v16, v16
	v_add_f32_e32 v13, 1.0, v13
	v_rcp_f32_e32 v13, v13
	v_mul_f32_e32 v15, 0xbfb8aa3b, v15
	v_mul_f32_e32 v12, v12, v16
	v_mul_f32_e32 v31, v12, v29
	v_add_f32_e32 v12, v17, v21
	v_mul_f32_e32 v12, 0xbfb8aa3b, v12
	v_exp_f32_e32 v12, v12
	v_exp_f32_e32 v15, v15
	v_add_f32_e32 v12, 1.0, v12
	v_rcp_f32_e32 v12, v12
	v_add_f32_e32 v15, 1.0, v15
	v_rcp_f32_e32 v15, v15
	v_mul_f32_e32 v12, 0xc1000000, v12
	v_mul_f32_e32 v12, v12, v177
	v_mul_f32_e32 v12, 0x3fb8aa3b, v12
	v_exp_f32_e32 v12, v12
	s_nop 0
	v_sub_f32_e32 v16, 1.0, v12
	v_add_f32_e32 v17, 1.0, v12
	v_mul_f32_e32 v16, v16, v17
	v_max_f32_e32 v16, 0, v16
	v_sqrt_f32_e32 v16, v16
	s_nop 0
	v_mul_f32_e32 v13, v13, v16
	v_mul_f32_e32 v13, v13, v33
	ds_write2_b64 v191, v[30:31], v[12:13] offset0:16 offset1:33
	v_add_f32_e32 v12, v18, v22
	v_mul_f32_e32 v12, 0xbfb8aa3b, v12
	v_exp_f32_e32 v12, v12
	v_add_f32_e32 v13, v14, v26
	v_mul_f32_e32 v13, 0xbfb8aa3b, v13
	v_exp_f32_e32 v13, v13
	v_add_f32_e32 v12, 1.0, v12
	v_rcp_f32_e32 v12, v12
	v_add_f32_e32 v13, 1.0, v13
	v_rcp_f32_e32 v13, v13
	v_mul_f32_e32 v12, 0xc1000000, v12
	v_mul_f32_e32 v12, v12, v179
	v_mul_f32_e32 v12, 0x3fb8aa3b, v12
	v_exp_f32_e32 v12, v12
	s_nop 0
	v_sub_f32_e32 v14, 1.0, v12
	v_add_f32_e32 v16, 1.0, v12
	v_mul_f32_e32 v14, v14, v16
	v_max_f32_e32 v14, 0, v14
	v_sqrt_f32_e32 v14, v14
	s_nop 0
	v_mul_f32_e32 v13, v13, v14
	v_add_f32_e32 v14, v19, v23
	v_mul_f32_e32 v14, 0xbfb8aa3b, v14
	v_exp_f32_e32 v14, v14
	v_mul_f32_e32 v13, v13, v34
	v_add_f32_e32 v14, 1.0, v14
	v_rcp_f32_e32 v14, v14
	s_nop 0
	v_mul_f32_e32 v14, 0xc1000000, v14
	v_mul_f32_e32 v14, v14, v181
	v_mul_f32_e32 v14, 0x3fb8aa3b, v14
	v_exp_f32_e32 v14, v14
	s_nop 0
	v_sub_f32_e32 v16, 1.0, v14
	v_add_f32_e32 v17, 1.0, v14
	v_mul_f32_e32 v16, v16, v17
	v_max_f32_e32 v16, 0, v16
	v_sqrt_f32_e32 v16, v16
	s_nop 0
	v_mul_f32_e32 v15, v15, v16
	v_mul_f32_e32 v15, v15, v35
	ds_write2_b64 v191, v[12:13], v[14:15] offset0:50 offset1:67
	v_mov_b32_e32 v20, v223
	v_mov_b32_e32 v21, v229
	v_mov_b32_e32 v22, v230
	v_mov_b32_e32 v23, v231
	v_mov_b32_e32 v24, v232
	v_mov_b32_e32 v25, v237
	v_mov_b32_e32 v26, v238
	v_mov_b32_e32 v27, v239
	v_mfma_f32_16x16x32_bf16 v[12:15], v[88:91], v[4:7], 0
	ds_read_b64 v[30:31], v2 offset:64
	s_waitcnt lgkmcnt(0)
	v_lshlrev_b32_e32 v29, 16, v30
	v_mfma_f32_16x16x32_bf16 v[16:19], v[96:99], v[8:11], v[12:15]
	v_and_b32_e32 v33, 0xffff0000, v30
	v_lshlrev_b32_e32 v34, 16, v31
	v_and_b32_e32 v35, 0xffff0000, v31
	v_mfma_f32_16x16x32_bf16 v[12:15], v[84:87], v[4:7], 0
	v_mfma_f32_16x16x32_bf16 v[12:15], v[92:95], v[8:11], v[12:15]
	s_waitcnt vmcnt(1)
	s_nop 1
	v_add_f32_e32 v16, v16, v20
	v_mul_f32_e32 v16, 0xbfb8aa3b, v16
	v_exp_f32_e32 v16, v16
	s_waitcnt vmcnt(0)
	s_nop 0
	v_add_f32_e32 v12, v12, v24
	v_mul_f32_e32 v12, 0xbfb8aa3b, v12
	v_exp_f32_e32 v12, v12
	v_add_f32_e32 v16, 1.0, v16
	v_rcp_f32_e32 v16, v16
	v_add_f32_e32 v13, v13, v25
	v_add_f32_e32 v12, 1.0, v12
	v_rcp_f32_e32 v12, v12
	v_mul_f32_e32 v16, 0xc1000000, v16
	v_mul_f32_e32 v16, v16, v178
	v_mul_f32_e32 v16, 0x3fb8aa3b, v16
	v_exp_f32_e32 v30, v16
	v_mul_f32_e32 v13, 0xbfb8aa3b, v13
	v_exp_f32_e32 v13, v13
	v_add_f32_e32 v15, v15, v27
	v_sub_f32_e32 v16, 1.0, v30
	v_add_f32_e32 v20, 1.0, v30
	v_mul_f32_e32 v16, v16, v20
	v_max_f32_e32 v16, 0, v16
	v_sqrt_f32_e32 v16, v16
	v_add_f32_e32 v13, 1.0, v13
	v_rcp_f32_e32 v13, v13
	v_mul_f32_e32 v15, 0xbfb8aa3b, v15
	v_mul_f32_e32 v12, v12, v16
	v_mul_f32_e32 v31, v12, v29
	v_add_f32_e32 v12, v17, v21
	v_mul_f32_e32 v12, 0xbfb8aa3b, v12
	v_exp_f32_e32 v12, v12
	v_exp_f32_e32 v15, v15
	v_add_f32_e32 v12, 1.0, v12
	v_rcp_f32_e32 v12, v12
	v_add_f32_e32 v15, 1.0, v15
	v_rcp_f32_e32 v15, v15
	v_mul_f32_e32 v12, 0xc1000000, v12
	v_mul_f32_e32 v12, v12, v180
	v_mul_f32_e32 v12, 0x3fb8aa3b, v12
	v_exp_f32_e32 v12, v12
	s_nop 0
	v_sub_f32_e32 v16, 1.0, v12
	v_add_f32_e32 v17, 1.0, v12
	v_mul_f32_e32 v16, v16, v17
	v_max_f32_e32 v16, 0, v16
	v_sqrt_f32_e32 v16, v16
	s_nop 0
	v_mul_f32_e32 v13, v13, v16
	v_mul_f32_e32 v13, v13, v33
	ds_write2_b64 v192, v[30:31], v[12:13] offset0:32 offset1:49
	v_add_f32_e32 v12, v18, v22
	v_mul_f32_e32 v12, 0xbfb8aa3b, v12
	v_exp_f32_e32 v12, v12
	v_add_f32_e32 v13, v14, v26
	v_mul_f32_e32 v13, 0xbfb8aa3b, v13
	v_exp_f32_e32 v13, v13
	v_add_f32_e32 v12, 1.0, v12
	v_rcp_f32_e32 v12, v12
	v_add_f32_e32 v13, 1.0, v13
	v_rcp_f32_e32 v13, v13
	v_mul_f32_e32 v12, 0xc1000000, v12
	v_mul_f32_e32 v12, v12, v182
	v_mul_f32_e32 v12, 0x3fb8aa3b, v12
	v_exp_f32_e32 v12, v12
	s_nop 0
	v_sub_f32_e32 v14, 1.0, v12
	v_add_f32_e32 v16, 1.0, v12
	v_mul_f32_e32 v14, v14, v16
	v_max_f32_e32 v14, 0, v14
	v_sqrt_f32_e32 v14, v14
	s_nop 0
	v_mul_f32_e32 v13, v13, v14
	v_add_f32_e32 v14, v19, v23
	v_mul_f32_e32 v14, 0xbfb8aa3b, v14
	v_exp_f32_e32 v14, v14
	v_mul_f32_e32 v13, v13, v34
	v_add_f32_e32 v14, 1.0, v14
	v_rcp_f32_e32 v14, v14
	s_nop 0
	v_mul_f32_e32 v14, 0xc1000000, v14
	v_mul_f32_e32 v14, v14, v183
	v_mul_f32_e32 v14, 0x3fb8aa3b, v14
	v_exp_f32_e32 v14, v14
	s_nop 0
	v_sub_f32_e32 v16, 1.0, v14
	v_add_f32_e32 v17, 1.0, v14
	v_mul_f32_e32 v16, v16, v17
	v_max_f32_e32 v16, 0, v16
	v_sqrt_f32_e32 v16, v16
	s_nop 0
	v_mul_f32_e32 v15, v15, v16
	v_mul_f32_e32 v15, v15, v35
	ds_write2_b64 v192, v[12:13], v[14:15] offset0:66 offset1:83
	v_mfma_f32_16x16x32_bf16 v[12:15], v[72:75], v[4:7], 0
	v_mfma_f32_16x16x32_bf16 v[4:7], v[68:71], v[4:7], 0
	v_mfma_f32_16x16x32_bf16 v[12:15], v[80:83], v[8:11], v[12:15]
	v_mfma_f32_16x16x32_bf16 v[4:7], v[76:79], v[8:11], v[4:7]
	global_load_dwordx4 v[8:11], v[170:171], off offset:192
	global_load_dwordx4 v[16:19], v[0:1], off offset:192
	ds_read_b64 v[20:21], v2 offset:96
	s_waitcnt lgkmcnt(0)
	v_lshlrev_b32_e32 v22, 16, v20
	v_and_b32_e32 v23, 0xffff0000, v20
	v_lshlrev_b32_e32 v24, 16, v21
	v_and_b32_e32 v25, 0xffff0000, v21
	s_waitcnt vmcnt(1)
	v_add_f32_e32 v8, v12, v8
	v_mul_f32_e32 v8, 0xbfb8aa3b, v8
	v_exp_f32_e32 v8, v8
	s_waitcnt vmcnt(0)
	v_add_f32_e32 v4, v4, v16
	v_mul_f32_e32 v4, 0xbfb8aa3b, v4
	v_exp_f32_e32 v4, v4
	v_add_f32_e32 v8, 1.0, v8
	v_rcp_f32_e32 v8, v8
	v_add_f32_e32 v5, v5, v17
	v_add_f32_e32 v4, 1.0, v4
	v_rcp_f32_e32 v4, v4
	v_mul_f32_e32 v8, 0xc1000000, v8
	v_mul_f32_e32 v8, v184, v8
	v_mul_f32_e32 v8, 0x3fb8aa3b, v8
	v_exp_f32_e32 v20, v8
	v_mul_f32_e32 v5, 0xbfb8aa3b, v5
	v_exp_f32_e32 v5, v5
	v_add_f32_e32 v7, v7, v19
	v_sub_f32_e32 v8, 1.0, v20
	v_add_f32_e32 v12, 1.0, v20
	v_mul_f32_e32 v8, v8, v12
	v_max_f32_e32 v8, 0, v8
	v_sqrt_f32_e32 v8, v8
	v_add_f32_e32 v5, 1.0, v5
	v_rcp_f32_e32 v5, v5
	v_mul_f32_e32 v7, 0xbfb8aa3b, v7
	v_mul_f32_e32 v4, v4, v8
	v_mul_f32_e32 v21, v4, v22
	v_add_f32_e32 v4, v13, v9
	v_mul_f32_e32 v4, 0xbfb8aa3b, v4
	v_exp_f32_e32 v4, v4
	v_exp_f32_e32 v7, v7
	v_add_f32_e32 v4, 1.0, v4
	v_rcp_f32_e32 v4, v4
	v_add_f32_e32 v7, 1.0, v7
	v_rcp_f32_e32 v7, v7
	v_mul_f32_e32 v4, 0xc1000000, v4
	v_mul_f32_e32 v4, v185, v4
	v_mul_f32_e32 v4, 0x3fb8aa3b, v4
	v_exp_f32_e32 v4, v4
	s_nop 0
	v_sub_f32_e32 v8, 1.0, v4
	v_add_f32_e32 v9, 1.0, v4
	v_mul_f32_e32 v8, v8, v9
	v_max_f32_e32 v8, 0, v8
	v_sqrt_f32_e32 v8, v8
	s_nop 0
	v_mul_f32_e32 v5, v5, v8
	v_mul_f32_e32 v5, v5, v23
	ds_write2_b64 v189, v[20:21], v[4:5] offset0:48 offset1:65
	v_add_f32_e32 v4, v14, v10
	v_mul_f32_e32 v4, 0xbfb8aa3b, v4
	v_exp_f32_e32 v4, v4
	v_add_f32_e32 v5, v6, v18
	v_mul_f32_e32 v5, 0xbfb8aa3b, v5
	v_exp_f32_e32 v5, v5
	v_add_f32_e32 v4, 1.0, v4
	v_rcp_f32_e32 v4, v4
	v_add_f32_e32 v5, 1.0, v5
	v_rcp_f32_e32 v5, v5
	v_mul_f32_e32 v4, 0xc1000000, v4
	v_mul_f32_e32 v4, v186, v4
	v_mul_f32_e32 v4, 0x3fb8aa3b, v4
	v_exp_f32_e32 v4, v4
	s_nop 0
	v_sub_f32_e32 v6, 1.0, v4
	v_add_f32_e32 v8, 1.0, v4
	v_mul_f32_e32 v6, v6, v8
	v_max_f32_e32 v6, 0, v6
	v_sqrt_f32_e32 v6, v6
	s_nop 0
	v_mul_f32_e32 v5, v5, v6
	v_add_f32_e32 v6, v15, v11
	v_mul_f32_e32 v6, 0xbfb8aa3b, v6
	v_exp_f32_e32 v6, v6
	v_mul_f32_e32 v5, v5, v24
	v_add_f32_e32 v6, 1.0, v6
	v_rcp_f32_e32 v6, v6
	s_nop 0
	v_mul_f32_e32 v6, 0xc1000000, v6
	v_mul_f32_e32 v6, v187, v6
	v_mul_f32_e32 v6, 0x3fb8aa3b, v6
	v_exp_f32_e32 v6, v6
	s_nop 0
	v_sub_f32_e32 v8, 1.0, v6
	v_add_f32_e32 v9, 1.0, v6
	v_mul_f32_e32 v8, v8, v9
	v_max_f32_e32 v8, 0, v8
	v_sqrt_f32_e32 v8, v8
	s_nop 0
	v_mul_f32_e32 v7, v7, v8
	v_mul_f32_e32 v7, v7, v25
	ds_write2_b64 v189, v[4:5], v[6:7] offset0:82 offset1:99
	s_waitcnt lgkmcnt(0)
	s_barrier
	ds_read2_b64 v[4:7], v188 offset1:1
	s_waitcnt lgkmcnt(0)
	v_fma_f32 v220, v40, v4, v5
	v_add_u32_e32 v4, 0x8810, v32
	ds_read2_b64 v[8:11], v4 offset1:1
	v_add_u32_e32 v5, 0x8820, v32
	v_fmac_f32_e32 v7, v6, v220
	ds_read2_b64 v[12:15], v5 offset1:1
	s_waitcnt lgkmcnt(1)
	v_fma_f32 v6, v8, v7, v9
	v_add_u32_e32 v8, 0x8830, v32
	ds_read2_b64 v[16:19], v8 offset1:1
	v_fmac_f32_e32 v11, v10, v6
	s_waitcnt lgkmcnt(1)
	v_fma_f32 v10, v12, v11, v13
	v_fmac_f32_e32 v15, v14, v10
	v_add_u32_e32 v9, 0x8840, v32
	ds_read2_b64 v[20:23], v9 offset1:1
	s_waitcnt lgkmcnt(1)
	v_fma_f32 v14, v16, v15, v17
	v_add_u32_e32 v12, 0x8850, v32
	v_add_u32_e32 v13, 0x8860, v32
	v_add_u32_e32 v16, 0x8870, v32
	ds_read2_b64 v[24:27], v12 offset1:1
	ds_read2_b64 v[28:31], v13 offset1:1
	ds_read2_b64 v[32:35], v16 offset1:1
	s_waitcnt lgkmcnt(0)
	s_barrier
	ds_read_b128 v[36:39], v166 offset:8704
	ds_read_b128 v[40:43], v166 offset:8768
	v_mov_b32_e32 v52, v240
	v_mov_b32_e32 v53, v241
	v_mov_b32_e32 v54, v242
	v_mov_b32_e32 v55, v243
	v_mov_b32_e32 v56, v244
	v_mov_b32_e32 v57, v245
	v_mov_b32_e32 v58, v246
	v_mov_b32_e32 v59, v247
	s_waitcnt lgkmcnt(1)
	v_mfma_f32_16x16x32_bf16 v[44:47], v[120:123], v[36:39], 0
	v_fmac_f32_e32 v19, v18, v14
	v_fma_f32 v18, v20, v19, v21
	ds_read_b64 v[20:21], v2 offset:8704
	s_waitcnt lgkmcnt(1)
	v_mfma_f32_16x16x32_bf16 v[44:47], v[162:165], v[40:43], v[44:47]
	v_fmac_f32_e32 v23, v22, v18
	v_fma_f32 v22, v24, v23, v25
	v_fmac_f32_e32 v27, v26, v22
	s_waitcnt lgkmcnt(0)
	v_lshlrev_b32_e32 v17, 16, v20
	v_and_b32_e32 v25, 0xffff0000, v20
	v_mfma_f32_16x16x32_bf16 v[48:51], v[116:119], v[36:39], 0
	v_fma_f32 v26, v28, v27, v29
	v_fmac_f32_e32 v31, v30, v26
	v_lshlrev_b32_e32 v29, 16, v21
	v_mfma_f32_16x16x32_bf16 v[48:51], v[124:127], v[40:43], v[48:51]
	v_and_b32_e32 v30, 0xffff0000, v21
	v_fma_f32 v28, v32, v31, v33
	v_fmac_f32_e32 v35, v34, v28
	s_waitcnt vmcnt(1)
	v_add_f32_e32 v20, v44, v52
	v_mul_f32_e32 v20, 0xbfb8aa3b, v20
	v_exp_f32_e32 v20, v20
	s_waitcnt vmcnt(0)
	v_add_f32_e32 v21, v48, v56
	v_mul_f32_e32 v21, 0xbfb8aa3b, v21
	v_exp_f32_e32 v21, v21
	v_add_f32_e32 v20, 1.0, v20
	v_rcp_f32_e32 v20, v20
	v_add_f32_e32 v21, 1.0, v21
	v_rcp_f32_e32 v21, v21
	v_mul_f32_e32 v20, 0xc1000000, v20
	v_mul_f32_e32 v20, v172, v20
	v_mul_f32_e32 v20, 0x3fb8aa3b, v20
	v_exp_f32_e32 v20, v20
	s_nop 0
	v_sub_f32_e32 v24, 1.0, v20
	v_add_f32_e32 v32, 1.0, v20
	v_mul_f32_e32 v24, v24, v32
	v_max_f32_e32 v24, 0, v24
	v_sqrt_f32_e32 v24, v24
	s_nop 0
	v_mul_f32_e32 v21, v21, v24
	v_mul_f32_e32 v21, v21, v17
	v_add_f32_e32 v17, v45, v53
	v_mul_f32_e32 v17, 0xbfb8aa3b, v17
	v_exp_f32_e32 v17, v17
	v_add_f32_e32 v24, v49, v57
	v_mul_f32_e32 v24, 0xbfb8aa3b, v24
	v_exp_f32_e32 v24, v24
	v_add_f32_e32 v17, 1.0, v17
	v_rcp_f32_e32 v17, v17
	v_add_f32_e32 v24, 1.0, v24
	v_rcp_f32_e32 v32, v24
	v_mul_f32_e32 v17, 0xc1000000, v17
	v_mul_f32_e32 v17, v173, v17
	v_mul_f32_e32 v17, 0x3fb8aa3b, v17
	v_exp_f32_e32 v24, v17
	s_nop 0
	v_sub_f32_e32 v17, 1.0, v24
	v_add_f32_e32 v33, 1.0, v24
	v_mul_f32_e32 v17, v17, v33
	v_max_f32_e32 v17, 0, v17
	v_sqrt_f32_e32 v17, v17
	s_nop 0
	v_mul_f32_e32 v17, v32, v17
	v_mul_f32_e32 v25, v17, v25
	v_add_f32_e32 v17, v46, v54
	v_mul_f32_e32 v17, 0xbfb8aa3b, v17
	v_exp_f32_e32 v17, v17
	ds_write2_b64 v190, v[20:21], v[24:25] offset1:17
	v_add_f32_e32 v20, v50, v58
	v_mul_f32_e32 v20, 0xbfb8aa3b, v20
	v_add_f32_e32 v17, 1.0, v17
	v_rcp_f32_e32 v17, v17
	v_exp_f32_e32 v20, v20
	v_mul_f32_e32 v17, 0xc1000000, v17
	v_mul_f32_e32 v17, v174, v17
	v_add_f32_e32 v20, 1.0, v20
	v_mul_f32_e32 v17, 0x3fb8aa3b, v17
	v_rcp_f32_e32 v21, v20
	v_exp_f32_e32 v20, v17
	s_nop 0
	v_sub_f32_e32 v17, 1.0, v20
	v_add_f32_e32 v24, 1.0, v20
	v_mul_f32_e32 v17, v17, v24
	v_max_f32_e32 v17, 0, v17
	v_sqrt_f32_e32 v17, v17
	v_add_f32_e32 v24, v51, v59
	v_mul_f32_e32 v24, 0xbfb8aa3b, v24
	v_exp_f32_e32 v24, v24
	v_mul_f32_e32 v17, v21, v17
	v_mul_f32_e32 v21, v17, v29
	v_add_f32_e32 v17, v47, v55
	v_mul_f32_e32 v17, 0xbfb8aa3b, v17
	v_exp_f32_e32 v17, v17
	v_add_f32_e32 v24, 1.0, v24
	v_rcp_f32_e32 v25, v24
	v_mfma_f32_16x16x32_bf16 v[44:47], v[104:107], v[36:39], 0
	v_add_f32_e32 v17, 1.0, v17
	v_rcp_f32_e32 v17, v17
	v_mfma_f32_16x16x32_bf16 v[48:51], v[112:115], v[40:43], v[44:47]
	v_mul_f32_e32 v17, 0xc1000000, v17
	v_mul_f32_e32 v17, v175, v17
	v_mul_f32_e32 v17, 0x3fb8aa3b, v17
	v_exp_f32_e32 v24, v17
	v_mfma_f32_16x16x32_bf16 v[44:47], v[100:103], v[36:39], 0
	v_sub_f32_e32 v17, 1.0, v24
	v_add_f32_e32 v29, 1.0, v24
	v_mul_f32_e32 v17, v17, v29
	v_max_f32_e32 v17, 0, v17
	v_sqrt_f32_e32 v17, v17
	v_mfma_f32_16x16x32_bf16 v[44:47], v[108:111], v[40:43], v[44:47]
	v_mul_f32_e32 v17, v25, v17
	v_mul_f32_e32 v25, v17, v30
	ds_write2_b64 v190, v[20:21], v[24:25] offset0:34 offset1:51
	v_mov_b32_e32 v52, v248
	v_mov_b32_e32 v53, v249
	v_mov_b32_e32 v54, v250
	v_mov_b32_e32 v55, v251
	v_mov_b32_e32 v56, v224
	v_mov_b32_e32 v57, v225
	v_mov_b32_e32 v58, v226
	v_mov_b32_e32 v59, v227
	ds_read_b64 v[20:21], v2 offset:8736
	s_waitcnt lgkmcnt(0)
	v_lshlrev_b32_e32 v17, 16, v20
	v_and_b32_e32 v25, 0xffff0000, v20
	v_lshlrev_b32_e32 v29, 16, v21
	v_and_b32_e32 v30, 0xffff0000, v21
	s_waitcnt vmcnt(1)
	v_add_f32_e32 v20, v48, v52
	v_mul_f32_e32 v20, 0xbfb8aa3b, v20
	v_exp_f32_e32 v20, v20
	s_waitcnt vmcnt(0)
	v_add_f32_e32 v21, v44, v56
	v_mul_f32_e32 v21, 0xbfb8aa3b, v21
	v_exp_f32_e32 v21, v21
	v_add_f32_e32 v20, 1.0, v20
	v_rcp_f32_e32 v20, v20
	v_add_f32_e32 v21, 1.0, v21
	v_rcp_f32_e32 v21, v21
	v_mul_f32_e32 v20, 0xc1000000, v20
	v_mul_f32_e32 v20, v176, v20
	v_mul_f32_e32 v20, 0x3fb8aa3b, v20
	v_exp_f32_e32 v20, v20
	s_nop 0
	v_sub_f32_e32 v24, 1.0, v20
	v_add_f32_e32 v32, 1.0, v20
	v_mul_f32_e32 v24, v24, v32
	v_max_f32_e32 v24, 0, v24
	v_sqrt_f32_e32 v24, v24
	s_nop 0
	v_mul_f32_e32 v21, v21, v24
	v_mul_f32_e32 v21, v21, v17
	v_add_f32_e32 v17, v49, v53
	v_mul_f32_e32 v17, 0xbfb8aa3b, v17
	v_exp_f32_e32 v17, v17
	v_add_f32_e32 v24, v45, v57
	v_mul_f32_e32 v24, 0xbfb8aa3b, v24
	v_exp_f32_e32 v24, v24
	v_add_f32_e32 v17, 1.0, v17
	v_rcp_f32_e32 v17, v17
	v_add_f32_e32 v24, 1.0, v24
	v_rcp_f32_e32 v32, v24
	v_mul_f32_e32 v17, 0xc1000000, v17
	v_mul_f32_e32 v17, v177, v17
	v_mul_f32_e32 v17, 0x3fb8aa3b, v17
	v_exp_f32_e32 v24, v17
	s_nop 0
	v_sub_f32_e32 v17, 1.0, v24
	v_add_f32_e32 v33, 1.0, v24
	v_mul_f32_e32 v17, v17, v33
	v_max_f32_e32 v17, 0, v17
	v_sqrt_f32_e32 v17, v17
	s_nop 0
	v_mul_f32_e32 v17, v32, v17
	v_mul_f32_e32 v25, v17, v25
	v_add_f32_e32 v17, v50, v54
	v_mul_f32_e32 v17, 0xbfb8aa3b, v17
	v_exp_f32_e32 v17, v17
	ds_write2_b64 v191, v[20:21], v[24:25] offset0:16 offset1:33
	v_add_f32_e32 v20, v46, v58
	v_mul_f32_e32 v20, 0xbfb8aa3b, v20
	v_add_f32_e32 v17, 1.0, v17
	v_rcp_f32_e32 v17, v17
	v_exp_f32_e32 v20, v20
	v_mul_f32_e32 v17, 0xc1000000, v17
	v_mul_f32_e32 v17, v179, v17
	v_add_f32_e32 v20, 1.0, v20
	v_mul_f32_e32 v17, 0x3fb8aa3b, v17
	v_rcp_f32_e32 v21, v20
	v_exp_f32_e32 v20, v17
	s_nop 0
	v_sub_f32_e32 v17, 1.0, v20
	v_add_f32_e32 v24, 1.0, v20
	v_mul_f32_e32 v17, v17, v24
	v_max_f32_e32 v17, 0, v17
	v_sqrt_f32_e32 v17, v17
	v_add_f32_e32 v24, v47, v59
	v_mul_f32_e32 v24, 0xbfb8aa3b, v24
	v_exp_f32_e32 v24, v24
	v_mul_f32_e32 v17, v21, v17
	v_mul_f32_e32 v21, v17, v29
	v_add_f32_e32 v17, v51, v55
	v_mul_f32_e32 v17, 0xbfb8aa3b, v17
	v_exp_f32_e32 v17, v17
	v_add_f32_e32 v24, 1.0, v24
	v_rcp_f32_e32 v25, v24
	v_mfma_f32_16x16x32_bf16 v[44:47], v[88:91], v[36:39], 0
	v_add_f32_e32 v17, 1.0, v17
	v_rcp_f32_e32 v17, v17
	v_mfma_f32_16x16x32_bf16 v[48:51], v[96:99], v[40:43], v[44:47]
	v_mul_f32_e32 v17, 0xc1000000, v17
	v_mul_f32_e32 v17, v181, v17
	v_mul_f32_e32 v17, 0x3fb8aa3b, v17
	v_exp_f32_e32 v24, v17
	v_mfma_f32_16x16x32_bf16 v[44:47], v[84:87], v[36:39], 0
	v_sub_f32_e32 v17, 1.0, v24
	v_add_f32_e32 v29, 1.0, v24
	v_mul_f32_e32 v17, v17, v29
	v_max_f32_e32 v17, 0, v17
	v_sqrt_f32_e32 v17, v17
	v_mfma_f32_16x16x32_bf16 v[44:47], v[92:95], v[40:43], v[44:47]
	v_mul_f32_e32 v17, v25, v17
	v_mul_f32_e32 v25, v17, v30
	ds_write2_b64 v191, v[20:21], v[24:25] offset0:50 offset1:67
	v_mov_b32_e32 v52, v223
	v_mov_b32_e32 v53, v229
	v_mov_b32_e32 v54, v230
	v_mov_b32_e32 v55, v231
	v_mov_b32_e32 v56, v232
	v_mov_b32_e32 v57, v237
	v_mov_b32_e32 v58, v238
	v_mov_b32_e32 v59, v239
	ds_read_b64 v[20:21], v2 offset:8768
	s_waitcnt lgkmcnt(0)
	v_lshlrev_b32_e32 v17, 16, v20
	v_and_b32_e32 v25, 0xffff0000, v20
	v_lshlrev_b32_e32 v29, 16, v21
	v_and_b32_e32 v30, 0xffff0000, v21
	s_waitcnt vmcnt(1)
	v_add_f32_e32 v20, v48, v52
	v_mul_f32_e32 v20, 0xbfb8aa3b, v20
	v_exp_f32_e32 v20, v20
	s_waitcnt vmcnt(0)
	v_add_f32_e32 v21, v44, v56
	v_mul_f32_e32 v21, 0xbfb8aa3b, v21
	v_exp_f32_e32 v21, v21
	v_add_f32_e32 v20, 1.0, v20
	v_rcp_f32_e32 v20, v20
	v_add_f32_e32 v21, 1.0, v21
	v_rcp_f32_e32 v21, v21
	v_mul_f32_e32 v20, 0xc1000000, v20
	v_mul_f32_e32 v20, v178, v20
	v_mul_f32_e32 v20, 0x3fb8aa3b, v20
	v_exp_f32_e32 v20, v20
	s_nop 0
	v_sub_f32_e32 v24, 1.0, v20
	v_add_f32_e32 v32, 1.0, v20
	v_mul_f32_e32 v24, v24, v32
	v_max_f32_e32 v24, 0, v24
	v_sqrt_f32_e32 v24, v24
	s_nop 0
	v_mul_f32_e32 v21, v21, v24
	v_mul_f32_e32 v21, v21, v17
	v_add_f32_e32 v17, v49, v53
	v_mul_f32_e32 v17, 0xbfb8aa3b, v17
	v_exp_f32_e32 v17, v17
	v_add_f32_e32 v24, v45, v57
	v_mul_f32_e32 v24, 0xbfb8aa3b, v24
	v_exp_f32_e32 v24, v24
	v_add_f32_e32 v17, 1.0, v17
	v_rcp_f32_e32 v17, v17
	v_add_f32_e32 v24, 1.0, v24
	v_rcp_f32_e32 v32, v24
	v_mul_f32_e32 v17, 0xc1000000, v17
	v_mul_f32_e32 v17, v180, v17
	v_mul_f32_e32 v17, 0x3fb8aa3b, v17
	v_exp_f32_e32 v24, v17
	s_nop 0
	v_sub_f32_e32 v17, 1.0, v24
	v_add_f32_e32 v33, 1.0, v24
	v_mul_f32_e32 v17, v17, v33
	v_max_f32_e32 v17, 0, v17
	v_sqrt_f32_e32 v17, v17
	s_nop 0
	v_mul_f32_e32 v17, v32, v17
	v_mul_f32_e32 v25, v17, v25
	v_add_f32_e32 v17, v50, v54
	v_mul_f32_e32 v17, 0xbfb8aa3b, v17
	v_exp_f32_e32 v17, v17
	ds_write2_b64 v192, v[20:21], v[24:25] offset0:32 offset1:49
	v_add_f32_e32 v20, v46, v58
	v_mul_f32_e32 v20, 0xbfb8aa3b, v20
	v_add_f32_e32 v17, 1.0, v17
	v_rcp_f32_e32 v17, v17
	v_exp_f32_e32 v20, v20
	v_mul_f32_e32 v17, 0xc1000000, v17
	v_mul_f32_e32 v17, v182, v17
	v_add_f32_e32 v20, 1.0, v20
	v_mul_f32_e32 v17, 0x3fb8aa3b, v17
	v_rcp_f32_e32 v21, v20
	v_exp_f32_e32 v20, v17
	s_nop 0
	v_sub_f32_e32 v17, 1.0, v20
	v_add_f32_e32 v24, 1.0, v20
	v_mul_f32_e32 v17, v17, v24
	v_max_f32_e32 v17, 0, v17
	v_sqrt_f32_e32 v17, v17
	v_add_f32_e32 v24, v47, v59
	v_mul_f32_e32 v24, 0xbfb8aa3b, v24
	v_exp_f32_e32 v24, v24
	v_mul_f32_e32 v17, v21, v17
	v_mul_f32_e32 v21, v17, v29
	v_add_f32_e32 v17, v51, v55
	v_mul_f32_e32 v17, 0xbfb8aa3b, v17
	v_exp_f32_e32 v17, v17
	v_add_f32_e32 v24, 1.0, v24
	v_rcp_f32_e32 v25, v24
	v_mfma_f32_16x16x32_bf16 v[44:47], v[72:75], v[36:39], 0
	v_add_f32_e32 v17, 1.0, v17
	v_rcp_f32_e32 v17, v17
	v_mfma_f32_16x16x32_bf16 v[36:39], v[68:71], v[36:39], 0
	v_mul_f32_e32 v17, 0xc1000000, v17
	v_mul_f32_e32 v17, v183, v17
	v_mul_f32_e32 v17, 0x3fb8aa3b, v17
	v_exp_f32_e32 v24, v17
	v_mfma_f32_16x16x32_bf16 v[44:47], v[80:83], v[40:43], v[44:47]
	v_sub_f32_e32 v17, 1.0, v24
	v_add_f32_e32 v29, 1.0, v24
	v_mul_f32_e32 v17, v17, v29
	v_max_f32_e32 v17, 0, v17
	v_sqrt_f32_e32 v17, v17
	v_mfma_f32_16x16x32_bf16 v[36:39], v[76:79], v[40:43], v[36:39]
	v_mul_f32_e32 v17, v25, v17
	v_mul_f32_e32 v25, v17, v30
	ds_write2_b64 v192, v[20:21], v[24:25] offset0:66 offset1:83
	global_load_dwordx4 v[40:43], v[170:171], off offset:192
	global_load_dwordx4 v[48:51], v[0:1], off offset:192
	ds_read_b64 v[20:21], v2 offset:8800
	s_waitcnt lgkmcnt(0)
	v_lshlrev_b32_e32 v17, 16, v20
	v_and_b32_e32 v25, 0xffff0000, v20
	v_lshlrev_b32_e32 v29, 16, v21
	v_and_b32_e32 v30, 0xffff0000, v21
	s_waitcnt vmcnt(1)
	v_add_f32_e32 v20, v44, v40
	v_mul_f32_e32 v20, 0xbfb8aa3b, v20
	v_exp_f32_e32 v20, v20
	s_waitcnt vmcnt(0)
	v_add_f32_e32 v21, v36, v48
	v_mul_f32_e32 v21, 0xbfb8aa3b, v21
	v_exp_f32_e32 v21, v21
	v_add_f32_e32 v20, 1.0, v20
	v_rcp_f32_e32 v20, v20
	v_add_f32_e32 v21, 1.0, v21
	v_rcp_f32_e32 v21, v21
	v_mul_f32_e32 v20, 0xc1000000, v20
	v_mul_f32_e32 v20, v184, v20
	v_mul_f32_e32 v20, 0x3fb8aa3b, v20
	v_exp_f32_e32 v20, v20
	s_nop 0
	v_sub_f32_e32 v24, 1.0, v20
	v_add_f32_e32 v32, 1.0, v20
	v_mul_f32_e32 v24, v24, v32
	v_max_f32_e32 v24, 0, v24
	v_sqrt_f32_e32 v24, v24
	s_nop 0
	v_mul_f32_e32 v21, v21, v24
	v_mul_f32_e32 v21, v21, v17
	v_add_f32_e32 v17, v45, v41
	v_mul_f32_e32 v17, 0xbfb8aa3b, v17
	v_exp_f32_e32 v17, v17
	v_add_f32_e32 v24, v37, v49
	v_mul_f32_e32 v24, 0xbfb8aa3b, v24
	v_exp_f32_e32 v24, v24
	v_add_f32_e32 v17, 1.0, v17
	v_rcp_f32_e32 v17, v17
	v_add_f32_e32 v24, 1.0, v24
	v_rcp_f32_e32 v32, v24
	v_mul_f32_e32 v17, 0xc1000000, v17
	v_mul_f32_e32 v17, v185, v17
	v_mul_f32_e32 v17, 0x3fb8aa3b, v17
	v_exp_f32_e32 v24, v17
	s_nop 0
	v_sub_f32_e32 v17, 1.0, v24
	v_add_f32_e32 v33, 1.0, v24
	v_mul_f32_e32 v17, v17, v33
	v_max_f32_e32 v17, 0, v17
	v_sqrt_f32_e32 v17, v17
	s_nop 0
	v_mul_f32_e32 v17, v32, v17
	v_mul_f32_e32 v25, v17, v25
	v_add_f32_e32 v17, v46, v42
	v_mul_f32_e32 v17, 0xbfb8aa3b, v17
	v_exp_f32_e32 v17, v17
	ds_write2_b64 v189, v[20:21], v[24:25] offset0:48 offset1:65
	v_add_f32_e32 v20, v38, v50
	v_mul_f32_e32 v20, 0xbfb8aa3b, v20
	v_add_f32_e32 v17, 1.0, v17
	v_rcp_f32_e32 v17, v17
	v_exp_f32_e32 v20, v20
	v_mul_f32_e32 v17, 0xc1000000, v17
	v_mul_f32_e32 v17, v186, v17
	v_add_f32_e32 v20, 1.0, v20
	v_mul_f32_e32 v17, 0x3fb8aa3b, v17
	v_rcp_f32_e32 v21, v20
	v_exp_f32_e32 v20, v17
	s_nop 0
	v_sub_f32_e32 v17, 1.0, v20
	v_add_f32_e32 v24, 1.0, v20
	v_mul_f32_e32 v17, v17, v24
	v_max_f32_e32 v17, 0, v17
	v_sqrt_f32_e32 v17, v17
	v_add_f32_e32 v24, v39, v51
	v_mul_f32_e32 v24, 0xbfb8aa3b, v24
	v_exp_f32_e32 v24, v24
	v_mul_f32_e32 v17, v21, v17
	v_mul_f32_e32 v21, v17, v29
	v_add_f32_e32 v17, v47, v43
	v_mul_f32_e32 v17, 0xbfb8aa3b, v17
	v_exp_f32_e32 v17, v17
	v_add_f32_e32 v24, 1.0, v24
	v_rcp_f32_e32 v25, v24
	v_add_f32_e32 v17, 1.0, v17
	v_rcp_f32_e32 v17, v17
	s_nop 0
	v_mul_f32_e32 v17, 0xc1000000, v17
	v_mul_f32_e32 v17, v187, v17
	v_mul_f32_e32 v17, 0x3fb8aa3b, v17
	v_exp_f32_e32 v24, v17
	s_nop 0
	v_sub_f32_e32 v17, 1.0, v24
	v_add_f32_e32 v29, 1.0, v24
	v_mul_f32_e32 v17, v17, v29
	v_max_f32_e32 v17, 0, v17
	v_sqrt_f32_e32 v17, v17
	s_nop 0
	v_mul_f32_e32 v17, v25, v17
	v_mul_f32_e32 v25, v17, v30
	ds_write2_b64 v189, v[20:21], v[24:25] offset0:82 offset1:99
	s_waitcnt lgkmcnt(0)
	s_barrier
	ds_read2_b64 v[36:39], v188 offset1:1
	ds_read2_b64 v[64:67], v16 offset1:1
	ds_read2_b64 v[40:43], v4 offset1:1
	ds_read2_b64 v[44:47], v5 offset1:1
	ds_read2_b64 v[48:51], v8 offset1:1
	ds_read2_b64 v[52:55], v9 offset1:1
	ds_read2_b64 v[56:59], v12 offset1:1
	ds_read2_b64 v[60:63], v13 offset1:1
	s_waitcnt lgkmcnt(0)
	s_barrier
	ds_read_b128 v[128:131], v166 offset:17408
	ds_read_b128 v[132:135], v166 offset:17472
	v_mov_b32_e32 v144, v240
	v_mov_b32_e32 v145, v241
	v_mov_b32_e32 v146, v242
	v_mov_b32_e32 v147, v243
	v_mov_b32_e32 v148, v244
	v_mov_b32_e32 v149, v245
	v_mov_b32_e32 v150, v246
	v_mov_b32_e32 v151, v247
	s_waitcnt lgkmcnt(1)
	v_mfma_f32_16x16x32_bf16 v[136:139], v[120:123], v[128:131], 0
	ds_read_b64 v[20:21], v2 offset:17408
	v_fma_f32 v29, v35, v36, v37
	v_fmac_f32_e32 v39, v38, v29
	s_waitcnt lgkmcnt(1)
	v_mfma_f32_16x16x32_bf16 v[136:139], v[162:165], v[132:135], v[136:139]
	v_fma_f32 v30, v40, v39, v41
	s_waitcnt lgkmcnt(0)
	v_lshlrev_b32_e32 v17, 16, v20
	v_and_b32_e32 v25, 0xffff0000, v20
	v_mfma_f32_16x16x32_bf16 v[140:143], v[116:119], v[128:131], 0
	v_lshlrev_b32_e32 v40, 16, v21
	v_and_b32_e32 v41, 0xffff0000, v21
	v_fmac_f32_e32 v43, v42, v30
	v_mfma_f32_16x16x32_bf16 v[140:143], v[124:127], v[132:135], v[140:143]
	v_fma_f32 v32, v44, v43, v45
	v_fmac_f32_e32 v47, v46, v32
	v_fma_f32 v33, v48, v47, v49
	v_fmac_f32_e32 v51, v50, v33
	v_fma_f32 v34, v52, v51, v53
	v_fmac_f32_e32 v55, v54, v34
	v_fma_f32 v36, v56, v55, v57
	v_fmac_f32_e32 v59, v58, v36
	v_fma_f32 v37, v60, v59, v61
	v_fmac_f32_e32 v63, v62, v37
	v_fma_f32 v38, v64, v63, v65
	v_fmac_f32_e32 v67, v66, v38
	s_waitcnt vmcnt(1)
	v_add_f32_e32 v20, v136, v144
	v_mul_f32_e32 v20, 0xbfb8aa3b, v20
	v_exp_f32_e32 v20, v20
	s_waitcnt vmcnt(0)
	v_add_f32_e32 v21, v140, v148
	v_mul_f32_e32 v21, 0xbfb8aa3b, v21
	v_exp_f32_e32 v21, v21
	v_add_f32_e32 v20, 1.0, v20
	v_rcp_f32_e32 v20, v20
	v_add_f32_e32 v21, 1.0, v21
	v_rcp_f32_e32 v21, v21
	v_mul_f32_e32 v20, 0xc1000000, v20
	v_mul_f32_e32 v20, v172, v20
	v_mul_f32_e32 v20, 0x3fb8aa3b, v20
	v_exp_f32_e32 v20, v20
	s_nop 0
	v_sub_f32_e32 v24, 1.0, v20
	v_add_f32_e32 v42, 1.0, v20
	v_mul_f32_e32 v24, v24, v42
	v_max_f32_e32 v24, 0, v24
	v_sqrt_f32_e32 v24, v24
	s_nop 0
	v_mul_f32_e32 v21, v21, v24
	v_mul_f32_e32 v21, v21, v17
	v_add_f32_e32 v17, v137, v145
	v_mul_f32_e32 v17, 0xbfb8aa3b, v17
	v_exp_f32_e32 v17, v17
	v_add_f32_e32 v24, v141, v149
	v_mul_f32_e32 v24, 0xbfb8aa3b, v24
	v_exp_f32_e32 v24, v24
	v_add_f32_e32 v17, 1.0, v17
	v_rcp_f32_e32 v17, v17
	v_add_f32_e32 v24, 1.0, v24
	v_rcp_f32_e32 v42, v24
	v_mul_f32_e32 v17, 0xc1000000, v17
	v_mul_f32_e32 v17, v173, v17
	v_mul_f32_e32 v17, 0x3fb8aa3b, v17
	v_exp_f32_e32 v24, v17
	s_nop 0
	v_sub_f32_e32 v17, 1.0, v24
	v_add_f32_e32 v44, 1.0, v24
	v_mul_f32_e32 v17, v17, v44
	v_max_f32_e32 v17, 0, v17
	v_sqrt_f32_e32 v17, v17
	s_nop 0
	v_mul_f32_e32 v17, v42, v17
	v_mul_f32_e32 v25, v17, v25
	v_add_f32_e32 v17, v138, v146
	v_mul_f32_e32 v17, 0xbfb8aa3b, v17
	v_exp_f32_e32 v17, v17
	ds_write2_b64 v190, v[20:21], v[24:25] offset1:17
	v_add_f32_e32 v20, v142, v150
	v_mul_f32_e32 v20, 0xbfb8aa3b, v20
	v_add_f32_e32 v17, 1.0, v17
	v_rcp_f32_e32 v17, v17
	v_exp_f32_e32 v20, v20
	v_mul_f32_e32 v17, 0xc1000000, v17
	v_mul_f32_e32 v17, v174, v17
	v_add_f32_e32 v20, 1.0, v20
	v_mul_f32_e32 v17, 0x3fb8aa3b, v17
	v_rcp_f32_e32 v21, v20
	v_exp_f32_e32 v20, v17
	s_nop 0
	v_sub_f32_e32 v17, 1.0, v20
	v_add_f32_e32 v24, 1.0, v20
	v_mul_f32_e32 v17, v17, v24
	v_max_f32_e32 v17, 0, v17
	v_sqrt_f32_e32 v17, v17
	v_add_f32_e32 v24, v143, v151
	v_mul_f32_e32 v24, 0xbfb8aa3b, v24
	v_exp_f32_e32 v24, v24
	v_mul_f32_e32 v17, v21, v17
	v_mul_f32_e32 v21, v17, v40
	v_add_f32_e32 v17, v139, v147
	v_mul_f32_e32 v17, 0xbfb8aa3b, v17
	v_exp_f32_e32 v17, v17
	v_add_f32_e32 v24, 1.0, v24
	v_rcp_f32_e32 v25, v24
	v_mfma_f32_16x16x32_bf16 v[136:139], v[104:107], v[128:131], 0
	v_add_f32_e32 v17, 1.0, v17
	v_rcp_f32_e32 v17, v17
	v_mfma_f32_16x16x32_bf16 v[140:143], v[112:115], v[132:135], v[136:139]
	v_mul_f32_e32 v17, 0xc1000000, v17
	v_mul_f32_e32 v17, v175, v17
	v_mul_f32_e32 v17, 0x3fb8aa3b, v17
	v_exp_f32_e32 v24, v17
	v_mfma_f32_16x16x32_bf16 v[136:139], v[100:103], v[128:131], 0
	v_sub_f32_e32 v17, 1.0, v24
	v_add_f32_e32 v40, 1.0, v24
	v_mul_f32_e32 v17, v17, v40
	v_max_f32_e32 v17, 0, v17
	v_sqrt_f32_e32 v17, v17
	v_mfma_f32_16x16x32_bf16 v[136:139], v[108:111], v[132:135], v[136:139]
	v_mul_f32_e32 v17, v25, v17
	v_mul_f32_e32 v25, v17, v41
	ds_write2_b64 v190, v[20:21], v[24:25] offset0:34 offset1:51
	v_mov_b32_e32 v144, v248
	v_mov_b32_e32 v145, v249
	v_mov_b32_e32 v146, v250
	v_mov_b32_e32 v147, v251
	v_mov_b32_e32 v148, v224
	v_mov_b32_e32 v149, v225
	v_mov_b32_e32 v150, v226
	v_mov_b32_e32 v151, v227
	ds_read_b64 v[20:21], v2 offset:17440
	s_waitcnt lgkmcnt(0)
	v_lshlrev_b32_e32 v17, 16, v20
	v_and_b32_e32 v25, 0xffff0000, v20
	v_lshlrev_b32_e32 v40, 16, v21
	v_and_b32_e32 v41, 0xffff0000, v21
	s_waitcnt vmcnt(1)
	v_add_f32_e32 v20, v140, v144
	v_mul_f32_e32 v20, 0xbfb8aa3b, v20
	v_exp_f32_e32 v20, v20
	s_waitcnt vmcnt(0)
	v_add_f32_e32 v21, v136, v148
	v_mul_f32_e32 v21, 0xbfb8aa3b, v21
	v_exp_f32_e32 v21, v21
	v_add_f32_e32 v20, 1.0, v20
	v_rcp_f32_e32 v20, v20
	v_add_f32_e32 v21, 1.0, v21
	v_rcp_f32_e32 v21, v21
	v_mul_f32_e32 v20, 0xc1000000, v20
	v_mul_f32_e32 v20, v176, v20
	v_mul_f32_e32 v20, 0x3fb8aa3b, v20
	v_exp_f32_e32 v20, v20
	s_nop 0
	v_sub_f32_e32 v24, 1.0, v20
	v_add_f32_e32 v42, 1.0, v20
	v_mul_f32_e32 v24, v24, v42
	v_max_f32_e32 v24, 0, v24
	v_sqrt_f32_e32 v24, v24
	s_nop 0
	v_mul_f32_e32 v21, v21, v24
	v_mul_f32_e32 v21, v21, v17
	v_add_f32_e32 v17, v141, v145
	v_mul_f32_e32 v17, 0xbfb8aa3b, v17
	v_exp_f32_e32 v17, v17
	v_add_f32_e32 v24, v137, v149
	v_mul_f32_e32 v24, 0xbfb8aa3b, v24
	v_exp_f32_e32 v24, v24
	v_add_f32_e32 v17, 1.0, v17
	v_rcp_f32_e32 v17, v17
	v_add_f32_e32 v24, 1.0, v24
	v_rcp_f32_e32 v42, v24
	v_mul_f32_e32 v17, 0xc1000000, v17
	v_mul_f32_e32 v17, v177, v17
	v_mul_f32_e32 v17, 0x3fb8aa3b, v17
	v_exp_f32_e32 v24, v17
	s_nop 0
	v_sub_f32_e32 v17, 1.0, v24
	v_add_f32_e32 v44, 1.0, v24
	v_mul_f32_e32 v17, v17, v44
	v_max_f32_e32 v17, 0, v17
	v_sqrt_f32_e32 v17, v17
	s_nop 0
	v_mul_f32_e32 v17, v42, v17
	v_mul_f32_e32 v25, v17, v25
	v_add_f32_e32 v17, v142, v146
	v_mul_f32_e32 v17, 0xbfb8aa3b, v17
	v_exp_f32_e32 v17, v17
	ds_write2_b64 v191, v[20:21], v[24:25] offset0:16 offset1:33
	v_add_f32_e32 v20, v138, v150
	v_mul_f32_e32 v20, 0xbfb8aa3b, v20
	v_add_f32_e32 v17, 1.0, v17
	v_rcp_f32_e32 v17, v17
	v_exp_f32_e32 v20, v20
	v_mul_f32_e32 v17, 0xc1000000, v17
	v_mul_f32_e32 v17, v179, v17
	v_add_f32_e32 v20, 1.0, v20
	v_mul_f32_e32 v17, 0x3fb8aa3b, v17
	v_rcp_f32_e32 v21, v20
	v_exp_f32_e32 v20, v17
	s_nop 0
	v_sub_f32_e32 v17, 1.0, v20
	v_add_f32_e32 v24, 1.0, v20
	v_mul_f32_e32 v17, v17, v24
	v_max_f32_e32 v17, 0, v17
	v_sqrt_f32_e32 v17, v17
	v_add_f32_e32 v24, v139, v151
	v_mul_f32_e32 v24, 0xbfb8aa3b, v24
	v_exp_f32_e32 v24, v24
	v_mul_f32_e32 v17, v21, v17
	v_mul_f32_e32 v21, v17, v40
	v_add_f32_e32 v17, v143, v147
	v_mul_f32_e32 v17, 0xbfb8aa3b, v17
	v_exp_f32_e32 v17, v17
	v_add_f32_e32 v24, 1.0, v24
	v_rcp_f32_e32 v25, v24
	v_mfma_f32_16x16x32_bf16 v[136:139], v[88:91], v[128:131], 0
	v_add_f32_e32 v17, 1.0, v17
	v_rcp_f32_e32 v17, v17
	v_mfma_f32_16x16x32_bf16 v[140:143], v[96:99], v[132:135], v[136:139]
	v_mul_f32_e32 v17, 0xc1000000, v17
	v_mul_f32_e32 v17, v181, v17
	v_mul_f32_e32 v17, 0x3fb8aa3b, v17
	v_exp_f32_e32 v24, v17
	v_mfma_f32_16x16x32_bf16 v[136:139], v[84:87], v[128:131], 0
	v_sub_f32_e32 v17, 1.0, v24
	v_add_f32_e32 v40, 1.0, v24
	v_mul_f32_e32 v17, v17, v40
	v_max_f32_e32 v17, 0, v17
	v_sqrt_f32_e32 v17, v17
	v_mfma_f32_16x16x32_bf16 v[136:139], v[92:95], v[132:135], v[136:139]
	v_mul_f32_e32 v17, v25, v17
	v_mul_f32_e32 v25, v17, v41
	ds_write2_b64 v191, v[20:21], v[24:25] offset0:50 offset1:67
	v_mov_b32_e32 v144, v223
	v_mov_b32_e32 v145, v229
	v_mov_b32_e32 v146, v230
	v_mov_b32_e32 v147, v231
	v_mov_b32_e32 v148, v232
	v_mov_b32_e32 v149, v237
	v_mov_b32_e32 v150, v238
	v_mov_b32_e32 v151, v239
	ds_read_b64 v[20:21], v2 offset:17472
	s_waitcnt lgkmcnt(0)
	v_lshlrev_b32_e32 v17, 16, v20
	v_and_b32_e32 v25, 0xffff0000, v20
	v_lshlrev_b32_e32 v40, 16, v21
	v_and_b32_e32 v41, 0xffff0000, v21
	s_waitcnt vmcnt(1)
	v_add_f32_e32 v20, v140, v144
	v_mul_f32_e32 v20, 0xbfb8aa3b, v20
	v_exp_f32_e32 v20, v20
	s_waitcnt vmcnt(0)
	v_add_f32_e32 v21, v136, v148
	v_mul_f32_e32 v21, 0xbfb8aa3b, v21
	v_exp_f32_e32 v21, v21
	v_add_f32_e32 v20, 1.0, v20
	v_rcp_f32_e32 v20, v20
	v_add_f32_e32 v21, 1.0, v21
	v_rcp_f32_e32 v21, v21
	v_mul_f32_e32 v20, 0xc1000000, v20
	v_mul_f32_e32 v20, v178, v20
	v_mul_f32_e32 v20, 0x3fb8aa3b, v20
	v_exp_f32_e32 v20, v20
	s_nop 0
	v_sub_f32_e32 v24, 1.0, v20
	v_add_f32_e32 v42, 1.0, v20
	v_mul_f32_e32 v24, v24, v42
	v_max_f32_e32 v24, 0, v24
	v_sqrt_f32_e32 v24, v24
	s_nop 0
	v_mul_f32_e32 v21, v21, v24
	v_mul_f32_e32 v21, v21, v17
	v_add_f32_e32 v17, v141, v145
	v_mul_f32_e32 v17, 0xbfb8aa3b, v17
	v_exp_f32_e32 v17, v17
	v_add_f32_e32 v24, v137, v149
	v_mul_f32_e32 v24, 0xbfb8aa3b, v24
	v_exp_f32_e32 v24, v24
	v_add_f32_e32 v17, 1.0, v17
	v_rcp_f32_e32 v17, v17
	v_add_f32_e32 v24, 1.0, v24
	v_rcp_f32_e32 v42, v24
	v_mul_f32_e32 v17, 0xc1000000, v17
	v_mul_f32_e32 v17, v180, v17
	v_mul_f32_e32 v17, 0x3fb8aa3b, v17
	v_exp_f32_e32 v24, v17
	s_nop 0
	v_sub_f32_e32 v17, 1.0, v24
	v_add_f32_e32 v44, 1.0, v24
	v_mul_f32_e32 v17, v17, v44
	v_max_f32_e32 v17, 0, v17
	v_sqrt_f32_e32 v17, v17
	s_nop 0
	v_mul_f32_e32 v17, v42, v17
	v_mul_f32_e32 v25, v17, v25
	v_add_f32_e32 v17, v142, v146
	v_mul_f32_e32 v17, 0xbfb8aa3b, v17
	v_exp_f32_e32 v17, v17
	ds_write2_b64 v192, v[20:21], v[24:25] offset0:32 offset1:49
	v_add_f32_e32 v20, v138, v150
	v_mul_f32_e32 v20, 0xbfb8aa3b, v20
	v_add_f32_e32 v17, 1.0, v17
	v_rcp_f32_e32 v17, v17
	v_exp_f32_e32 v20, v20
	v_mul_f32_e32 v17, 0xc1000000, v17
	v_mul_f32_e32 v17, v182, v17
	v_add_f32_e32 v20, 1.0, v20
	v_mul_f32_e32 v17, 0x3fb8aa3b, v17
	v_rcp_f32_e32 v21, v20
	v_exp_f32_e32 v20, v17
	s_nop 0
	v_sub_f32_e32 v17, 1.0, v20
	v_add_f32_e32 v24, 1.0, v20
	v_mul_f32_e32 v17, v17, v24
	v_max_f32_e32 v17, 0, v17
	v_sqrt_f32_e32 v17, v17
	v_add_f32_e32 v24, v139, v151
	v_mul_f32_e32 v24, 0xbfb8aa3b, v24
	v_exp_f32_e32 v24, v24
	v_mul_f32_e32 v17, v21, v17
	v_mul_f32_e32 v21, v17, v40
	v_add_f32_e32 v17, v143, v147
	v_mul_f32_e32 v17, 0xbfb8aa3b, v17
	v_exp_f32_e32 v17, v17
	v_add_f32_e32 v24, 1.0, v24
	v_rcp_f32_e32 v25, v24
	v_mfma_f32_16x16x32_bf16 v[136:139], v[72:75], v[128:131], 0
	v_add_f32_e32 v17, 1.0, v17
	v_rcp_f32_e32 v17, v17
	v_mfma_f32_16x16x32_bf16 v[128:131], v[68:71], v[128:131], 0
	v_mul_f32_e32 v17, 0xc1000000, v17
	v_mul_f32_e32 v17, v183, v17
	v_mul_f32_e32 v17, 0x3fb8aa3b, v17
	v_exp_f32_e32 v24, v17
	v_mfma_f32_16x16x32_bf16 v[136:139], v[80:83], v[132:135], v[136:139]
	v_sub_f32_e32 v17, 1.0, v24
	v_add_f32_e32 v40, 1.0, v24
	v_mul_f32_e32 v17, v17, v40
	v_max_f32_e32 v17, 0, v17
	v_sqrt_f32_e32 v17, v17
	v_mfma_f32_16x16x32_bf16 v[128:131], v[76:79], v[132:135], v[128:131]
	v_mul_f32_e32 v17, v25, v17
	v_mul_f32_e32 v25, v17, v41
	ds_write2_b64 v192, v[20:21], v[24:25] offset0:66 offset1:83
	global_load_dwordx4 v[132:135], v[170:171], off offset:192
	global_load_dwordx4 v[140:143], v[0:1], off offset:192
	ds_read_b64 v[20:21], v2 offset:17504
	s_waitcnt lgkmcnt(0)
	v_lshlrev_b32_e32 v17, 16, v20
	v_and_b32_e32 v25, 0xffff0000, v20
	v_lshlrev_b32_e32 v40, 16, v21
	v_and_b32_e32 v41, 0xffff0000, v21
	s_waitcnt vmcnt(1)
	v_add_f32_e32 v20, v136, v132
	v_mul_f32_e32 v20, 0xbfb8aa3b, v20
	v_exp_f32_e32 v20, v20
	s_waitcnt vmcnt(0)
	v_add_f32_e32 v21, v128, v140
	v_mul_f32_e32 v21, 0xbfb8aa3b, v21
	v_exp_f32_e32 v21, v21
	v_add_f32_e32 v20, 1.0, v20
	v_rcp_f32_e32 v20, v20
	v_add_f32_e32 v21, 1.0, v21
	v_rcp_f32_e32 v21, v21
	v_mul_f32_e32 v20, 0xc1000000, v20
	v_mul_f32_e32 v20, v184, v20
	v_mul_f32_e32 v20, 0x3fb8aa3b, v20
	v_exp_f32_e32 v20, v20
	s_nop 0
	v_sub_f32_e32 v24, 1.0, v20
	v_add_f32_e32 v42, 1.0, v20
	v_mul_f32_e32 v24, v24, v42
	v_max_f32_e32 v24, 0, v24
	v_sqrt_f32_e32 v24, v24
	s_nop 0
	v_mul_f32_e32 v21, v21, v24
	v_mul_f32_e32 v21, v21, v17
	v_add_f32_e32 v17, v137, v133
	v_mul_f32_e32 v17, 0xbfb8aa3b, v17
	v_exp_f32_e32 v17, v17
	v_add_f32_e32 v24, v129, v141
	v_mul_f32_e32 v24, 0xbfb8aa3b, v24
	v_exp_f32_e32 v24, v24
	v_add_f32_e32 v17, 1.0, v17
	v_rcp_f32_e32 v17, v17
	v_add_f32_e32 v24, 1.0, v24
	v_rcp_f32_e32 v42, v24
	v_mul_f32_e32 v17, 0xc1000000, v17
	v_mul_f32_e32 v17, v185, v17
	v_mul_f32_e32 v17, 0x3fb8aa3b, v17
	v_exp_f32_e32 v24, v17
	s_nop 0
	v_sub_f32_e32 v17, 1.0, v24
	v_add_f32_e32 v44, 1.0, v24
	v_mul_f32_e32 v17, v17, v44
	v_max_f32_e32 v17, 0, v17
	v_sqrt_f32_e32 v17, v17
	s_nop 0
	v_mul_f32_e32 v17, v42, v17
	v_mul_f32_e32 v25, v17, v25
	v_add_f32_e32 v17, v138, v134
	v_mul_f32_e32 v17, 0xbfb8aa3b, v17
	v_exp_f32_e32 v17, v17
	ds_write2_b64 v189, v[20:21], v[24:25] offset0:48 offset1:65
	v_add_f32_e32 v20, v130, v142
	v_mul_f32_e32 v20, 0xbfb8aa3b, v20
	v_add_f32_e32 v17, 1.0, v17
	v_rcp_f32_e32 v17, v17
	v_exp_f32_e32 v20, v20
	v_mul_f32_e32 v17, 0xc1000000, v17
	v_mul_f32_e32 v17, v186, v17
	v_add_f32_e32 v20, 1.0, v20
	v_mul_f32_e32 v17, 0x3fb8aa3b, v17
	v_rcp_f32_e32 v21, v20
	v_exp_f32_e32 v20, v17
	s_nop 0
	v_sub_f32_e32 v17, 1.0, v20
	v_add_f32_e32 v24, 1.0, v20
	v_mul_f32_e32 v17, v17, v24
	v_max_f32_e32 v17, 0, v17
	v_sqrt_f32_e32 v17, v17
	v_add_f32_e32 v24, v131, v143
	v_mul_f32_e32 v24, 0xbfb8aa3b, v24
	v_exp_f32_e32 v24, v24
	v_mul_f32_e32 v17, v21, v17
	v_mul_f32_e32 v21, v17, v40
	v_add_f32_e32 v17, v139, v135
	v_mul_f32_e32 v17, 0xbfb8aa3b, v17
	v_exp_f32_e32 v17, v17
	v_add_f32_e32 v24, 1.0, v24
	v_rcp_f32_e32 v25, v24
	v_add_f32_e32 v17, 1.0, v17
	v_rcp_f32_e32 v17, v17
	s_nop 0
	v_mul_f32_e32 v17, 0xc1000000, v17
	v_mul_f32_e32 v17, v187, v17
	v_mul_f32_e32 v17, 0x3fb8aa3b, v17
	v_exp_f32_e32 v24, v17
	s_nop 0
	v_sub_f32_e32 v17, 1.0, v24
	v_add_f32_e32 v40, 1.0, v24
	v_mul_f32_e32 v17, v17, v40
	v_max_f32_e32 v17, 0, v17
	v_sqrt_f32_e32 v17, v17
	s_nop 0
	v_mul_f32_e32 v17, v25, v17
	v_mul_f32_e32 v25, v17, v41
	ds_write2_b64 v189, v[20:21], v[24:25] offset0:82 offset1:99
	s_waitcnt lgkmcnt(0)
	s_barrier
	ds_read2_b64 v[130:133], v188 offset1:1
	ds_read2_b64 v[158:161], v16 offset1:1
	ds_read2_b64 v[134:137], v4 offset1:1
	ds_read2_b64 v[138:141], v5 offset1:1
	ds_read2_b64 v[142:145], v8 offset1:1
	ds_read2_b64 v[146:149], v9 offset1:1
	s_waitcnt lgkmcnt(5)
	v_fma_f32 v40, v67, v130, v131
	ds_read2_b64 v[150:153], v12 offset1:1
	ds_read2_b64 v[154:157], v13 offset1:1
	s_waitcnt lgkmcnt(0)
	s_barrier
	ds_read_b128 v[128:131], v166 offset:26112
	ds_read_b128 v[166:169], v166 offset:26176
	s_waitcnt lgkmcnt(1)
	v_mfma_f32_16x16x32_bf16 v[120:123], v[120:123], v[128:131], 0
	v_fmac_f32_e32 v133, v132, v40
	v_fma_f32 v41, v134, v133, v135
	v_fmac_f32_e32 v137, v136, v41
	v_mfma_f32_16x16x32_bf16 v[116:119], v[116:119], v[128:131], 0
	v_fma_f32 v42, v138, v137, v139
	v_fmac_f32_e32 v141, v140, v42
	v_fma_f32 v44, v142, v141, v143
	s_waitcnt lgkmcnt(0)
	v_mfma_f32_16x16x32_bf16 v[120:123], v[162:165], v[166:169], v[120:123]
	v_fmac_f32_e32 v145, v144, v44
	v_fma_f32 v45, v146, v145, v147
	v_fmac_f32_e32 v149, v148, v45
	v_mfma_f32_16x16x32_bf16 v[116:119], v[124:127], v[166:169], v[116:119]
	v_mov_b32_e32 v124, v240
	v_mov_b32_e32 v125, v241
	v_mov_b32_e32 v126, v242
	v_mov_b32_e32 v127, v243
	v_mov_b32_e32 v162, v244
	v_mov_b32_e32 v163, v245
	v_mov_b32_e32 v164, v246
	v_mov_b32_e32 v165, v247
	ds_read_b64 v[20:21], v2 offset:26112
	v_fma_f32 v46, v150, v149, v151
	v_mfma_f32_16x16x32_bf16 v[104:107], v[104:107], v[128:131], 0
	v_fmac_f32_e32 v153, v152, v46
	v_fma_f32 v53, v154, v153, v155
	s_waitcnt lgkmcnt(0)
	v_lshlrev_b32_e32 v17, 16, v20
	v_and_b32_e32 v25, 0xffff0000, v20
	v_lshlrev_b32_e32 v48, 16, v21
	v_and_b32_e32 v49, 0xffff0000, v21
	v_mfma_f32_16x16x32_bf16 v[100:103], v[100:103], v[128:131], 0
	v_fmac_f32_e32 v157, v156, v53
	v_fma_f32 v54, v158, v157, v159
	v_fmac_f32_e32 v161, v160, v54
	v_mfma_f32_16x16x32_bf16 v[104:107], v[112:115], v[166:169], v[104:107]
	s_waitcnt vmcnt(1)
	v_add_f32_e32 v20, v120, v124
	v_mul_f32_e32 v20, 0xbfb8aa3b, v20
	v_exp_f32_e32 v20, v20
	s_waitcnt vmcnt(0)
	v_add_f32_e32 v21, v116, v162
	v_mul_f32_e32 v21, 0xbfb8aa3b, v21
	v_exp_f32_e32 v21, v21
	v_add_f32_e32 v20, 1.0, v20
	v_rcp_f32_e32 v20, v20
	v_mfma_f32_16x16x32_bf16 v[100:103], v[108:111], v[166:169], v[100:103]
	v_add_f32_e32 v21, 1.0, v21
	v_rcp_f32_e32 v21, v21
	v_mul_f32_e32 v20, 0xc1000000, v20
	v_mul_f32_e32 v20, v172, v20
	v_mul_f32_e32 v20, 0x3fb8aa3b, v20
	v_exp_f32_e32 v20, v20
	v_mfma_f32_16x16x32_bf16 v[88:91], v[88:91], v[128:131], 0
	v_sub_f32_e32 v24, 1.0, v20
	v_add_f32_e32 v50, 1.0, v20
	v_mul_f32_e32 v24, v24, v50
	v_max_f32_e32 v24, 0, v24
	v_sqrt_f32_e32 v24, v24
	v_mfma_f32_16x16x32_bf16 v[84:87], v[84:87], v[128:131], 0
	v_mul_f32_e32 v21, v21, v24
	v_mul_f32_e32 v21, v21, v17
	v_add_f32_e32 v17, v121, v125
	v_mul_f32_e32 v17, 0xbfb8aa3b, v17
	v_exp_f32_e32 v17, v17
	v_add_f32_e32 v24, v117, v163
	v_mul_f32_e32 v24, 0xbfb8aa3b, v24
	v_exp_f32_e32 v24, v24
	v_add_f32_e32 v17, 1.0, v17
	v_rcp_f32_e32 v17, v17
	v_mfma_f32_16x16x32_bf16 v[88:91], v[96:99], v[166:169], v[88:91]
	v_add_f32_e32 v24, 1.0, v24
	v_rcp_f32_e32 v50, v24
	v_mul_f32_e32 v17, 0xc1000000, v17
	v_mul_f32_e32 v17, v173, v17
	v_mul_f32_e32 v17, 0x3fb8aa3b, v17
	v_exp_f32_e32 v24, v17
	v_mfma_f32_16x16x32_bf16 v[84:87], v[92:95], v[166:169], v[84:87]
	v_sub_f32_e32 v17, 1.0, v24
	v_add_f32_e32 v52, 1.0, v24
	v_mul_f32_e32 v17, v17, v52
	v_max_f32_e32 v17, 0, v17
	v_sqrt_f32_e32 v17, v17
	v_mfma_f32_16x16x32_bf16 v[72:75], v[72:75], v[128:131], 0
	v_mul_f32_e32 v17, v50, v17
	v_mul_f32_e32 v25, v17, v25
	v_add_f32_e32 v17, v122, v126
	v_mul_f32_e32 v17, 0xbfb8aa3b, v17
	v_exp_f32_e32 v17, v17
	ds_write2_b64 v190, v[20:21], v[24:25] offset1:17
	v_add_f32_e32 v20, v118, v164
	v_mul_f32_e32 v20, 0xbfb8aa3b, v20
	v_add_f32_e32 v17, 1.0, v17
	v_rcp_f32_e32 v17, v17
	v_exp_f32_e32 v20, v20
	v_mfma_f32_16x16x32_bf16 v[68:71], v[68:71], v[128:131], 0
	v_mul_f32_e32 v17, 0xc1000000, v17
	v_mul_f32_e32 v17, v174, v17
	v_add_f32_e32 v20, 1.0, v20
	v_mul_f32_e32 v17, 0x3fb8aa3b, v17
	v_rcp_f32_e32 v21, v20
	v_exp_f32_e32 v20, v17
	v_mfma_f32_16x16x32_bf16 v[72:75], v[80:83], v[166:169], v[72:75]
	v_sub_f32_e32 v17, 1.0, v20
	v_add_f32_e32 v24, 1.0, v20
	v_mul_f32_e32 v17, v17, v24
	v_max_f32_e32 v17, 0, v17
	v_sqrt_f32_e32 v17, v17
	v_add_f32_e32 v24, v119, v165
	v_mul_f32_e32 v24, 0xbfb8aa3b, v24
	v_exp_f32_e32 v24, v24
	v_mul_f32_e32 v17, v21, v17
	v_mul_f32_e32 v21, v17, v48
	v_add_f32_e32 v17, v123, v127
	v_mul_f32_e32 v17, 0xbfb8aa3b, v17
	v_exp_f32_e32 v17, v17
	v_add_f32_e32 v24, 1.0, v24
	v_rcp_f32_e32 v25, v24
	v_mfma_f32_16x16x32_bf16 v[68:71], v[76:79], v[166:169], v[68:71]
	v_add_f32_e32 v17, 1.0, v17
	v_rcp_f32_e32 v17, v17
	s_nop 0
	v_mul_f32_e32 v17, 0xc1000000, v17
	v_mul_f32_e32 v17, v175, v17
	v_mul_f32_e32 v17, 0x3fb8aa3b, v17
	v_exp_f32_e32 v24, v17
	s_nop 0
	v_sub_f32_e32 v17, 1.0, v24
	v_add_f32_e32 v48, 1.0, v24
	v_mul_f32_e32 v17, v17, v48
	v_max_f32_e32 v17, 0, v17
	v_sqrt_f32_e32 v17, v17
	s_nop 0
	v_mul_f32_e32 v17, v25, v17
	v_mul_f32_e32 v25, v17, v49
	ds_write2_b64 v190, v[20:21], v[24:25] offset0:34 offset1:51
	v_mov_b32_e32 v108, v248
	v_mov_b32_e32 v109, v249
	v_mov_b32_e32 v110, v250
	v_mov_b32_e32 v111, v251
	v_mov_b32_e32 v112, v224
	v_mov_b32_e32 v113, v225
	v_mov_b32_e32 v114, v226
	v_mov_b32_e32 v115, v227
	ds_read_b64 v[20:21], v2 offset:26144
	s_waitcnt lgkmcnt(0)
	v_lshlrev_b32_e32 v17, 16, v20
	v_and_b32_e32 v25, 0xffff0000, v20
	v_lshlrev_b32_e32 v48, 16, v21
	v_and_b32_e32 v49, 0xffff0000, v21
	s_waitcnt vmcnt(1)
	v_add_f32_e32 v20, v104, v108
	v_mul_f32_e32 v20, 0xbfb8aa3b, v20
	v_exp_f32_e32 v20, v20
	s_waitcnt vmcnt(0)
	v_add_f32_e32 v21, v100, v112
	v_mul_f32_e32 v21, 0xbfb8aa3b, v21
	v_exp_f32_e32 v21, v21
	v_add_f32_e32 v20, 1.0, v20
	v_rcp_f32_e32 v20, v20
	v_add_f32_e32 v21, 1.0, v21
	v_rcp_f32_e32 v21, v21
	v_mul_f32_e32 v20, 0xc1000000, v20
	v_mul_f32_e32 v20, v176, v20
	v_mul_f32_e32 v20, 0x3fb8aa3b, v20
	v_exp_f32_e32 v20, v20
	s_nop 0
	v_sub_f32_e32 v24, 1.0, v20
	v_add_f32_e32 v50, 1.0, v20
	v_mul_f32_e32 v24, v24, v50
	v_max_f32_e32 v24, 0, v24
	v_sqrt_f32_e32 v24, v24
	s_nop 0
	v_mul_f32_e32 v21, v21, v24
	v_mul_f32_e32 v21, v21, v17
	v_add_f32_e32 v17, v105, v109
	v_mul_f32_e32 v17, 0xbfb8aa3b, v17
	v_exp_f32_e32 v17, v17
	v_add_f32_e32 v24, v101, v113
	v_mul_f32_e32 v24, 0xbfb8aa3b, v24
	v_exp_f32_e32 v24, v24
	v_add_f32_e32 v17, 1.0, v17
	v_rcp_f32_e32 v17, v17
	v_add_f32_e32 v24, 1.0, v24
	v_rcp_f32_e32 v50, v24
	v_mul_f32_e32 v17, 0xc1000000, v17
	v_mul_f32_e32 v17, v177, v17
	v_mul_f32_e32 v17, 0x3fb8aa3b, v17
	v_exp_f32_e32 v24, v17
	s_nop 0
	v_sub_f32_e32 v17, 1.0, v24
	v_add_f32_e32 v52, 1.0, v24
	v_mul_f32_e32 v17, v17, v52
	v_max_f32_e32 v17, 0, v17
	v_sqrt_f32_e32 v17, v17
	s_nop 0
	v_mul_f32_e32 v17, v50, v17
	v_mul_f32_e32 v25, v17, v25
	v_add_f32_e32 v17, v106, v110
	v_mul_f32_e32 v17, 0xbfb8aa3b, v17
	v_exp_f32_e32 v17, v17
	ds_write2_b64 v191, v[20:21], v[24:25] offset0:16 offset1:33
	v_add_f32_e32 v20, v102, v114
	v_mul_f32_e32 v20, 0xbfb8aa3b, v20
	v_add_f32_e32 v17, 1.0, v17
	v_rcp_f32_e32 v17, v17
	v_exp_f32_e32 v20, v20
	v_mul_f32_e32 v17, 0xc1000000, v17
	v_mul_f32_e32 v17, v179, v17
	v_add_f32_e32 v20, 1.0, v20
	v_mul_f32_e32 v17, 0x3fb8aa3b, v17
	v_rcp_f32_e32 v21, v20
	v_exp_f32_e32 v20, v17
	s_nop 0
	v_sub_f32_e32 v17, 1.0, v20
	v_add_f32_e32 v24, 1.0, v20
	v_mul_f32_e32 v17, v17, v24
	v_max_f32_e32 v17, 0, v17
	v_sqrt_f32_e32 v17, v17
	v_add_f32_e32 v24, v103, v115
	v_mul_f32_e32 v24, 0xbfb8aa3b, v24
	v_exp_f32_e32 v24, v24
	v_mul_f32_e32 v17, v21, v17
	v_mul_f32_e32 v21, v17, v48
	v_add_f32_e32 v17, v107, v111
	v_mul_f32_e32 v17, 0xbfb8aa3b, v17
	v_exp_f32_e32 v17, v17
	v_add_f32_e32 v24, 1.0, v24
	v_rcp_f32_e32 v25, v24
	v_add_f32_e32 v17, 1.0, v17
	v_rcp_f32_e32 v17, v17
	s_nop 0
	v_mul_f32_e32 v17, 0xc1000000, v17
	v_mul_f32_e32 v17, v181, v17
	v_mul_f32_e32 v17, 0x3fb8aa3b, v17
	v_exp_f32_e32 v24, v17
	s_nop 0
	v_sub_f32_e32 v17, 1.0, v24
	v_add_f32_e32 v48, 1.0, v24
	v_mul_f32_e32 v17, v17, v48
	v_max_f32_e32 v17, 0, v17
	v_sqrt_f32_e32 v17, v17
	s_nop 0
	v_mul_f32_e32 v17, v25, v17
	v_mul_f32_e32 v25, v17, v49
	ds_write2_b64 v191, v[20:21], v[24:25] offset0:50 offset1:67
	v_mov_b32_e32 v92, v223
	v_mov_b32_e32 v93, v229
	v_mov_b32_e32 v94, v230
	v_mov_b32_e32 v95, v231
	v_mov_b32_e32 v96, v232
	v_mov_b32_e32 v97, v237
	v_mov_b32_e32 v98, v238
	v_mov_b32_e32 v99, v239
	ds_read_b64 v[20:21], v2 offset:26176
	s_waitcnt lgkmcnt(0)
	v_lshlrev_b32_e32 v17, 16, v20
	v_and_b32_e32 v25, 0xffff0000, v20
	v_lshlrev_b32_e32 v48, 16, v21
	v_and_b32_e32 v49, 0xffff0000, v21
	s_waitcnt vmcnt(1)
	v_add_f32_e32 v20, v88, v92
	v_mul_f32_e32 v20, 0xbfb8aa3b, v20
	v_exp_f32_e32 v20, v20
	s_waitcnt vmcnt(0)
	v_add_f32_e32 v21, v84, v96
	v_mul_f32_e32 v21, 0xbfb8aa3b, v21
	v_exp_f32_e32 v21, v21
	v_add_f32_e32 v20, 1.0, v20
	v_rcp_f32_e32 v20, v20
	v_add_f32_e32 v21, 1.0, v21
	v_rcp_f32_e32 v21, v21
	v_mul_f32_e32 v20, 0xc1000000, v20
	v_mul_f32_e32 v20, v178, v20
	v_mul_f32_e32 v20, 0x3fb8aa3b, v20
	v_exp_f32_e32 v20, v20
	s_nop 0
	v_sub_f32_e32 v24, 1.0, v20
	v_add_f32_e32 v50, 1.0, v20
	v_mul_f32_e32 v24, v24, v50
	v_max_f32_e32 v24, 0, v24
	v_sqrt_f32_e32 v24, v24
	s_nop 0
	v_mul_f32_e32 v21, v21, v24
	v_mul_f32_e32 v21, v21, v17
	v_add_f32_e32 v17, v89, v93
	v_mul_f32_e32 v17, 0xbfb8aa3b, v17
	v_exp_f32_e32 v17, v17
	v_add_f32_e32 v24, v85, v97
	v_mul_f32_e32 v24, 0xbfb8aa3b, v24
	v_exp_f32_e32 v24, v24
	v_add_f32_e32 v17, 1.0, v17
	v_rcp_f32_e32 v17, v17
	v_add_f32_e32 v24, 1.0, v24
	v_rcp_f32_e32 v50, v24
	v_mul_f32_e32 v17, 0xc1000000, v17
	v_mul_f32_e32 v17, v180, v17
	v_mul_f32_e32 v17, 0x3fb8aa3b, v17
	v_exp_f32_e32 v24, v17
	s_nop 0
	v_sub_f32_e32 v17, 1.0, v24
	v_add_f32_e32 v52, 1.0, v24
	v_mul_f32_e32 v17, v17, v52
	v_max_f32_e32 v17, 0, v17
	v_sqrt_f32_e32 v17, v17
	s_nop 0
	v_mul_f32_e32 v17, v50, v17
	v_mul_f32_e32 v25, v17, v25
	v_add_f32_e32 v17, v90, v94
	v_mul_f32_e32 v17, 0xbfb8aa3b, v17
	v_exp_f32_e32 v17, v17
	ds_write2_b64 v192, v[20:21], v[24:25] offset0:32 offset1:49
	v_add_f32_e32 v20, v86, v98
	v_mul_f32_e32 v20, 0xbfb8aa3b, v20
	v_add_f32_e32 v17, 1.0, v17
	v_rcp_f32_e32 v17, v17
	v_exp_f32_e32 v20, v20
	v_mul_f32_e32 v17, 0xc1000000, v17
	v_mul_f32_e32 v17, v182, v17
	v_add_f32_e32 v20, 1.0, v20
	v_mul_f32_e32 v17, 0x3fb8aa3b, v17
	v_rcp_f32_e32 v21, v20
	v_exp_f32_e32 v20, v17
	s_nop 0
	v_sub_f32_e32 v17, 1.0, v20
	v_add_f32_e32 v24, 1.0, v20
	v_mul_f32_e32 v17, v17, v24
	v_max_f32_e32 v17, 0, v17
	v_sqrt_f32_e32 v17, v17
	v_add_f32_e32 v24, v87, v99
	v_mul_f32_e32 v24, 0xbfb8aa3b, v24
	v_exp_f32_e32 v24, v24
	v_mul_f32_e32 v17, v21, v17
	v_mul_f32_e32 v21, v17, v48
	v_add_f32_e32 v17, v91, v95
	v_mul_f32_e32 v17, 0xbfb8aa3b, v17
	v_exp_f32_e32 v17, v17
	v_add_f32_e32 v24, 1.0, v24
	v_rcp_f32_e32 v25, v24
	v_add_f32_e32 v17, 1.0, v17
	v_rcp_f32_e32 v17, v17
	s_nop 0
	v_mul_f32_e32 v17, 0xc1000000, v17
	v_mul_f32_e32 v17, v183, v17
	v_mul_f32_e32 v17, 0x3fb8aa3b, v17
	v_exp_f32_e32 v24, v17
	s_nop 0
	v_sub_f32_e32 v17, 1.0, v24
	v_add_f32_e32 v48, 1.0, v24
	v_mul_f32_e32 v17, v17, v48
	v_max_f32_e32 v17, 0, v17
	v_sqrt_f32_e32 v17, v17
	s_nop 0
	v_mul_f32_e32 v17, v25, v17
	v_mul_f32_e32 v25, v17, v49
	ds_write2_b64 v192, v[20:21], v[24:25] offset0:66 offset1:83
	global_load_dwordx4 v[76:79], v[170:171], off offset:192
	global_load_dwordx4 v[80:83], v[0:1], off offset:192
	ds_read_b64 v[0:1], v2 offset:26208
	s_waitcnt lgkmcnt(0)
	v_lshlrev_b32_e32 v2, 16, v0
	v_and_b32_e32 v17, 0xffff0000, v0
	v_lshlrev_b32_e32 v24, 16, v1
	v_and_b32_e32 v25, 0xffff0000, v1
	s_waitcnt vmcnt(1)
	v_add_f32_e32 v0, v72, v76
	v_mul_f32_e32 v0, 0xbfb8aa3b, v0
	v_exp_f32_e32 v0, v0
	s_waitcnt vmcnt(0)
	v_add_f32_e32 v1, v68, v80
	v_mul_f32_e32 v1, 0xbfb8aa3b, v1
	v_exp_f32_e32 v1, v1
	v_add_f32_e32 v0, 1.0, v0
	v_rcp_f32_e32 v0, v0
	v_add_f32_e32 v1, 1.0, v1
	v_rcp_f32_e32 v1, v1
	v_mul_f32_e32 v0, 0xc1000000, v0
	v_mul_f32_e32 v0, v184, v0
	v_mul_f32_e32 v0, 0x3fb8aa3b, v0
	v_exp_f32_e32 v0, v0
	s_nop 0
	v_sub_f32_e32 v20, 1.0, v0
	v_add_f32_e32 v21, 1.0, v0
	v_mul_f32_e32 v20, v20, v21
	v_max_f32_e32 v20, 0, v20
	v_sqrt_f32_e32 v20, v20
	s_nop 0
	v_mul_f32_e32 v1, v1, v20
	v_mul_f32_e32 v1, v1, v2
	v_add_f32_e32 v2, v73, v77
	v_mul_f32_e32 v2, 0xbfb8aa3b, v2
	v_exp_f32_e32 v2, v2
	v_add_f32_e32 v20, v69, v81
	v_mul_f32_e32 v20, 0xbfb8aa3b, v20
	v_exp_f32_e32 v20, v20
	v_add_f32_e32 v2, 1.0, v2
	v_rcp_f32_e32 v2, v2
	v_add_f32_e32 v20, 1.0, v20
	v_rcp_f32_e32 v21, v20
	v_mul_f32_e32 v2, 0xc1000000, v2
	v_mul_f32_e32 v2, v185, v2
	v_mul_f32_e32 v2, 0x3fb8aa3b, v2
	v_exp_f32_e32 v20, v2
	s_nop 0
	v_sub_f32_e32 v2, 1.0, v20
	v_add_f32_e32 v48, 1.0, v20
	v_mul_f32_e32 v2, v2, v48
	v_max_f32_e32 v2, 0, v2
	v_sqrt_f32_e32 v2, v2
	s_nop 0
	v_mul_f32_e32 v2, v21, v2
	v_mul_f32_e32 v21, v2, v17
	ds_write2_b64 v189, v[0:1], v[20:21] offset0:48 offset1:65
	v_add_f32_e32 v0, v74, v78
	v_mul_f32_e32 v0, 0xbfb8aa3b, v0
	v_exp_f32_e32 v0, v0
	v_add_f32_e32 v1, v70, v82
	v_mul_f32_e32 v1, 0xbfb8aa3b, v1
	v_exp_f32_e32 v1, v1
	v_add_f32_e32 v0, 1.0, v0
	v_rcp_f32_e32 v0, v0
	v_add_f32_e32 v1, 1.0, v1
	v_rcp_f32_e32 v1, v1
	v_mul_f32_e32 v0, 0xc1000000, v0
	v_mul_f32_e32 v0, v186, v0
	v_mul_f32_e32 v0, 0x3fb8aa3b, v0
	v_exp_f32_e32 v0, v0
	s_nop 0
	v_sub_f32_e32 v2, 1.0, v0
	v_add_f32_e32 v17, 1.0, v0
	v_mul_f32_e32 v2, v2, v17
	v_max_f32_e32 v2, 0, v2
	v_sqrt_f32_e32 v2, v2
	v_add_f32_e32 v17, v71, v83
	v_mul_f32_e32 v17, 0xbfb8aa3b, v17
	v_exp_f32_e32 v17, v17
	v_mul_f32_e32 v1, v1, v2
	v_add_f32_e32 v2, v75, v79
	v_mul_f32_e32 v2, 0xbfb8aa3b, v2
	v_exp_f32_e32 v2, v2
	v_add_f32_e32 v17, 1.0, v17
	v_rcp_f32_e32 v17, v17
	v_mul_f32_e32 v1, v1, v24
	v_add_f32_e32 v2, 1.0, v2
	v_rcp_f32_e32 v2, v2
	s_nop 0
	v_mul_f32_e32 v2, 0xc1000000, v2
	v_mul_f32_e32 v2, v187, v2
	v_mul_f32_e32 v2, 0x3fb8aa3b, v2
	v_exp_f32_e32 v20, v2
	s_nop 0
	v_sub_f32_e32 v2, 1.0, v20
	v_add_f32_e32 v21, 1.0, v20
	v_mul_f32_e32 v2, v2, v21
	v_max_f32_e32 v2, 0, v2
	v_sqrt_f32_e32 v2, v2
	s_nop 0
	v_mul_f32_e32 v2, v17, v2
	v_mul_f32_e32 v21, v2, v25
	ds_write2_b64 v189, v[0:1], v[20:21] offset0:82 offset1:99
	s_waitcnt lgkmcnt(0)
	s_barrier
	ds_read2_b64 v[182:185], v12 offset1:1
	ds_read2_b64 v[190:193], v16 offset1:1
	v_mov_b32_e32 v12, v222
	ds_read2_b64 v[162:165], v188 offset1:1
	ds_read2_b64 v[166:169], v4 offset1:1
	ds_read2_b64 v[170:173], v5 offset1:1
	ds_read2_b64 v[174:177], v8 offset1:1
	ds_read2_b64 v[178:181], v9 offset1:1
	ds_read2_b64 v[186:189], v13 offset1:1
	s_waitcnt lgkmcnt(0)
	s_barrier
	v_mov_b32_e32 v9, v3
	v_ashrrev_i32_e32 v2, 6, v12
	v_add_u32_e32 v0, s0, v2
	v_readlane_b32 s0, v252, 55
	v_ashrrev_i32_e32 v1, 31, v0
	v_bfe_u32 v13, v12, 4, 2
	v_add_u32_e32 v4, s0, v2
	v_lshlrev_b64 v[0:1], 13, v[0:1]
	v_ashrrev_i32_e32 v5, 31, v4
	v_and_b32_e32 v20, 15, v12
	v_lshl_add_u64 v[0:1], s[84:85], 0, v[0:1]
	v_lshlrev_b64 v[4:5], 13, v[4:5]
	v_lshlrev_b32_e32 v2, 4, v13
	v_lshl_add_u64 v[4:5], s[84:85], 0, v[4:5]
	v_lshl_add_u64 v[0:1], v[0:1], 0, v[2:3]
	v_lshlrev_b32_e32 v8, 7, v20
	v_lshl_add_u64 v[4:5], v[4:5], 0, v[2:3]
	v_lshl_add_u64 v[16:17], v[0:1], 0, v[8:9]
	v_lshl_add_u64 v[48:49], v[4:5], 0, v[8:9]
	global_load_dwordx4 v[120:123], v[16:17], off
	global_load_dwordx4 v[116:119], v[48:49], off
	global_load_dwordx4 v[128:131], v[16:17], off offset:64
	global_load_dwordx4 v[124:127], v[48:49], off offset:64
	global_load_dwordx4 v[104:107], v[16:17], off offset:2048
	global_load_dwordx4 v[100:103], v[48:49], off offset:2048
	global_load_dwordx4 v[112:115], v[16:17], off offset:2112
	global_load_dwordx4 v[108:111], v[48:49], off offset:2112
	v_or_b32_e32 v16, 0x1000, v8
	v_mov_b32_e32 v17, v3
	v_or_b32_e32 v8, 0x1800, v8
	v_lshl_add_u64 v[48:49], v[0:1], 0, v[16:17]
	v_lshl_add_u64 v[16:17], v[4:5], 0, v[16:17]
	v_lshl_add_u64 v[0:1], v[0:1], 0, v[8:9]
	v_lshl_add_u64 v[4:5], v[4:5], 0, v[8:9]
	v_and_b32_e32 v8, 0xffffffc0, v12
	v_ashrrev_i32_e32 v9, 31, v8
	v_readlane_b32 s0, v252, 56
	global_load_dwordx4 v[88:91], v[48:49], off
	global_load_dwordx4 v[84:87], v[16:17], off
	global_load_dwordx4 v[96:99], v[48:49], off offset:64
	global_load_dwordx4 v[92:95], v[16:17], off offset:64
	global_load_dwordx4 v[72:75], v[0:1], off
	global_load_dwordx4 v[68:71], v[4:5], off
	global_load_dwordx4 v[80:83], v[0:1], off offset:64
	global_load_dwordx4 v[76:79], v[4:5], off offset:64
	v_lshlrev_b64 v[0:1], 2, v[8:9]
	v_readlane_b32 s1, v252, 57
	v_fma_f32 v24, v161, v162, v163
	v_fmac_f32_e32 v165, v164, v24
	v_lshl_add_u64 v[16:17], s[0:1], 0, v[0:1]
	v_readlane_b32 s0, v252, 58
	v_readlane_b32 s1, v252, 59
	v_fma_f32 v25, v166, v165, v167
	v_fmac_f32_e32 v169, v168, v25
	v_lshl_add_u64 v[4:5], s[0:1], 0, v[0:1]
	v_lshl_add_u64 v[4:5], v[4:5], 0, v[2:3]
	v_fma_f32 v58, v170, v169, v171
	v_fmac_f32_e32 v173, v172, v58
	v_fma_f32 v60, v174, v173, v175
	v_fmac_f32_e32 v177, v176, v60
	v_fma_f32 v61, v178, v177, v179
	v_fmac_f32_e32 v181, v180, v61
	v_fma_f32 v134, v182, v181, v183
	v_fmac_f32_e32 v185, v184, v134
	v_fma_f32 v135, v186, v185, v187
	v_readlane_b32 s0, v252, 60
	v_readlane_b32 s1, v252, 61
	v_lshlrev_b32_e32 v21, 3, v13
	v_fmac_f32_e32 v189, v188, v135
	v_lshl_add_u64 v[0:1], s[0:1], 0, v[0:1]
	v_fma_f32 v136, v190, v189, v191
	v_fmac_f32_e32 v193, v192, v136
	s_ashr_i32 s1, s8, 31
	s_add_u32 s0, s4, s8
	s_addc_u32 s1, s5, s1
	v_readlane_b32 s4, v252, 17
	v_readlane_b32 s5, v252, 18
	s_waitcnt vmcnt(0)
	s_lshl_b32 s98, s16, 11
	s_add_u32 s98, s98, 0x8400
	s_add_u32 s98, s30, s98
	s_addc_u32 s99, s31, 0
	v_lshrrev_b32_e32 v66, 4, v222
	v_and_b32_e32 v65, 3, v66
	v_lshrrev_b32_e32 v66, 2, v66
	v_lshlrev_b32_e32 v65, 4, v65
	v_lshl_or_b32 v66, v66, 8, v65
	global_load_dword v48, v66, s[98:99]
	global_load_dword v49, v66, s[98:99] offset:4
	global_load_dword v50, v66, s[98:99] offset:8
	global_load_dword v52, v66, s[98:99] offset:12
	global_load_dword v182, v66, s[98:99] offset:64
	global_load_dword v184, v66, s[98:99] offset:68
	global_load_dword v186, v66, s[98:99] offset:72
	global_load_dword v187, v66, s[98:99] offset:76
	global_load_dword v132, v66, s[98:99] offset:128
	global_load_dword v160, v66, s[98:99] offset:132
	global_load_dword v180, v66, s[98:99] offset:136
	global_load_dword v183, v66, s[98:99] offset:140
	global_load_dword v62, v66, s[98:99] offset:192
	global_load_dword v64, v66, s[98:99] offset:196
	global_load_dword v65, v66, s[98:99] offset:200
	global_load_dword v66, v66, s[98:99] offset:204
	v_lshlrev_b32_e32 v140, 3, v20
	v_lshl_or_b32 v139, v13, 2, v8
	v_ashrrev_i32_e32 v13, 31, v12
	v_lshl_add_u32 v56, v8, 1, 32
	v_lshl_add_u64 v[4:5], v[0:1], 0, v[2:3]
	v_lshl_add_u64 v[0:1], v[16:17], 0, v[2:3]
	v_lshlrev_b64 v[16:17], 1, v[12:13]
	v_mul_lo_u32 v12, v12, s6
	v_add_u32_e32 v138, 32, v12
	v_mul_u32_u24_e32 v12, 0x220, v20
	v_add3_u32 v57, v56, v12, v2
	ds_read_b128 v[194:197], v57 offset:26112
	ds_read_b128 v[198:201], v57 offset:26176
	global_load_dwordx4 v[240:243], v[4:5], off
	global_load_dwordx4 v[244:247], v[0:1], off
	global_load_dwordx4 v[248:251], v[4:5], off offset:64
	global_load_dwordx4 v[224:227], v[0:1], off offset:64
	global_load_dword v223, v[4:5], off offset:128
	global_load_dword v229, v[4:5], off offset:132
	global_load_dword v230, v[4:5], off offset:136
	global_load_dword v231, v[4:5], off offset:140
	global_load_dword v232, v[0:1], off offset:128
	global_load_dword v237, v[0:1], off offset:132
	global_load_dword v238, v[0:1], off offset:136
	global_load_dword v239, v[0:1], off offset:140
	s_waitcnt vmcnt(0)
	v_mov_b32_e32 v210, v240
	v_mov_b32_e32 v211, v241
	v_mov_b32_e32 v212, v242
	v_mov_b32_e32 v213, v243
	v_mov_b32_e32 v214, v244
	v_mov_b32_e32 v215, v245
	v_mov_b32_e32 v216, v246
	v_mov_b32_e32 v217, v247
	s_waitcnt lgkmcnt(1)
	v_mfma_f32_16x16x32_bf16 v[202:205], v[120:123], v[194:197], 0
	v_sub_u32_e32 v2, v57, v21
	ds_read_b64 v[12:13], v2 offset:26112
	v_lshl_add_u64 v[8:9], s[4:5], 0, v[16:17]
	s_waitcnt lgkmcnt(1)
	v_mfma_f32_16x16x32_bf16 v[202:205], v[128:131], v[198:201], v[202:205]
	v_lshl_add_u64 v[16:17], s[20:21], 0, v[16:17]
	v_add_u32_e32 v188, 0x8800, v138
	s_waitcnt lgkmcnt(0)
	v_lshlrev_b32_e32 v21, 16, v12
	v_mfma_f32_16x16x32_bf16 v[206:209], v[116:119], v[194:197], 0
	v_and_b32_e32 v56, 0xffff0000, v12
	v_lshlrev_b32_e32 v144, 16, v13
	v_and_b32_e32 v13, 0xffff0000, v13
	v_mfma_f32_16x16x32_bf16 v[206:209], v[124:127], v[198:201], v[206:209]
	s_waitcnt vmcnt(1)
	v_add_f32_e32 v12, v202, v210
	v_mul_f32_e32 v12, 0xbfb8aa3b, v12
	v_exp_f32_e32 v12, v12
	s_waitcnt vmcnt(0)
	s_nop 2
	v_add_f32_e32 v20, v206, v214
	v_mul_f32_e32 v20, 0xbfb8aa3b, v20
	v_exp_f32_e32 v20, v20
	v_add_f32_e32 v12, 1.0, v12
	v_rcp_f32_e32 v12, v12
	v_add_f32_e32 v20, 1.0, v20
	v_rcp_f32_e32 v142, v20
	v_mul_f32_e32 v12, 0xc1000000, v12
	s_waitcnt vmcnt(0)
	v_mul_f32_e32 v12, v12, v48
	v_mul_f32_e32 v12, 0x3fb8aa3b, v12
	v_exp_f32_e32 v20, v12
	s_nop 0
	v_sub_f32_e32 v12, 1.0, v20
	v_add_f32_e32 v143, 1.0, v20
	v_mul_f32_e32 v12, v12, v143
	v_max_f32_e32 v12, 0, v12
	v_sqrt_f32_e32 v12, v12
	s_nop 0
	v_mul_f32_e32 v12, v142, v12
	v_mul_f32_e32 v21, v12, v21
	v_mul_lo_u32 v12, v139, s6
	v_add_f32_e32 v139, v203, v211
	v_mul_f32_e32 v139, 0xbfb8aa3b, v139
	v_exp_f32_e32 v139, v139
	v_add3_u32 v12, 32, v140, v12
	v_add_f32_e32 v140, v207, v215
	v_mul_f32_e32 v140, 0xbfb8aa3b, v140
	v_add_f32_e32 v139, 1.0, v139
	v_rcp_f32_e32 v139, v139
	v_exp_f32_e32 v140, v140
	v_add_u32_e32 v192, 0x9000, v12
	v_add_u32_e32 v191, 0x9800, v12
	v_mul_f32_e32 v139, 0xc1000000, v139
	v_mul_f32_e32 v139, v139, v49
	v_mul_f32_e32 v139, 0x3fb8aa3b, v139
	v_exp_f32_e32 v142, v139
	v_add_f32_e32 v140, 1.0, v140
	v_rcp_f32_e32 v140, v140
	v_add_u32_e32 v190, 0xa000, v12
	v_sub_f32_e32 v139, 1.0, v142
	v_add_f32_e32 v143, 1.0, v142
	v_mul_f32_e32 v139, v139, v143
	v_max_f32_e32 v139, 0, v139
	v_sqrt_f32_e32 v139, v139
	s_mul_i32 s6, s1, 0x1c00
	v_mul_f32_e32 v139, v140, v139
	v_mul_f32_e32 v143, v139, v56
	v_add_u32_e32 v56, 0x8800, v12
	ds_write2_b64 v56, v[20:21], v[142:143] offset1:17
	v_add_f32_e32 v20, v204, v212
	v_mul_f32_e32 v20, 0xbfb8aa3b, v20
	v_exp_f32_e32 v20, v20
	v_add_f32_e32 v21, v208, v216
	v_mul_f32_e32 v21, 0xbfb8aa3b, v21
	v_exp_f32_e32 v21, v21
	v_add_f32_e32 v20, 1.0, v20
	v_rcp_f32_e32 v20, v20
	v_add_f32_e32 v21, 1.0, v21
	v_rcp_f32_e32 v21, v21
	v_mul_f32_e32 v20, 0xc1000000, v20
	v_mul_f32_e32 v20, v20, v50
	v_mul_f32_e32 v20, 0x3fb8aa3b, v20
	v_exp_f32_e32 v20, v20
	s_nop 0
	v_sub_f32_e32 v139, 1.0, v20
	v_add_f32_e32 v140, 1.0, v20
	v_mul_f32_e32 v139, v139, v140
	v_max_f32_e32 v139, 0, v139
	v_sqrt_f32_e32 v139, v139
	v_add_f32_e32 v140, v209, v217
	v_mul_f32_e32 v140, 0xbfb8aa3b, v140
	v_exp_f32_e32 v140, v140
	v_mul_f32_e32 v21, v21, v139
	v_add_f32_e32 v139, v205, v213
	v_mul_f32_e32 v139, 0xbfb8aa3b, v139
	v_exp_f32_e32 v139, v139
	v_add_f32_e32 v140, 1.0, v140
	v_rcp_f32_e32 v140, v140
	v_mul_f32_e32 v21, v21, v144
	v_add_f32_e32 v139, 1.0, v139
	v_rcp_f32_e32 v139, v139
	v_mfma_f32_16x16x32_bf16 v[202:205], v[104:107], v[194:197], 0
	v_mul_f32_e32 v139, 0xc1000000, v139
	v_mul_f32_e32 v139, v139, v52
	v_mul_f32_e32 v139, 0x3fb8aa3b, v139
	v_exp_f32_e32 v142, v139
	v_mfma_f32_16x16x32_bf16 v[206:209], v[112:115], v[198:201], v[202:205]
	v_sub_f32_e32 v139, 1.0, v142
	v_add_f32_e32 v143, 1.0, v142
	v_mul_f32_e32 v139, v139, v143
	v_max_f32_e32 v139, 0, v139
	v_sqrt_f32_e32 v139, v139
	v_mfma_f32_16x16x32_bf16 v[202:205], v[100:103], v[194:197], 0
	v_mul_f32_e32 v139, v140, v139
	v_mul_f32_e32 v143, v139, v13
	ds_write2_b64 v56, v[20:21], v[142:143] offset0:34 offset1:51
	v_mov_b32_e32 v210, v248
	v_mov_b32_e32 v211, v249
	v_mov_b32_e32 v212, v250
	v_mov_b32_e32 v213, v251
	v_mov_b32_e32 v214, v224
	v_mov_b32_e32 v215, v225
	v_mov_b32_e32 v216, v226
	v_mov_b32_e32 v217, v227
	ds_read_b64 v[20:21], v2 offset:26144
	v_mfma_f32_16x16x32_bf16 v[202:205], v[108:111], v[198:201], v[202:205]
	s_waitcnt lgkmcnt(0)
	v_lshlrev_b32_e32 v13, 16, v20
	v_and_b32_e32 v139, 0xffff0000, v20
	v_lshlrev_b32_e32 v140, 16, v21
	v_and_b32_e32 v144, 0xffff0000, v21
	s_waitcnt vmcnt(1)
	v_add_f32_e32 v20, v206, v210
	v_mul_f32_e32 v20, 0xbfb8aa3b, v20
	v_exp_f32_e32 v20, v20
	s_waitcnt vmcnt(0)
	v_add_f32_e32 v21, v202, v214
	v_mul_f32_e32 v21, 0xbfb8aa3b, v21
	v_exp_f32_e32 v21, v21
	v_add_f32_e32 v20, 1.0, v20
	v_rcp_f32_e32 v20, v20
	v_add_f32_e32 v21, 1.0, v21
	v_rcp_f32_e32 v21, v21
	v_mul_f32_e32 v20, 0xc1000000, v20
	v_mul_f32_e32 v20, v20, v182
	v_mul_f32_e32 v20, 0x3fb8aa3b, v20
	v_exp_f32_e32 v20, v20
	s_nop 0
	v_sub_f32_e32 v142, 1.0, v20
	v_add_f32_e32 v143, 1.0, v20
	v_mul_f32_e32 v142, v142, v143
	v_max_f32_e32 v142, 0, v142
	v_sqrt_f32_e32 v142, v142
	s_nop 0
	v_mul_f32_e32 v21, v21, v142
	v_mul_f32_e32 v21, v21, v13
	v_add_f32_e32 v13, v207, v211
	v_mul_f32_e32 v13, 0xbfb8aa3b, v13
	v_exp_f32_e32 v13, v13
	v_add_f32_e32 v142, v203, v215
	v_mul_f32_e32 v142, 0xbfb8aa3b, v142
	v_exp_f32_e32 v142, v142
	v_add_f32_e32 v13, 1.0, v13
	v_rcp_f32_e32 v13, v13
	v_add_f32_e32 v142, 1.0, v142
	v_rcp_f32_e32 v143, v142
	v_mul_f32_e32 v13, 0xc1000000, v13
	v_mul_f32_e32 v13, v13, v184
	v_mul_f32_e32 v13, 0x3fb8aa3b, v13
	v_exp_f32_e32 v142, v13
	s_nop 0
	v_sub_f32_e32 v13, 1.0, v142
	v_add_f32_e32 v146, 1.0, v142
	v_mul_f32_e32 v13, v13, v146
	v_max_f32_e32 v13, 0, v13
	v_sqrt_f32_e32 v13, v13
	s_nop 0
	v_mul_f32_e32 v13, v143, v13
	v_mul_f32_e32 v143, v13, v139
	v_add_f32_e32 v13, v208, v212
	v_mul_f32_e32 v13, 0xbfb8aa3b, v13
	v_exp_f32_e32 v13, v13
	ds_write2_b64 v192, v[20:21], v[142:143] offset0:16 offset1:33
	v_add_f32_e32 v20, v204, v216
	v_mul_f32_e32 v20, 0xbfb8aa3b, v20
	v_add_f32_e32 v13, 1.0, v13
	v_rcp_f32_e32 v13, v13
	v_exp_f32_e32 v20, v20
	v_mul_f32_e32 v13, 0xc1000000, v13
	v_mul_f32_e32 v13, v13, v186
	v_add_f32_e32 v20, 1.0, v20
	v_mul_f32_e32 v13, 0x3fb8aa3b, v13
	v_rcp_f32_e32 v21, v20
	v_exp_f32_e32 v20, v13
	s_nop 0
	v_sub_f32_e32 v13, 1.0, v20
	v_add_f32_e32 v139, 1.0, v20
	v_mul_f32_e32 v13, v13, v139
	v_max_f32_e32 v13, 0, v13
	v_sqrt_f32_e32 v13, v13
	v_add_f32_e32 v139, v205, v217
	v_mul_f32_e32 v139, 0xbfb8aa3b, v139
	v_exp_f32_e32 v139, v139
	v_mul_f32_e32 v13, v21, v13
	v_mul_f32_e32 v21, v13, v140
	v_add_f32_e32 v13, v209, v213
	v_mul_f32_e32 v13, 0xbfb8aa3b, v13
	v_exp_f32_e32 v13, v13
	v_add_f32_e32 v139, 1.0, v139
	v_rcp_f32_e32 v139, v139
	v_mfma_f32_16x16x32_bf16 v[202:205], v[88:91], v[194:197], 0
	v_add_f32_e32 v13, 1.0, v13
	v_rcp_f32_e32 v13, v13
	v_mfma_f32_16x16x32_bf16 v[202:205], v[96:99], v[198:201], v[202:205]
	v_mul_f32_e32 v13, 0xc1000000, v13
	v_mul_f32_e32 v13, v13, v187
	v_mul_f32_e32 v13, 0x3fb8aa3b, v13
	v_exp_f32_e32 v142, v13
	v_mfma_f32_16x16x32_bf16 v[206:209], v[84:87], v[194:197], 0
	v_sub_f32_e32 v13, 1.0, v142
	v_add_f32_e32 v140, 1.0, v142
	v_mul_f32_e32 v13, v13, v140
	v_max_f32_e32 v13, 0, v13
	v_sqrt_f32_e32 v13, v13
	v_mfma_f32_16x16x32_bf16 v[206:209], v[92:95], v[198:201], v[206:209]
	v_mul_f32_e32 v13, v139, v13
	v_mul_f32_e32 v143, v13, v144
	ds_write2_b64 v192, v[20:21], v[142:143] offset0:50 offset1:67
	v_mov_b32_e32 v210, v223
	v_mov_b32_e32 v211, v229
	v_mov_b32_e32 v212, v230
	v_mov_b32_e32 v213, v231
	v_mov_b32_e32 v214, v232
	v_mov_b32_e32 v215, v237
	v_mov_b32_e32 v216, v238
	v_mov_b32_e32 v217, v239
	ds_read_b64 v[20:21], v2 offset:26176
	s_waitcnt lgkmcnt(0)
	v_lshlrev_b32_e32 v13, 16, v20
	v_and_b32_e32 v139, 0xffff0000, v20
	v_lshlrev_b32_e32 v140, 16, v21
	v_and_b32_e32 v144, 0xffff0000, v21
	s_waitcnt vmcnt(1)
	v_add_f32_e32 v20, v202, v210
	v_mul_f32_e32 v20, 0xbfb8aa3b, v20
	v_exp_f32_e32 v20, v20
	s_waitcnt vmcnt(0)
	v_add_f32_e32 v21, v206, v214
	v_mul_f32_e32 v21, 0xbfb8aa3b, v21
	v_exp_f32_e32 v21, v21
	v_add_f32_e32 v20, 1.0, v20
	v_rcp_f32_e32 v20, v20
	v_add_f32_e32 v21, 1.0, v21
	v_rcp_f32_e32 v21, v21
	v_mul_f32_e32 v20, 0xc1000000, v20
	v_mul_f32_e32 v20, v20, v132
	v_mul_f32_e32 v20, 0x3fb8aa3b, v20
	v_exp_f32_e32 v20, v20
	s_nop 0
	v_sub_f32_e32 v142, 1.0, v20
	v_add_f32_e32 v143, 1.0, v20
	v_mul_f32_e32 v142, v142, v143
	v_max_f32_e32 v142, 0, v142
	v_sqrt_f32_e32 v142, v142
	s_nop 0
	v_mul_f32_e32 v21, v21, v142
	v_mul_f32_e32 v21, v21, v13
	v_add_f32_e32 v13, v203, v211
	v_mul_f32_e32 v13, 0xbfb8aa3b, v13
	v_exp_f32_e32 v13, v13
	v_add_f32_e32 v142, v207, v215
	v_mul_f32_e32 v142, 0xbfb8aa3b, v142
	v_exp_f32_e32 v142, v142
	v_add_f32_e32 v13, 1.0, v13
	v_rcp_f32_e32 v13, v13
	v_add_f32_e32 v142, 1.0, v142
	v_rcp_f32_e32 v143, v142
	v_mul_f32_e32 v13, 0xc1000000, v13
	v_mul_f32_e32 v13, v13, v160
	v_mul_f32_e32 v13, 0x3fb8aa3b, v13
	v_exp_f32_e32 v142, v13
	s_nop 0
	v_sub_f32_e32 v13, 1.0, v142
	v_add_f32_e32 v146, 1.0, v142
	v_mul_f32_e32 v13, v13, v146
	v_max_f32_e32 v13, 0, v13
	v_sqrt_f32_e32 v13, v13
	s_nop 0
	v_mul_f32_e32 v13, v143, v13
	v_mul_f32_e32 v143, v13, v139
	v_add_f32_e32 v13, v204, v212
	v_mul_f32_e32 v13, 0xbfb8aa3b, v13
	v_exp_f32_e32 v13, v13
	ds_write2_b64 v191, v[20:21], v[142:143] offset0:32 offset1:49
	v_add_f32_e32 v20, v208, v216
	v_mul_f32_e32 v20, 0xbfb8aa3b, v20
	v_add_f32_e32 v13, 1.0, v13
	v_rcp_f32_e32 v13, v13
	v_exp_f32_e32 v20, v20
	v_mul_f32_e32 v13, 0xc1000000, v13
	v_mul_f32_e32 v13, v13, v180
	v_add_f32_e32 v20, 1.0, v20
	v_mul_f32_e32 v13, 0x3fb8aa3b, v13
	v_rcp_f32_e32 v21, v20
	v_exp_f32_e32 v20, v13
	s_nop 0
	v_sub_f32_e32 v13, 1.0, v20
	v_add_f32_e32 v139, 1.0, v20
	v_mul_f32_e32 v13, v13, v139
	v_max_f32_e32 v13, 0, v13
	v_sqrt_f32_e32 v13, v13
	v_add_f32_e32 v139, v209, v217
	v_mul_f32_e32 v139, 0xbfb8aa3b, v139
	v_exp_f32_e32 v139, v139
	v_mul_f32_e32 v13, v21, v13
	v_mul_f32_e32 v21, v13, v140
	v_add_f32_e32 v13, v205, v213
	v_mul_f32_e32 v13, 0xbfb8aa3b, v13
	v_exp_f32_e32 v13, v13
	v_add_f32_e32 v139, 1.0, v139
	v_rcp_f32_e32 v139, v139
	v_mfma_f32_16x16x32_bf16 v[202:205], v[72:75], v[194:197], 0
	v_add_f32_e32 v13, 1.0, v13
	v_rcp_f32_e32 v13, v13
	v_mfma_f32_16x16x32_bf16 v[194:197], v[68:71], v[194:197], 0
	v_mul_f32_e32 v13, 0xc1000000, v13
	v_mul_f32_e32 v13, v13, v183
	v_mul_f32_e32 v13, 0x3fb8aa3b, v13
	v_exp_f32_e32 v142, v13
	v_mfma_f32_16x16x32_bf16 v[202:205], v[80:83], v[198:201], v[202:205]
	v_sub_f32_e32 v13, 1.0, v142
	v_add_f32_e32 v140, 1.0, v142
	v_mul_f32_e32 v13, v13, v140
	v_max_f32_e32 v13, 0, v13
	v_sqrt_f32_e32 v13, v13
	v_mfma_f32_16x16x32_bf16 v[194:197], v[76:79], v[198:201], v[194:197]
	v_mul_f32_e32 v13, v139, v13
	v_mul_f32_e32 v143, v13, v144
	ds_write2_b64 v191, v[20:21], v[142:143] offset0:66 offset1:83
	global_load_dwordx4 v[206:209], v[4:5], off offset:192
	global_load_dwordx4 v[198:201], v[0:1], off offset:192
	ds_read_b64 v[20:21], v2 offset:26208
	s_waitcnt lgkmcnt(0)
	v_lshlrev_b32_e32 v13, 16, v20
	v_and_b32_e32 v139, 0xffff0000, v20
	v_lshlrev_b32_e32 v140, 16, v21
	v_and_b32_e32 v20, 0xffff0000, v21
	s_waitcnt vmcnt(1)
	v_add_f32_e32 v21, v202, v206
	v_mul_f32_e32 v21, 0xbfb8aa3b, v21
	v_exp_f32_e32 v21, v21
	s_waitcnt vmcnt(0)
	v_add_f32_e32 v142, v194, v198
	v_mul_f32_e32 v142, 0xbfb8aa3b, v142
	v_exp_f32_e32 v142, v142
	v_add_f32_e32 v21, 1.0, v21
	v_rcp_f32_e32 v21, v21
	v_add_f32_e32 v12, v204, v208
	v_add_f32_e32 v142, 1.0, v142
	v_rcp_f32_e32 v143, v142
	v_mul_f32_e32 v21, 0xc1000000, v21
	v_mul_f32_e32 v21, v62, v21
	v_mul_f32_e32 v21, 0x3fb8aa3b, v21
	v_exp_f32_e32 v142, v21
	v_mul_f32_e32 v12, 0xbfb8aa3b, v12
	v_exp_f32_e32 v12, v12
	v_add_u32_e32 v194, 0x8850, v138
	v_sub_f32_e32 v21, 1.0, v142
	v_add_f32_e32 v144, 1.0, v142
	v_mul_f32_e32 v21, v21, v144
	v_max_f32_e32 v21, 0, v21
	v_sqrt_f32_e32 v21, v21
	v_add_f32_e32 v12, 1.0, v12
	v_rcp_f32_e32 v12, v12
	v_mul_f32_e32 v21, v143, v21
	v_mul_f32_e32 v143, v21, v13
	v_add_f32_e32 v13, v203, v207
	v_mul_f32_e32 v13, 0xbfb8aa3b, v13
	v_exp_f32_e32 v13, v13
	v_add_f32_e32 v21, v195, v199
	v_mul_f32_e32 v21, 0xbfb8aa3b, v21
	v_exp_f32_e32 v21, v21
	v_add_f32_e32 v13, 1.0, v13
	v_rcp_f32_e32 v13, v13
	v_mul_f32_e32 v12, 0xc1000000, v12
	v_add_f32_e32 v21, 1.0, v21
	v_rcp_f32_e32 v21, v21
	v_mul_f32_e32 v13, 0xc1000000, v13
	v_mul_f32_e32 v13, v64, v13
	v_mul_f32_e32 v13, 0x3fb8aa3b, v13
	v_exp_f32_e32 v146, v13
	v_mul_f32_e32 v12, v65, v12
	v_mul_f32_e32 v12, 0x3fb8aa3b, v12
	v_exp_f32_e32 v12, v12
	v_sub_f32_e32 v13, 1.0, v146
	v_add_f32_e32 v144, 1.0, v146
	v_mul_f32_e32 v13, v13, v144
	v_max_f32_e32 v13, 0, v13
	v_sqrt_f32_e32 v13, v13
	v_add_u32_e32 v195, 0x8860, v138
	v_mul_f32_e32 v13, v21, v13
	v_mul_f32_e32 v147, v13, v139
	v_add_f32_e32 v13, v196, v200
	v_mul_f32_e32 v13, 0xbfb8aa3b, v13
	v_exp_f32_e32 v13, v13
	v_sub_f32_e32 v21, 1.0, v12
	v_add_f32_e32 v139, 1.0, v12
	v_mul_f32_e32 v21, v21, v139
	v_add_f32_e32 v13, 1.0, v13
	v_max_f32_e32 v21, 0, v21
	v_rcp_f32_e32 v13, v13
	v_sqrt_f32_e32 v21, v21
	ds_write2_b64 v190, v[142:143], v[146:147] offset0:48 offset1:65
	v_add_f32_e32 v139, v197, v201
	v_mul_f32_e32 v139, 0xbfb8aa3b, v139
	v_mul_f32_e32 v13, v13, v21
	v_add_f32_e32 v21, v205, v209
	v_mul_f32_e32 v21, 0xbfb8aa3b, v21
	v_exp_f32_e32 v21, v21
	v_exp_f32_e32 v139, v139
	v_mul_f32_e32 v13, v13, v140
	v_add_u32_e32 v196, 0x8870, v138
	v_add_f32_e32 v21, 1.0, v21
	v_rcp_f32_e32 v21, v21
	v_add_f32_e32 v139, 1.0, v139
	v_rcp_f32_e32 v139, v139
	v_mul_f32_e32 v21, 0xc1000000, v21
	v_mul_f32_e32 v21, v66, v21
	v_mul_f32_e32 v21, 0x3fb8aa3b, v21
	v_exp_f32_e32 v142, v21
	s_nop 0
	v_sub_f32_e32 v21, 1.0, v142
	v_add_f32_e32 v140, 1.0, v142
	v_mul_f32_e32 v21, v21, v140
	v_max_f32_e32 v21, 0, v21
	v_sqrt_f32_e32 v21, v21
	s_nop 0
	v_mul_f32_e32 v21, v139, v21
	v_mul_f32_e32 v143, v21, v20
	ds_write2_b64 v190, v[12:13], v[142:143] offset0:82 offset1:99
	v_mad_u64_u32 v[12:13], s[4:5], s0, v233, v[8:9]
	s_mov_b32 s4, 0x6e000
	v_add_u32_e32 v13, s6, v13
	v_add_co_u32_e32 v20, vcc, s4, v12
	s_waitcnt lgkmcnt(0)
	s_nop 0
	v_addc_co_u32_e32 v21, vcc, 0, v13, vcc
	s_barrier
	global_load_ushort v20, v[20:21], off offset:1024
	ds_read2_b64 v[198:201], v196 offset1:1
	s_lshl_b64 s[4:5], s[0:1], 11
	s_or_b32 s8, s4, 0x18000
	s_mov_b32 s9, s5
	s_waitcnt lgkmcnt(0)
	v_fma_f32 v144, v221, v200, v201
	v_add_f32_e32 v139, v193, v144
	ds_read2_b64 v[200:203], v195 offset1:1
	v_fmac_f32_e32 v199, v144, v198
	v_add_f32_e32 v136, v136, v199
	v_add_u32_e32 v193, 0x8840, v138
	s_waitcnt vmcnt(0)
	v_lshlrev_b32_e32 v20, 16, v20
	v_mul_f32_e32 v20, v139, v20
	v_cvt_pk_bf16_f32 v148, v20, s0
	v_lshl_add_u64 v[20:21], v[16:17], 0, s[4:5]
	v_add_co_u32_e32 v142, vcc, s7, v20
	s_mov_b32 s7, 0x6c000
	s_nop 0
	v_addc_co_u32_e32 v143, vcc, 0, v21, vcc
	v_add_co_u32_e32 v146, vcc, s7, v12
	s_mov_b32 s7, 0x6a000
	s_nop 0
	v_addc_co_u32_e32 v147, vcc, 0, v13, vcc
	global_load_ushort v150, v[146:147], off offset:2048
	v_add_co_u32_e32 v146, vcc, s7, v12
	s_mov_b32 s7, 0x69000
	s_nop 0
	v_addc_co_u32_e32 v147, vcc, 0, v13, vcc
	global_load_ushort v151, v[146:147], off offset:3072
	v_add_co_u32_e32 v146, vcc, s7, v12
	s_mov_b32 s7, 0x67000
	s_nop 0
	v_addc_co_u32_e32 v147, vcc, 0, v13, vcc
	global_load_ushort v152, v[146:147], off
	v_add_co_u32_e32 v146, vcc, s7, v12
	s_mov_b32 s7, 0x65000
	s_nop 0
	v_addc_co_u32_e32 v147, vcc, 0, v13, vcc
	global_load_ushort v154, v[146:147], off offset:1024
	v_add_co_u32_e32 v146, vcc, s7, v12
	s_mov_b32 s7, 0x63000
	s_nop 0
	v_addc_co_u32_e32 v147, vcc, 0, v13, vcc
	global_load_ushort v155, v[146:147], off offset:2048
	v_add_co_u32_e32 v146, vcc, s7, v12
	s_mov_b32 s7, 0x62000
	s_nop 0
	v_addc_co_u32_e32 v147, vcc, 0, v13, vcc
	global_load_ushort v156, v[146:147], off offset:3072
	v_add_co_u32_e32 v146, vcc, s7, v12
	s_mov_b32 s7, 0x60000
	s_nop 0
	v_addc_co_u32_e32 v147, vcc, 0, v13, vcc
	global_load_ushort v158, v[146:147], off
	v_add_co_u32_e32 v146, vcc, s7, v12
	s_mov_b32 s7, 0x5e000
	s_nop 0
	v_addc_co_u32_e32 v147, vcc, 0, v13, vcc
	global_load_ushort v159, v[146:147], off offset:1024
	v_add_co_u32_e32 v146, vcc, s7, v12
	s_mov_b32 s7, 0x5c000
	s_nop 0
	v_addc_co_u32_e32 v147, vcc, 0, v13, vcc
	global_load_ushort v162, v[146:147], off offset:2048
	v_add_co_u32_e32 v146, vcc, s7, v12
	s_mov_b32 s7, 0x5b000
	s_nop 0
	v_addc_co_u32_e32 v147, vcc, 0, v13, vcc
	global_load_ushort v163, v[146:147], off offset:3072
	v_add_co_u32_e32 v146, vcc, s7, v12
	s_mov_b32 s7, 0x59000
	s_nop 0
	v_addc_co_u32_e32 v147, vcc, 0, v13, vcc
	global_load_ushort v164, v[146:147], off
	v_add_co_u32_e32 v146, vcc, s7, v12
	s_mov_b32 s7, 0x57000
	s_nop 0
	v_addc_co_u32_e32 v147, vcc, 0, v13, vcc
	global_load_ushort v166, v[146:147], off offset:1024
	v_add_co_u32_e32 v146, vcc, s7, v12
	s_mov_b32 s7, 0x55000
	s_nop 0
	v_addc_co_u32_e32 v147, vcc, 0, v13, vcc
	global_load_ushort v167, v[146:147], off offset:2048
	v_add_co_u32_e32 v146, vcc, s7, v12
	s_mov_b32 s7, 0x54000
	s_nop 0
	v_addc_co_u32_e32 v147, vcc, 0, v13, vcc
	global_load_ushort v140, v[146:147], off offset:3072
	v_add_co_u32_e32 v146, vcc, s7, v12
	s_waitcnt vmcnt(13)
	v_lshlrev_b32_e32 v144, 16, v150
	v_addc_co_u32_e32 v147, vcc, 0, v13, vcc
	global_load_ushort v139, v[146:147], off
	v_mul_f32_e32 v136, v136, v144
	v_cvt_pk_bf16_f32 v136, v136, s0
	global_store_short v[142:143], v136, off
	s_waitcnt lgkmcnt(0)
	v_fma_f32 v136, v199, v202, v203
	ds_read2_b64 v[202:205], v194 offset1:1
	global_store_short v[142:143], v148, off offset:2048
	v_add_f32_e32 v142, v189, v136
	s_waitcnt vmcnt(15)
	v_lshlrev_b32_e32 v143, 16, v151
	v_fmac_f32_e32 v201, v136, v200
	v_mul_f32_e32 v142, v142, v143
	s_mov_b32 s7, 0x1e000
	v_add_f32_e32 v135, v135, v201
	s_waitcnt vmcnt(14)
	v_lshlrev_b32_e32 v136, 16, v152
	v_cvt_pk_bf16_f32 v144, v142, s0
	v_add_co_u32_e32 v142, vcc, s7, v20
	v_mul_f32_e32 v135, v135, v136
	s_nop 0
	v_addc_co_u32_e32 v143, vcc, 0, v21, vcc
	v_cvt_pk_bf16_f32 v135, v135, s0
	global_store_short v[142:143], v135, off
	s_waitcnt lgkmcnt(0)
	v_fma_f32 v135, v201, v204, v205
	ds_read2_b64 v[198:201], v193 offset1:1
	global_store_short v[142:143], v144, off offset:2048
	v_add_f32_e32 v136, v185, v135
	s_waitcnt vmcnt(15)
	v_lshlrev_b32_e32 v142, 16, v154
	s_mov_b32 s7, 0x1d000
	v_fmac_f32_e32 v203, v135, v202
	v_mul_f32_e32 v136, v136, v142
	v_add_co_u32_e32 v142, vcc, s7, v20
	v_add_f32_e32 v134, v134, v203
	s_waitcnt vmcnt(14)
	v_lshlrev_b32_e32 v135, 16, v155
	v_cvt_pk_bf16_f32 v136, v136, s0
	v_addc_co_u32_e32 v143, vcc, 0, v21, vcc
	v_mul_f32_e32 v134, v134, v135
	v_add_u32_e32 v189, 0x8830, v138
	global_store_short v[142:143], v136, off offset:2048
	v_cvt_pk_bf16_f32 v134, v134, s0
	s_waitcnt lgkmcnt(0)
	v_fma_f32 v136, v203, v200, v201
	ds_read2_b64 v[200:203], v189 offset1:1
	global_store_short v[142:143], v134, off
	v_add_f32_e32 v134, v181, v136
	s_waitcnt vmcnt(15)
	v_lshlrev_b32_e32 v135, 16, v156
	v_fmac_f32_e32 v199, v136, v198
	v_mul_f32_e32 v134, v134, v135
	s_mov_b32 s7, 0x1c000
	v_add_f32_e32 v61, v61, v199
	s_waitcnt vmcnt(14)
	v_lshlrev_b32_e32 v136, 16, v158
	v_cvt_pk_bf16_f32 v142, v134, s0
	v_add_co_u32_e32 v134, vcc, s7, v20
	v_mul_f32_e32 v61, v61, v136
	s_nop 0
	v_addc_co_u32_e32 v135, vcc, 0, v21, vcc
	v_cvt_pk_bf16_f32 v61, v61, s0
	global_store_short v[134:135], v61, off
	s_waitcnt lgkmcnt(0)
	v_fma_f32 v61, v199, v202, v203
	v_add_u32_e32 v185, 0x8820, v138
	global_store_short v[134:135], v142, off offset:2048
	v_add_f32_e32 v134, v177, v61
	ds_read2_b64 v[174:177], v185 offset1:1
	s_waitcnt vmcnt(15)
	v_lshlrev_b32_e32 v135, 16, v159
	v_fmac_f32_e32 v201, v61, v200
	v_mul_f32_e32 v134, v134, v135
	s_mov_b32 s7, 0x1b000
	v_add_f32_e32 v60, v60, v201
	s_waitcnt vmcnt(14)
	v_lshlrev_b32_e32 v61, 16, v162
	v_cvt_pk_bf16_f32 v136, v134, s0
	v_add_co_u32_e32 v134, vcc, s7, v20
	v_mul_f32_e32 v60, v60, v61
	s_nop 0
	v_addc_co_u32_e32 v135, vcc, 0, v21, vcc
	v_cvt_pk_bf16_f32 v60, v60, s0
	global_store_short v[134:135], v136, off offset:2048
	global_store_short v[134:135], v60, off
	s_waitcnt lgkmcnt(0)
	v_fma_f32 v134, v201, v176, v177
	v_add_u32_e32 v181, 0x8810, v138
	v_add_f32_e32 v60, v173, v134
	ds_read2_b64 v[170:173], v181 offset1:1
	s_waitcnt vmcnt(15)
	v_lshlrev_b32_e32 v61, 16, v163
	v_fmac_f32_e32 v175, v134, v174
	v_mul_f32_e32 v60, v60, v61
	s_mov_b32 s7, 0x1a000
	v_add_f32_e32 v58, v58, v175
	s_waitcnt vmcnt(14)
	v_lshlrev_b32_e32 v134, 16, v164
	v_cvt_pk_bf16_f32 v135, v60, s0
	v_add_co_u32_e32 v60, vcc, s7, v20
	v_mul_f32_e32 v58, v58, v134
	s_nop 0
	v_addc_co_u32_e32 v61, vcc, 0, v21, vcc
	v_cvt_pk_bf16_f32 v58, v58, s0
	global_store_short v[60:61], v58, off
	s_waitcnt lgkmcnt(0)
	v_fma_f32 v58, v175, v172, v173
	global_store_short v[60:61], v135, off offset:2048
	v_add_f32_e32 v60, v169, v58
	s_waitcnt vmcnt(15)
	v_lshlrev_b32_e32 v61, 16, v166
	v_fmac_f32_e32 v171, v58, v170
	s_waitcnt vmcnt(14)
	v_lshlrev_b32_e32 v58, 16, v167
	ds_read2_b64 v[166:169], v188 offset1:1
	v_mul_f32_e32 v60, v60, v61
	s_mov_b32 s7, 0x19000
	v_add_f32_e32 v25, v25, v171
	v_cvt_pk_bf16_f32 v134, v60, s0
	v_add_co_u32_e32 v60, vcc, s7, v20
	v_mul_f32_e32 v25, v25, v58
	s_nop 0
	v_addc_co_u32_e32 v61, vcc, 0, v21, vcc
	v_cvt_pk_bf16_f32 v25, v25, s0
	global_store_short v[60:61], v25, off
	s_waitcnt lgkmcnt(0)
	v_fma_f32 v25, v171, v168, v169
	global_store_short v[60:61], v134, off offset:2048
	v_add_f32_e32 v58, v165, v25
	s_waitcnt vmcnt(15)
	v_lshlrev_b32_e32 v60, 16, v140
	s_mov_b32 s7, 0x18000
	v_fmac_f32_e32 v167, v25, v166
	v_mul_f32_e32 v58, v58, v60
	v_add_co_u32_e32 v60, vcc, s7, v20
	v_add_f32_e32 v24, v24, v167
	s_waitcnt vmcnt(14)
	v_lshlrev_b32_e32 v25, 16, v139
	v_cvt_pk_bf16_f32 v58, v58, s0
	v_addc_co_u32_e32 v61, vcc, 0, v21, vcc
	v_mul_f32_e32 v24, v24, v25
	global_store_short v[60:61], v58, off offset:2048
	v_cvt_pk_bf16_f32 v58, v24, s0
	v_lshl_add_u64 v[24:25], v[16:17], 0, s[8:9]
	global_store_short v[24:25], v58, off
	s_barrier
	ds_read_b128 v[162:165], v57 offset:17408
	ds_read_b128 v[168:171], v57 offset:17472
	v_mov_b32_e32 v198, v240
	v_mov_b32_e32 v199, v241
	v_mov_b32_e32 v200, v242
	v_mov_b32_e32 v201, v243
	v_mov_b32_e32 v202, v244
	v_mov_b32_e32 v203, v245
	v_mov_b32_e32 v204, v246
	v_mov_b32_e32 v205, v247
	s_waitcnt lgkmcnt(1)
	v_mfma_f32_16x16x32_bf16 v[172:175], v[120:123], v[162:165], 0
	ds_read_b64 v[24:25], v2 offset:17408
	s_or_b32 s8, s0, 47
	s_mov_b32 s7, 0xfffe8000
	s_waitcnt lgkmcnt(1)
	v_mfma_f32_16x16x32_bf16 v[172:175], v[128:131], v[168:171], v[172:175]
	s_mov_b32 s9, s1
	s_waitcnt lgkmcnt(0)
	v_lshlrev_b32_e32 v58, 16, v24
	v_and_b32_e32 v61, 0xffff0000, v24
	v_mfma_f32_16x16x32_bf16 v[176:179], v[116:119], v[162:165], 0
	v_lshlrev_b32_e32 v134, 16, v25
	v_and_b32_e32 v135, 0xffff0000, v25
	s_waitcnt vmcnt(1)
	v_add_f32_e32 v24, v172, v198
	v_mul_f32_e32 v24, 0xbfb8aa3b, v24
	v_exp_f32_e32 v24, v24
	v_mfma_f32_16x16x32_bf16 v[176:179], v[124:127], v[168:171], v[176:179]
	v_add_f32_e32 v24, 1.0, v24
	v_rcp_f32_e32 v24, v24
	s_nop 0
	v_mul_f32_e32 v24, 0xc1000000, v24
	v_mul_f32_e32 v24, v48, v24
	v_mul_f32_e32 v24, 0x3fb8aa3b, v24
	s_waitcnt vmcnt(0)
	s_nop 0
	v_add_f32_e32 v25, v176, v202
	v_exp_f32_e32 v24, v24
	v_mul_f32_e32 v25, 0xbfb8aa3b, v25
	v_exp_f32_e32 v25, v25
	v_sub_f32_e32 v60, 1.0, v24
	v_add_f32_e32 v136, 1.0, v24
	v_mul_f32_e32 v60, v60, v136
	v_add_f32_e32 v25, 1.0, v25
	v_max_f32_e32 v60, 0, v60
	v_rcp_f32_e32 v25, v25
	v_sqrt_f32_e32 v60, v60
	s_nop 0
	v_mul_f32_e32 v25, v25, v60
	v_mul_f32_e32 v25, v25, v58
	v_add_f32_e32 v58, v173, v199
	v_mul_f32_e32 v58, 0xbfb8aa3b, v58
	v_exp_f32_e32 v58, v58
	v_add_f32_e32 v60, v177, v203
	v_mul_f32_e32 v60, 0xbfb8aa3b, v60
	v_exp_f32_e32 v60, v60
	v_add_f32_e32 v58, 1.0, v58
	v_rcp_f32_e32 v58, v58
	v_add_f32_e32 v60, 1.0, v60
	v_rcp_f32_e32 v136, v60
	v_mul_f32_e32 v58, 0xc1000000, v58
	v_mul_f32_e32 v58, v49, v58
	v_mul_f32_e32 v58, 0x3fb8aa3b, v58
	v_exp_f32_e32 v60, v58
	s_nop 0
	v_sub_f32_e32 v58, 1.0, v60
	v_add_f32_e32 v138, 1.0, v60
	v_mul_f32_e32 v58, v58, v138
	v_max_f32_e32 v58, 0, v58
	v_sqrt_f32_e32 v58, v58
	s_nop 0
	v_mul_f32_e32 v58, v136, v58
	v_mul_f32_e32 v61, v58, v61
	ds_write2_b64 v56, v[24:25], v[60:61] offset1:17
	v_add_f32_e32 v24, v174, v200
	v_mul_f32_e32 v24, 0xbfb8aa3b, v24
	v_exp_f32_e32 v24, v24
	v_add_f32_e32 v25, v178, v204
	v_mul_f32_e32 v25, 0xbfb8aa3b, v25
	v_exp_f32_e32 v25, v25
	v_add_f32_e32 v24, 1.0, v24
	v_rcp_f32_e32 v24, v24
	v_add_f32_e32 v25, 1.0, v25
	v_rcp_f32_e32 v25, v25
	v_mul_f32_e32 v24, 0xc1000000, v24
	v_mul_f32_e32 v24, v50, v24
	v_mul_f32_e32 v24, 0x3fb8aa3b, v24
	v_exp_f32_e32 v24, v24
	s_nop 0
	v_sub_f32_e32 v58, 1.0, v24
	v_add_f32_e32 v60, 1.0, v24
	v_mul_f32_e32 v58, v58, v60
	v_max_f32_e32 v58, 0, v58
	v_sqrt_f32_e32 v58, v58
	v_add_f32_e32 v60, v179, v205
	v_mul_f32_e32 v60, 0xbfb8aa3b, v60
	v_exp_f32_e32 v60, v60
	v_mul_f32_e32 v25, v25, v58
	v_add_f32_e32 v58, v175, v201
	v_mul_f32_e32 v58, 0xbfb8aa3b, v58
	v_exp_f32_e32 v58, v58
	v_add_f32_e32 v60, 1.0, v60
	v_rcp_f32_e32 v61, v60
	v_mul_f32_e32 v25, v25, v134
	v_add_f32_e32 v58, 1.0, v58
	v_rcp_f32_e32 v58, v58
	v_mfma_f32_16x16x32_bf16 v[172:175], v[104:107], v[162:165], 0
	v_mul_f32_e32 v58, 0xc1000000, v58
	v_mul_f32_e32 v58, v52, v58
	v_mul_f32_e32 v58, 0x3fb8aa3b, v58
	v_exp_f32_e32 v60, v58
	v_mfma_f32_16x16x32_bf16 v[172:175], v[112:115], v[168:171], v[172:175]
	v_sub_f32_e32 v58, 1.0, v60
	v_add_f32_e32 v134, 1.0, v60
	v_mul_f32_e32 v58, v58, v134
	v_max_f32_e32 v58, 0, v58
	v_sqrt_f32_e32 v58, v58
	v_mfma_f32_16x16x32_bf16 v[176:179], v[100:103], v[162:165], 0
	v_mul_f32_e32 v58, v61, v58
	v_mul_f32_e32 v61, v58, v135
	ds_write2_b64 v56, v[24:25], v[60:61] offset0:34 offset1:51
	v_mov_b32_e32 v198, v248
	v_mov_b32_e32 v199, v249
	v_mov_b32_e32 v200, v250
	v_mov_b32_e32 v201, v251
	v_mov_b32_e32 v202, v224
	v_mov_b32_e32 v203, v225
	v_mov_b32_e32 v204, v226
	v_mov_b32_e32 v205, v227
	ds_read_b64 v[24:25], v2 offset:17440
	v_mfma_f32_16x16x32_bf16 v[176:179], v[108:111], v[168:171], v[176:179]
	s_waitcnt lgkmcnt(0)
	v_lshlrev_b32_e32 v58, 16, v24
	v_and_b32_e32 v61, 0xffff0000, v24
	v_lshlrev_b32_e32 v134, 16, v25
	v_and_b32_e32 v135, 0xffff0000, v25
	s_waitcnt vmcnt(1)
	v_add_f32_e32 v24, v172, v198
	v_mul_f32_e32 v24, 0xbfb8aa3b, v24
	v_exp_f32_e32 v24, v24
	s_waitcnt vmcnt(0)
	v_add_f32_e32 v25, v176, v202
	v_mul_f32_e32 v25, 0xbfb8aa3b, v25
	v_exp_f32_e32 v25, v25
	v_add_f32_e32 v24, 1.0, v24
	v_rcp_f32_e32 v24, v24
	v_add_f32_e32 v25, 1.0, v25
	v_rcp_f32_e32 v25, v25
	v_mul_f32_e32 v24, 0xc1000000, v24
	v_mul_f32_e32 v24, v182, v24
	v_mul_f32_e32 v24, 0x3fb8aa3b, v24
	v_exp_f32_e32 v24, v24
	s_nop 0
	v_sub_f32_e32 v60, 1.0, v24
	v_add_f32_e32 v136, 1.0, v24
	v_mul_f32_e32 v60, v60, v136
	v_max_f32_e32 v60, 0, v60
	v_sqrt_f32_e32 v60, v60
	s_nop 0
	v_mul_f32_e32 v25, v25, v60
	v_mul_f32_e32 v25, v25, v58
	v_add_f32_e32 v58, v173, v199
	v_mul_f32_e32 v58, 0xbfb8aa3b, v58
	v_exp_f32_e32 v58, v58
	v_add_f32_e32 v60, v177, v203
	v_mul_f32_e32 v60, 0xbfb8aa3b, v60
	v_exp_f32_e32 v60, v60
	v_add_f32_e32 v58, 1.0, v58
	v_rcp_f32_e32 v58, v58
	v_add_f32_e32 v60, 1.0, v60
	v_rcp_f32_e32 v136, v60
	v_mul_f32_e32 v58, 0xc1000000, v58
	v_mul_f32_e32 v58, v184, v58
	v_mul_f32_e32 v58, 0x3fb8aa3b, v58
	v_exp_f32_e32 v60, v58
	s_nop 0
	v_sub_f32_e32 v58, 1.0, v60
	v_add_f32_e32 v138, 1.0, v60
	v_mul_f32_e32 v58, v58, v138
	v_max_f32_e32 v58, 0, v58
	v_sqrt_f32_e32 v58, v58
	s_nop 0
	v_mul_f32_e32 v58, v136, v58
	v_mul_f32_e32 v61, v58, v61
	ds_write2_b64 v192, v[24:25], v[60:61] offset0:16 offset1:33
	v_add_f32_e32 v24, v174, v200
	v_mul_f32_e32 v24, 0xbfb8aa3b, v24
	v_exp_f32_e32 v24, v24
	v_add_f32_e32 v25, v178, v204
	v_mul_f32_e32 v25, 0xbfb8aa3b, v25
	v_exp_f32_e32 v25, v25
	v_add_f32_e32 v24, 1.0, v24
	v_rcp_f32_e32 v24, v24
	v_add_f32_e32 v25, 1.0, v25
	v_rcp_f32_e32 v25, v25
	v_mul_f32_e32 v24, 0xc1000000, v24
	v_mul_f32_e32 v24, v186, v24
	v_mul_f32_e32 v24, 0x3fb8aa3b, v24
	v_exp_f32_e32 v24, v24
	s_nop 0
	v_sub_f32_e32 v58, 1.0, v24
	v_add_f32_e32 v60, 1.0, v24
	v_mul_f32_e32 v58, v58, v60
	v_max_f32_e32 v58, 0, v58
	v_sqrt_f32_e32 v58, v58
	v_add_f32_e32 v60, v179, v205
	v_mul_f32_e32 v60, 0xbfb8aa3b, v60
	v_exp_f32_e32 v60, v60
	v_mul_f32_e32 v25, v25, v58
	v_add_f32_e32 v58, v175, v201
	v_mul_f32_e32 v58, 0xbfb8aa3b, v58
	v_exp_f32_e32 v58, v58
	v_add_f32_e32 v60, 1.0, v60
	v_rcp_f32_e32 v61, v60
	v_mul_f32_e32 v25, v25, v134
	v_add_f32_e32 v58, 1.0, v58
	v_rcp_f32_e32 v58, v58
	v_mfma_f32_16x16x32_bf16 v[172:175], v[88:91], v[162:165], 0
	v_mul_f32_e32 v58, 0xc1000000, v58
	v_mul_f32_e32 v58, v187, v58
	v_mul_f32_e32 v58, 0x3fb8aa3b, v58
	v_exp_f32_e32 v60, v58
	v_mfma_f32_16x16x32_bf16 v[172:175], v[96:99], v[168:171], v[172:175]
	v_sub_f32_e32 v58, 1.0, v60
	v_add_f32_e32 v134, 1.0, v60
	v_mul_f32_e32 v58, v58, v134
	v_max_f32_e32 v58, 0, v58
	v_sqrt_f32_e32 v58, v58
	v_mfma_f32_16x16x32_bf16 v[176:179], v[84:87], v[162:165], 0
	v_mul_f32_e32 v58, v61, v58
	v_mul_f32_e32 v61, v58, v135
	ds_write2_b64 v192, v[24:25], v[60:61] offset0:50 offset1:67
	v_mov_b32_e32 v198, v223
	v_mov_b32_e32 v199, v229
	v_mov_b32_e32 v200, v230
	v_mov_b32_e32 v201, v231
	v_mov_b32_e32 v202, v232
	v_mov_b32_e32 v203, v237
	v_mov_b32_e32 v204, v238
	v_mov_b32_e32 v205, v239
	ds_read_b64 v[24:25], v2 offset:17472
	v_mfma_f32_16x16x32_bf16 v[176:179], v[92:95], v[168:171], v[176:179]
	s_waitcnt lgkmcnt(0)
	v_lshlrev_b32_e32 v58, 16, v24
	v_and_b32_e32 v61, 0xffff0000, v24
	v_lshlrev_b32_e32 v134, 16, v25
	v_and_b32_e32 v135, 0xffff0000, v25
	s_waitcnt vmcnt(1)
	v_add_f32_e32 v24, v172, v198
	v_mul_f32_e32 v24, 0xbfb8aa3b, v24
	v_exp_f32_e32 v24, v24
	s_waitcnt vmcnt(0)
	v_add_f32_e32 v25, v176, v202
	v_mul_f32_e32 v25, 0xbfb8aa3b, v25
	v_exp_f32_e32 v25, v25
	v_add_f32_e32 v24, 1.0, v24
	v_rcp_f32_e32 v24, v24
	v_add_f32_e32 v25, 1.0, v25
	v_rcp_f32_e32 v25, v25
	v_mul_f32_e32 v24, 0xc1000000, v24
	v_mul_f32_e32 v24, v132, v24
	v_mul_f32_e32 v24, 0x3fb8aa3b, v24
	v_exp_f32_e32 v24, v24
	s_nop 0
	v_sub_f32_e32 v60, 1.0, v24
	v_add_f32_e32 v136, 1.0, v24
	v_mul_f32_e32 v60, v60, v136
	v_max_f32_e32 v60, 0, v60
	v_sqrt_f32_e32 v60, v60
	s_nop 0
	v_mul_f32_e32 v25, v25, v60
	v_mul_f32_e32 v25, v25, v58
	v_add_f32_e32 v58, v173, v199
	v_mul_f32_e32 v58, 0xbfb8aa3b, v58
	v_exp_f32_e32 v58, v58
	v_add_f32_e32 v60, v177, v203
	v_mul_f32_e32 v60, 0xbfb8aa3b, v60
	v_exp_f32_e32 v60, v60
	v_add_f32_e32 v58, 1.0, v58
	v_rcp_f32_e32 v58, v58
	v_add_f32_e32 v60, 1.0, v60
	v_rcp_f32_e32 v136, v60
	v_mul_f32_e32 v58, 0xc1000000, v58
	v_mul_f32_e32 v58, v160, v58
	v_mul_f32_e32 v58, 0x3fb8aa3b, v58
	v_exp_f32_e32 v60, v58
	s_nop 0
	v_sub_f32_e32 v58, 1.0, v60
	v_add_f32_e32 v138, 1.0, v60
	v_mul_f32_e32 v58, v58, v138
	v_max_f32_e32 v58, 0, v58
	v_sqrt_f32_e32 v58, v58
	s_nop 0
	v_mul_f32_e32 v58, v136, v58
	v_mul_f32_e32 v61, v58, v61
	ds_write2_b64 v191, v[24:25], v[60:61] offset0:32 offset1:49
	v_add_f32_e32 v24, v174, v200
	v_mul_f32_e32 v24, 0xbfb8aa3b, v24
	v_exp_f32_e32 v24, v24
	v_add_f32_e32 v25, v178, v204
	v_mul_f32_e32 v25, 0xbfb8aa3b, v25
	v_exp_f32_e32 v25, v25
	v_add_f32_e32 v24, 1.0, v24
	v_rcp_f32_e32 v24, v24
	v_add_f32_e32 v25, 1.0, v25
	v_rcp_f32_e32 v25, v25
	v_mul_f32_e32 v24, 0xc1000000, v24
	v_mul_f32_e32 v24, v180, v24
	v_mul_f32_e32 v24, 0x3fb8aa3b, v24
	v_exp_f32_e32 v24, v24
	s_nop 0
	v_sub_f32_e32 v58, 1.0, v24
	v_add_f32_e32 v60, 1.0, v24
	v_mul_f32_e32 v58, v58, v60
	v_max_f32_e32 v58, 0, v58
	v_sqrt_f32_e32 v58, v58
	v_add_f32_e32 v60, v179, v205
	v_mul_f32_e32 v60, 0xbfb8aa3b, v60
	v_exp_f32_e32 v60, v60
	v_mul_f32_e32 v25, v25, v58
	v_add_f32_e32 v58, v175, v201
	v_mul_f32_e32 v58, 0xbfb8aa3b, v58
	v_exp_f32_e32 v58, v58
	v_add_f32_e32 v60, 1.0, v60
	v_rcp_f32_e32 v61, v60
	v_mul_f32_e32 v25, v25, v134
	v_add_f32_e32 v58, 1.0, v58
	v_rcp_f32_e32 v58, v58
	v_mfma_f32_16x16x32_bf16 v[172:175], v[72:75], v[162:165], 0
	v_mul_f32_e32 v58, 0xc1000000, v58
	v_mul_f32_e32 v58, v183, v58
	v_mul_f32_e32 v58, 0x3fb8aa3b, v58
	v_exp_f32_e32 v60, v58
	v_mfma_f32_16x16x32_bf16 v[162:165], v[68:71], v[162:165], 0
	v_sub_f32_e32 v58, 1.0, v60
	v_add_f32_e32 v134, 1.0, v60
	v_mul_f32_e32 v58, v58, v134
	v_max_f32_e32 v58, 0, v58
	v_sqrt_f32_e32 v58, v58
	v_mfma_f32_16x16x32_bf16 v[172:175], v[80:83], v[168:171], v[172:175]
	v_mul_f32_e32 v58, v61, v58
	v_mul_f32_e32 v61, v58, v135
	ds_write2_b64 v191, v[24:25], v[60:61] offset0:66 offset1:83
	v_mfma_f32_16x16x32_bf16 v[162:165], v[76:79], v[168:171], v[162:165]
	global_load_dwordx4 v[176:179], v[4:5], off offset:192
	global_load_dwordx4 v[168:171], v[0:1], off offset:192
	ds_read_b64 v[24:25], v2 offset:17504
	s_waitcnt lgkmcnt(0)
	v_lshlrev_b32_e32 v60, 16, v24
	v_and_b32_e32 v61, 0xffff0000, v24
	v_lshlrev_b32_e32 v134, 16, v25
	v_and_b32_e32 v58, 0xffff0000, v25
	s_waitcnt vmcnt(1)
	v_add_f32_e32 v24, v172, v176
	v_mul_f32_e32 v24, 0xbfb8aa3b, v24
	v_exp_f32_e32 v24, v24
	s_waitcnt vmcnt(0)
	v_add_f32_e32 v25, v162, v168
	v_mul_f32_e32 v25, 0xbfb8aa3b, v25
	v_exp_f32_e32 v25, v25
	v_add_f32_e32 v24, 1.0, v24
	v_rcp_f32_e32 v24, v24
	v_add_f32_e32 v25, 1.0, v25
	v_rcp_f32_e32 v25, v25
	v_mul_f32_e32 v24, 0xc1000000, v24
	v_mul_f32_e32 v24, v62, v24
	v_mul_f32_e32 v24, 0x3fb8aa3b, v24
	v_exp_f32_e32 v24, v24
	s_nop 0
	v_sub_f32_e32 v135, 1.0, v24
	v_add_f32_e32 v136, 1.0, v24
	v_mul_f32_e32 v135, v135, v136
	v_max_f32_e32 v135, 0, v135
	v_sqrt_f32_e32 v135, v135
	s_nop 0
	v_mul_f32_e32 v25, v25, v135
	v_mul_f32_e32 v25, v25, v60
	v_add_f32_e32 v60, v173, v177
	v_mul_f32_e32 v60, 0xbfb8aa3b, v60
	v_exp_f32_e32 v60, v60
	v_add_f32_e32 v135, v163, v169
	v_mul_f32_e32 v135, 0xbfb8aa3b, v135
	v_exp_f32_e32 v135, v135
	v_add_f32_e32 v60, 1.0, v60
	v_rcp_f32_e32 v60, v60
	v_add_f32_e32 v135, 1.0, v135
	v_rcp_f32_e32 v135, v135
	v_mul_f32_e32 v60, 0xc1000000, v60
	v_mul_f32_e32 v60, v64, v60
	v_mul_f32_e32 v60, 0x3fb8aa3b, v60
	v_exp_f32_e32 v60, v60
	s_nop 0
	v_sub_f32_e32 v136, 1.0, v60
	v_add_f32_e32 v138, 1.0, v60
	v_mul_f32_e32 v136, v136, v138
	v_max_f32_e32 v136, 0, v136
	v_sqrt_f32_e32 v136, v136
	s_nop 0
	v_mul_f32_e32 v135, v135, v136
	v_mul_f32_e32 v61, v135, v61
	ds_write2_b64 v190, v[24:25], v[60:61] offset0:48 offset1:65
	v_add_f32_e32 v24, v174, v178
	v_mul_f32_e32 v24, 0xbfb8aa3b, v24
	v_exp_f32_e32 v24, v24
	v_add_f32_e32 v25, v164, v170
	v_mul_f32_e32 v25, 0xbfb8aa3b, v25
	v_exp_f32_e32 v25, v25
	v_add_f32_e32 v24, 1.0, v24
	v_rcp_f32_e32 v24, v24
	v_add_f32_e32 v25, 1.0, v25
	v_rcp_f32_e32 v25, v25
	v_mul_f32_e32 v24, 0xc1000000, v24
	v_mul_f32_e32 v24, v65, v24
	v_mul_f32_e32 v24, 0x3fb8aa3b, v24
	v_exp_f32_e32 v24, v24
	s_nop 0
	v_sub_f32_e32 v60, 1.0, v24
	v_add_f32_e32 v61, 1.0, v24
	v_mul_f32_e32 v60, v60, v61
	v_max_f32_e32 v60, 0, v60
	v_sqrt_f32_e32 v60, v60
	v_add_f32_e32 v61, v165, v171
	v_mul_f32_e32 v61, 0xbfb8aa3b, v61
	v_exp_f32_e32 v61, v61
	v_mul_f32_e32 v25, v25, v60
	v_add_f32_e32 v60, v175, v179
	v_mul_f32_e32 v60, 0xbfb8aa3b, v60
	v_exp_f32_e32 v60, v60
	v_mul_f32_e32 v25, v25, v134
	v_add_f32_e32 v61, 1.0, v61
	v_rcp_f32_e32 v61, v61
	v_add_f32_e32 v60, 1.0, v60
	v_rcp_f32_e32 v60, v60
	s_nop 0
	v_mul_f32_e32 v60, 0xc1000000, v60
	v_mul_f32_e32 v60, v66, v60
	v_mul_f32_e32 v60, 0x3fb8aa3b, v60
	v_exp_f32_e32 v60, v60
	s_nop 0
	v_sub_f32_e32 v134, 1.0, v60
	v_add_f32_e32 v135, 1.0, v60
	v_mul_f32_e32 v134, v134, v135
	v_max_f32_e32 v134, 0, v134
	v_sqrt_f32_e32 v134, v134
	s_nop 0
	v_mul_f32_e32 v61, v61, v134
	v_mul_f32_e32 v61, v61, v58
	ds_write2_b64 v190, v[24:25], v[60:61] offset0:82 offset1:99
	v_mad_u64_u32 v[60:61], s[10:11], s8, v233, v[8:9]
	v_add_u32_e32 v61, s6, v61
	s_waitcnt lgkmcnt(0)
	s_barrier
	global_load_ushort v25, v[60:61], off
	ds_read2_b64 v[162:165], v196 offset1:1
	s_movk_i32 s11, 0xf000
	s_movk_i32 s10, 0x8000
	s_lshl_b64 s[8:9], s[8:9], 11
	v_lshl_add_u64 v[134:135], v[16:17], 0, s[8:9]
	s_waitcnt lgkmcnt(0)
	v_fma_f32 v58, v167, v164, v165
	v_add_f32_e32 v24, v161, v58
	ds_read2_b64 v[164:167], v195 offset1:1
	v_fmac_f32_e32 v163, v58, v162
	v_add_f32_e32 v54, v54, v163
	s_or_b32 s8, s4, 0x17000
	s_mov_b32 s9, s5
	s_waitcnt vmcnt(0)
	v_lshlrev_b32_e32 v25, 16, v25
	v_mul_f32_e32 v24, v24, v25
	v_cvt_pk_bf16_f32 v136, v24, s0
	v_add_co_u32_e32 v24, vcc, s11, v60
	s_nop 1
	v_addc_co_u32_e32 v25, vcc, -1, v61, vcc
	global_load_ushort v138, v[24:25], off offset:-3072
	v_add_co_u32_e32 v24, vcc, s22, v60
	s_nop 1
	v_addc_co_u32_e32 v25, vcc, -1, v61, vcc
	global_load_ushort v139, v[24:25], off offset:-2048
	v_add_co_u32_e32 v24, vcc, s13, v60
	s_nop 1
	v_addc_co_u32_e32 v25, vcc, -1, v61, vcc
	global_load_ushort v140, v[24:25], off offset:-1024
	v_add_co_u32_e32 v24, vcc, s12, v60
	s_nop 1
	v_addc_co_u32_e32 v25, vcc, -1, v61, vcc
	global_load_ushort v142, v[24:25], off
	v_add_co_u32_e32 v24, vcc, s10, v60
	s_nop 1
	v_addc_co_u32_e32 v25, vcc, -1, v61, vcc
	global_load_ushort v143, v[24:25], off offset:-3072
	v_add_co_u32_e32 v24, vcc, s33, v60
	s_nop 1
	v_addc_co_u32_e32 v25, vcc, -1, v61, vcc
	global_load_ushort v144, v[24:25], off offset:-2048
	v_add_co_u32_e32 v24, vcc, s38, v60
	s_nop 1
	v_addc_co_u32_e32 v25, vcc, -1, v61, vcc
	global_load_ushort v146, v[24:25], off offset:-1024
	v_add_co_u32_e32 v24, vcc, s39, v60
	s_nop 1
	v_addc_co_u32_e32 v25, vcc, -1, v61, vcc
	global_load_ushort v158, v[24:25], off
	v_add_co_u32_e32 v24, vcc, s42, v60
	s_nop 1
	v_addc_co_u32_e32 v25, vcc, -1, v61, vcc
	global_load_ushort v159, v[24:25], off offset:-3072
	v_add_co_u32_e32 v24, vcc, s43, v60
	s_nop 1
	v_addc_co_u32_e32 v25, vcc, -1, v61, vcc
	global_load_ushort v161, v[24:25], off offset:-2048
	v_add_co_u32_e32 v24, vcc, s56, v60
	s_nop 1
	v_addc_co_u32_e32 v25, vcc, -1, v61, vcc
	global_load_ushort v168, v[24:25], off offset:-1024
	v_add_co_u32_e32 v24, vcc, s57, v60
	s_nop 1
	v_addc_co_u32_e32 v25, vcc, -1, v61, vcc
	global_load_ushort v169, v[24:25], off
	v_add_co_u32_e32 v24, vcc, s58, v60
	s_nop 1
	v_addc_co_u32_e32 v25, vcc, -1, v61, vcc
	global_load_ushort v170, v[24:25], off offset:-3072
	v_add_co_u32_e32 v24, vcc, s7, v60
	s_waitcnt vmcnt(12)
	v_lshlrev_b32_e32 v58, 16, v138
	v_addc_co_u32_e32 v25, vcc, -1, v61, vcc
	global_load_ushort v25, v[24:25], off offset:-2048
	v_add_co_u32_e32 v60, vcc, s59, v60
	v_mul_f32_e32 v54, v54, v58
	s_nop 0
	v_addc_co_u32_e32 v61, vcc, -1, v61, vcc
	global_load_ushort v24, v[60:61], off offset:-1024
	v_cvt_pk_bf16_f32 v54, v54, s0
	v_lshl_add_u64 v[60:61], v[16:17], 0, s[8:9]
	global_store_short v[60:61], v54, off
	s_waitcnt lgkmcnt(0)
	v_fma_f32 v54, v163, v166, v167
	v_add_f32_e32 v58, v157, v54
	ds_read2_b64 v[154:157], v194 offset1:1
	s_waitcnt vmcnt(14)
	v_lshlrev_b32_e32 v60, 16, v139
	v_fmac_f32_e32 v165, v54, v164
	v_mul_f32_e32 v58, v58, v60
	s_or_b32 s8, s4, 0x16800
	v_add_f32_e32 v53, v53, v165
	s_waitcnt vmcnt(13)
	v_lshlrev_b32_e32 v54, 16, v140
	v_cvt_pk_bf16_f32 v58, v58, s0
	v_lshl_add_u64 v[60:61], v[16:17], 0, s[8:9]
	v_mul_f32_e32 v53, v53, v54
	s_or_b32 s8, s4, 0x16000
	global_store_short v[60:61], v58, off
	v_cvt_pk_bf16_f32 v53, v53, s0
	v_lshl_add_u64 v[60:61], v[16:17], 0, s[8:9]
	global_store_short v[60:61], v53, off
	s_waitcnt lgkmcnt(0)
	v_fma_f32 v53, v165, v156, v157
	v_add_f32_e32 v54, v153, v53
	ds_read2_b64 v[150:153], v193 offset1:1
	s_waitcnt vmcnt(14)
	v_lshlrev_b32_e32 v58, 16, v142
	v_fmac_f32_e32 v155, v53, v154
	v_mul_f32_e32 v54, v54, v58
	s_or_b32 s8, s4, 0x15800
	v_add_f32_e32 v46, v46, v155
	s_waitcnt vmcnt(13)
	v_lshlrev_b32_e32 v53, 16, v143
	v_cvt_pk_bf16_f32 v54, v54, s0
	v_lshl_add_u64 v[60:61], v[16:17], 0, s[8:9]
	v_mul_f32_e32 v46, v46, v53
	s_or_b32 s8, s4, 0x15000
	global_store_short v[60:61], v54, off
	v_cvt_pk_bf16_f32 v46, v46, s0
	v_lshl_add_u64 v[60:61], v[16:17], 0, s[8:9]
	global_store_short v[60:61], v46, off
	s_waitcnt lgkmcnt(0)
	v_fma_f32 v46, v155, v152, v153
	v_add_f32_e32 v53, v149, v46
	v_fmac_f32_e32 v151, v46, v150
	s_waitcnt vmcnt(13)
	v_lshlrev_b32_e32 v46, 16, v146
	ds_read2_b64 v[146:149], v189 offset1:1
	v_lshlrev_b32_e32 v54, 16, v144
	v_mul_f32_e32 v53, v53, v54
	s_or_b32 s8, s4, 0x14800
	v_add_f32_e32 v45, v45, v151
	v_cvt_pk_bf16_f32 v53, v53, s0
	v_lshl_add_u64 v[60:61], v[16:17], 0, s[8:9]
	v_mul_f32_e32 v45, v45, v46
	s_or_b32 s8, s4, 0x14000
	global_store_short v[60:61], v53, off
	v_cvt_pk_bf16_f32 v45, v45, s0
	v_lshl_add_u64 v[60:61], v[16:17], 0, s[8:9]
	global_store_short v[60:61], v45, off
	s_waitcnt lgkmcnt(0)
	v_fma_f32 v45, v151, v148, v149
	v_add_f32_e32 v46, v145, v45
	ds_read2_b64 v[142:145], v185 offset1:1
	s_waitcnt vmcnt(14)
	v_lshlrev_b32_e32 v53, 16, v158
	v_fmac_f32_e32 v147, v45, v146
	v_mul_f32_e32 v46, v46, v53
	s_or_b32 s8, s4, 0x13800
	v_add_f32_e32 v44, v44, v147
	s_waitcnt vmcnt(13)
	v_lshlrev_b32_e32 v45, 16, v159
	v_cvt_pk_bf16_f32 v46, v46, s0
	v_lshl_add_u64 v[60:61], v[16:17], 0, s[8:9]
	v_mul_f32_e32 v44, v44, v45
	s_or_b32 s8, s4, 0x13000
	global_store_short v[60:61], v46, off
	v_cvt_pk_bf16_f32 v46, v44, s0
	v_lshl_add_u64 v[44:45], v[16:17], 0, s[8:9]
	global_store_short v[44:45], v46, off
	s_waitcnt lgkmcnt(0)
	v_fma_f32 v46, v147, v144, v145
	v_add_f32_e32 v44, v141, v46
	s_waitcnt vmcnt(14)
	v_lshlrev_b32_e32 v45, 16, v161
	v_mul_f32_e32 v44, v44, v45
	s_or_b32 s8, s4, 0x12800
	ds_read2_b64 v[138:141], v181 offset1:1
	v_cvt_pk_bf16_f32 v53, v44, s0
	v_lshl_add_u64 v[44:45], v[16:17], 0, s[8:9]
	v_fmac_f32_e32 v143, v46, v142
	global_store_short v[44:45], v53, off
	v_add_f32_e32 v42, v42, v143
	s_waitcnt vmcnt(14)
	v_lshlrev_b32_e32 v44, 16, v168
	v_mul_f32_e32 v42, v42, v44
	s_or_b32 s8, s4, 0x12000
	v_cvt_pk_bf16_f32 v42, v42, s0
	v_lshl_add_u64 v[44:45], v[16:17], 0, s[8:9]
	global_store_short v[44:45], v42, off
	s_waitcnt lgkmcnt(0)
	v_fma_f32 v42, v143, v140, v141
	global_store_short v[134:135], v136, off
	v_add_f32_e32 v44, v137, v42
	ds_read2_b64 v[134:137], v188 offset1:1
	s_waitcnt vmcnt(15)
	v_lshlrev_b32_e32 v45, 16, v169
	v_fmac_f32_e32 v139, v42, v138
	v_mul_f32_e32 v44, v44, v45
	s_or_b32 s8, s4, 0x11800
	v_add_f32_e32 v41, v41, v139
	s_waitcnt vmcnt(14)
	v_lshlrev_b32_e32 v42, 16, v170
	v_cvt_pk_bf16_f32 v46, v44, s0
	v_lshl_add_u64 v[44:45], v[16:17], 0, s[8:9]
	v_mul_f32_e32 v41, v41, v42
	s_or_b32 s8, s4, 0x11000
	global_store_short v[44:45], v46, off
	v_cvt_pk_bf16_f32 v41, v41, s0
	v_lshl_add_u64 v[44:45], v[16:17], 0, s[8:9]
	global_store_short v[44:45], v41, off
	s_waitcnt lgkmcnt(0)
	v_fma_f32 v41, v139, v136, v137
	v_add_f32_e32 v42, v133, v41
	s_waitcnt vmcnt(15)
	v_lshlrev_b32_e32 v25, 16, v25
	v_mul_f32_e32 v25, v42, v25
	s_or_b32 s8, s4, 0x10800
	v_cvt_pk_bf16_f32 v25, v25, s0
	v_lshl_add_u64 v[44:45], v[16:17], 0, s[8:9]
	v_fmac_f32_e32 v135, v41, v134
	global_store_short v[44:45], v25, off
	v_add_f32_e32 v25, v40, v135
	s_waitcnt vmcnt(15)
	v_lshlrev_b32_e32 v24, 16, v24
	v_mul_f32_e32 v24, v25, v24
	s_or_b32 s8, s4, 0x10000
	v_cvt_pk_bf16_f32 v40, v24, s0
	v_lshl_add_u64 v[24:25], v[16:17], 0, s[8:9]
	global_store_short v[24:25], v40, off
	s_barrier
	ds_read_b128 v[136:139], v57 offset:8704
	ds_read_b128 v[144:147], v57 offset:8768
	v_mov_b32_e32 v152, v240
	v_mov_b32_e32 v153, v241
	v_mov_b32_e32 v154, v242
	v_mov_b32_e32 v155, v243
	v_mov_b32_e32 v156, v244
	v_mov_b32_e32 v157, v245
	v_mov_b32_e32 v158, v246
	v_mov_b32_e32 v159, v247
	s_waitcnt lgkmcnt(1)
	v_mfma_f32_16x16x32_bf16 v[140:143], v[120:123], v[136:139], 0
	ds_read_b64 v[24:25], v2 offset:8704
	s_or_b32 s0, s0, 31
	v_mad_u64_u32 v[8:9], s[8:9], s0, v233, v[8:9]
	s_waitcnt lgkmcnt(1)
	v_mfma_f32_16x16x32_bf16 v[140:143], v[128:131], v[144:147], v[140:143]
	s_waitcnt lgkmcnt(0)
	v_lshlrev_b32_e32 v40, 16, v24
	v_and_b32_e32 v41, 0xffff0000, v24
	v_lshlrev_b32_e32 v42, 16, v25
	v_mfma_f32_16x16x32_bf16 v[148:151], v[116:119], v[136:139], 0
	v_and_b32_e32 v44, 0xffff0000, v25
	v_add_u32_e32 v9, s6, v9
	s_waitcnt vmcnt(1)
	v_add_f32_e32 v24, v140, v152
	v_mul_f32_e32 v24, 0xbfb8aa3b, v24
	v_exp_f32_e32 v24, v24
	v_mfma_f32_16x16x32_bf16 v[148:151], v[124:127], v[144:147], v[148:151]
	v_add_f32_e32 v24, 1.0, v24
	v_rcp_f32_e32 v24, v24
	s_nop 0
	v_mul_f32_e32 v24, 0xc1000000, v24
	v_mul_f32_e32 v24, v48, v24
	v_mul_f32_e32 v24, 0x3fb8aa3b, v24
	s_waitcnt vmcnt(0)
	s_nop 0
	v_add_f32_e32 v25, v148, v156
	v_exp_f32_e32 v24, v24
	v_mul_f32_e32 v25, 0xbfb8aa3b, v25
	v_exp_f32_e32 v25, v25
	v_sub_f32_e32 v45, 1.0, v24
	v_add_f32_e32 v46, 1.0, v24
	v_mul_f32_e32 v45, v45, v46
	v_add_f32_e32 v25, 1.0, v25
	v_max_f32_e32 v45, 0, v45
	v_rcp_f32_e32 v25, v25
	v_sqrt_f32_e32 v45, v45
	s_nop 0
	v_mul_f32_e32 v25, v25, v45
	v_mul_f32_e32 v25, v25, v40
	v_add_f32_e32 v40, v141, v153
	v_mul_f32_e32 v40, 0xbfb8aa3b, v40
	v_exp_f32_e32 v40, v40
	v_add_f32_e32 v45, v149, v157
	v_mul_f32_e32 v45, 0xbfb8aa3b, v45
	v_exp_f32_e32 v45, v45
	v_add_f32_e32 v40, 1.0, v40
	v_rcp_f32_e32 v40, v40
	v_add_f32_e32 v45, 1.0, v45
	v_rcp_f32_e32 v45, v45
	v_mul_f32_e32 v40, 0xc1000000, v40
	v_mul_f32_e32 v40, v49, v40
	v_mul_f32_e32 v40, 0x3fb8aa3b, v40
	v_exp_f32_e32 v40, v40
	s_nop 0
	v_sub_f32_e32 v46, 1.0, v40
	v_add_f32_e32 v53, 1.0, v40
	v_mul_f32_e32 v46, v46, v53
	v_max_f32_e32 v46, 0, v46
	v_sqrt_f32_e32 v46, v46
	s_nop 0
	v_mul_f32_e32 v45, v45, v46
	v_mul_f32_e32 v41, v45, v41
	ds_write2_b64 v56, v[24:25], v[40:41] offset1:17
	v_add_f32_e32 v24, v142, v154
	v_mul_f32_e32 v24, 0xbfb8aa3b, v24
	v_exp_f32_e32 v24, v24
	v_add_f32_e32 v25, v150, v158
	v_mul_f32_e32 v25, 0xbfb8aa3b, v25
	v_exp_f32_e32 v25, v25
	v_add_f32_e32 v24, 1.0, v24
	v_rcp_f32_e32 v24, v24
	v_add_f32_e32 v25, 1.0, v25
	v_rcp_f32_e32 v25, v25
	v_mul_f32_e32 v24, 0xc1000000, v24
	v_mul_f32_e32 v24, v50, v24
	v_mul_f32_e32 v24, 0x3fb8aa3b, v24
	v_exp_f32_e32 v24, v24
	s_nop 0
	v_sub_f32_e32 v40, 1.0, v24
	v_add_f32_e32 v41, 1.0, v24
	v_mul_f32_e32 v40, v40, v41
	v_max_f32_e32 v40, 0, v40
	v_sqrt_f32_e32 v40, v40
	v_add_f32_e32 v41, v151, v159
	v_mul_f32_e32 v41, 0xbfb8aa3b, v41
	v_exp_f32_e32 v41, v41
	v_mul_f32_e32 v25, v25, v40
	v_add_f32_e32 v40, v143, v155
	v_mul_f32_e32 v40, 0xbfb8aa3b, v40
	v_exp_f32_e32 v40, v40
	v_mul_f32_e32 v25, v25, v42
	v_add_f32_e32 v41, 1.0, v41
	v_rcp_f32_e32 v41, v41
	v_add_f32_e32 v40, 1.0, v40
	v_rcp_f32_e32 v40, v40
	v_mfma_f32_16x16x32_bf16 v[140:143], v[104:107], v[136:139], 0
	v_mul_f32_e32 v40, 0xc1000000, v40
	v_mul_f32_e32 v40, v52, v40
	v_mul_f32_e32 v40, 0x3fb8aa3b, v40
	v_exp_f32_e32 v40, v40
	v_mfma_f32_16x16x32_bf16 v[148:151], v[112:115], v[144:147], v[140:143]
	v_sub_f32_e32 v42, 1.0, v40
	v_add_f32_e32 v45, 1.0, v40
	v_mul_f32_e32 v42, v42, v45
	v_max_f32_e32 v42, 0, v42
	v_sqrt_f32_e32 v42, v42
	v_mfma_f32_16x16x32_bf16 v[140:143], v[100:103], v[136:139], 0
	v_mul_f32_e32 v41, v41, v42
	v_mul_f32_e32 v41, v41, v44
	ds_write2_b64 v56, v[24:25], v[40:41] offset0:34 offset1:51
	v_mov_b32_e32 v152, v248
	v_mov_b32_e32 v153, v249
	v_mov_b32_e32 v154, v250
	v_mov_b32_e32 v155, v251
	v_mov_b32_e32 v156, v224
	v_mov_b32_e32 v157, v225
	v_mov_b32_e32 v158, v226
	v_mov_b32_e32 v159, v227
	ds_read_b64 v[24:25], v2 offset:8736
	v_mfma_f32_16x16x32_bf16 v[140:143], v[108:111], v[144:147], v[140:143]
	s_waitcnt lgkmcnt(0)
	v_lshlrev_b32_e32 v40, 16, v24
	v_and_b32_e32 v41, 0xffff0000, v24
	v_lshlrev_b32_e32 v42, 16, v25
	v_and_b32_e32 v44, 0xffff0000, v25
	s_waitcnt vmcnt(1)
	v_add_f32_e32 v24, v148, v152
	v_mul_f32_e32 v24, 0xbfb8aa3b, v24
	v_exp_f32_e32 v24, v24
	s_waitcnt vmcnt(0)
	v_add_f32_e32 v25, v140, v156
	v_mul_f32_e32 v25, 0xbfb8aa3b, v25
	v_exp_f32_e32 v25, v25
	v_add_f32_e32 v24, 1.0, v24
	v_rcp_f32_e32 v24, v24
	v_add_f32_e32 v25, 1.0, v25
	v_rcp_f32_e32 v25, v25
	v_mul_f32_e32 v24, 0xc1000000, v24
	v_mul_f32_e32 v24, v182, v24
	v_mul_f32_e32 v24, 0x3fb8aa3b, v24
	v_exp_f32_e32 v24, v24
	s_nop 0
	v_sub_f32_e32 v45, 1.0, v24
	v_add_f32_e32 v46, 1.0, v24
	v_mul_f32_e32 v45, v45, v46
	v_max_f32_e32 v45, 0, v45
	v_sqrt_f32_e32 v45, v45
	s_nop 0
	v_mul_f32_e32 v25, v25, v45
	v_mul_f32_e32 v25, v25, v40
	v_add_f32_e32 v40, v149, v153
	v_mul_f32_e32 v40, 0xbfb8aa3b, v40
	v_exp_f32_e32 v40, v40
	v_add_f32_e32 v45, v141, v157
	v_mul_f32_e32 v45, 0xbfb8aa3b, v45
	v_exp_f32_e32 v45, v45
	v_add_f32_e32 v40, 1.0, v40
	v_rcp_f32_e32 v40, v40
	v_add_f32_e32 v45, 1.0, v45
	v_rcp_f32_e32 v45, v45
	v_mul_f32_e32 v40, 0xc1000000, v40
	v_mul_f32_e32 v40, v184, v40
	v_mul_f32_e32 v40, 0x3fb8aa3b, v40
	v_exp_f32_e32 v40, v40
	s_nop 0
	v_sub_f32_e32 v46, 1.0, v40
	v_add_f32_e32 v53, 1.0, v40
	v_mul_f32_e32 v46, v46, v53
	v_max_f32_e32 v46, 0, v46
	v_sqrt_f32_e32 v46, v46
	s_nop 0
	v_mul_f32_e32 v45, v45, v46
	v_mul_f32_e32 v41, v45, v41
	ds_write2_b64 v192, v[24:25], v[40:41] offset0:16 offset1:33
	v_add_f32_e32 v24, v150, v154
	v_mul_f32_e32 v24, 0xbfb8aa3b, v24
	v_exp_f32_e32 v24, v24
	v_add_f32_e32 v25, v142, v158
	v_mul_f32_e32 v25, 0xbfb8aa3b, v25
	v_exp_f32_e32 v25, v25
	v_add_f32_e32 v24, 1.0, v24
	v_rcp_f32_e32 v24, v24
	v_add_f32_e32 v25, 1.0, v25
	v_rcp_f32_e32 v25, v25
	v_mul_f32_e32 v24, 0xc1000000, v24
	v_mul_f32_e32 v24, v186, v24
	v_mul_f32_e32 v24, 0x3fb8aa3b, v24
	v_exp_f32_e32 v24, v24
	s_nop 0
	v_sub_f32_e32 v40, 1.0, v24
	v_add_f32_e32 v41, 1.0, v24
	v_mul_f32_e32 v40, v40, v41
	v_max_f32_e32 v40, 0, v40
	v_sqrt_f32_e32 v40, v40
	v_add_f32_e32 v41, v143, v159
	v_mul_f32_e32 v41, 0xbfb8aa3b, v41
	v_exp_f32_e32 v41, v41
	v_mul_f32_e32 v25, v25, v40
	v_add_f32_e32 v40, v151, v155
	v_mul_f32_e32 v40, 0xbfb8aa3b, v40
	v_exp_f32_e32 v40, v40
	v_mul_f32_e32 v25, v25, v42
	v_add_f32_e32 v41, 1.0, v41
	v_rcp_f32_e32 v41, v41
	v_add_f32_e32 v40, 1.0, v40
	v_rcp_f32_e32 v40, v40
	v_mfma_f32_16x16x32_bf16 v[140:143], v[88:91], v[136:139], 0
	v_mul_f32_e32 v40, 0xc1000000, v40
	v_mul_f32_e32 v40, v187, v40
	v_mul_f32_e32 v40, 0x3fb8aa3b, v40
	v_exp_f32_e32 v40, v40
	v_mfma_f32_16x16x32_bf16 v[140:143], v[96:99], v[144:147], v[140:143]
	v_sub_f32_e32 v42, 1.0, v40
	v_add_f32_e32 v45, 1.0, v40
	v_mul_f32_e32 v42, v42, v45
	v_max_f32_e32 v42, 0, v42
	v_sqrt_f32_e32 v42, v42
	v_mfma_f32_16x16x32_bf16 v[148:151], v[84:87], v[136:139], 0
	v_mul_f32_e32 v41, v41, v42
	v_mul_f32_e32 v41, v41, v44
	ds_write2_b64 v192, v[24:25], v[40:41] offset0:50 offset1:67
	v_mov_b32_e32 v152, v223
	v_mov_b32_e32 v153, v229
	v_mov_b32_e32 v154, v230
	v_mov_b32_e32 v155, v231
	v_mov_b32_e32 v156, v232
	v_mov_b32_e32 v157, v237
	v_mov_b32_e32 v158, v238
	v_mov_b32_e32 v159, v239
	ds_read_b64 v[24:25], v2 offset:8768
	v_mfma_f32_16x16x32_bf16 v[148:151], v[92:95], v[144:147], v[148:151]
	s_waitcnt lgkmcnt(0)
	v_lshlrev_b32_e32 v40, 16, v24
	v_and_b32_e32 v41, 0xffff0000, v24
	v_lshlrev_b32_e32 v42, 16, v25
	v_and_b32_e32 v44, 0xffff0000, v25
	s_waitcnt vmcnt(1)
	v_add_f32_e32 v24, v140, v152
	v_mul_f32_e32 v24, 0xbfb8aa3b, v24
	v_exp_f32_e32 v24, v24
	s_waitcnt vmcnt(0)
	v_add_f32_e32 v25, v148, v156
	v_mul_f32_e32 v25, 0xbfb8aa3b, v25
	v_exp_f32_e32 v25, v25
	v_add_f32_e32 v24, 1.0, v24
	v_rcp_f32_e32 v24, v24
	v_add_f32_e32 v25, 1.0, v25
	v_rcp_f32_e32 v25, v25
	v_mul_f32_e32 v24, 0xc1000000, v24
	v_mul_f32_e32 v24, v132, v24
	v_mul_f32_e32 v24, 0x3fb8aa3b, v24
	v_exp_f32_e32 v24, v24
	s_nop 0
	v_sub_f32_e32 v45, 1.0, v24
	v_add_f32_e32 v46, 1.0, v24
	v_mul_f32_e32 v45, v45, v46
	v_max_f32_e32 v45, 0, v45
	v_sqrt_f32_e32 v45, v45
	s_nop 0
	v_mul_f32_e32 v25, v25, v45
	v_mul_f32_e32 v25, v25, v40
	v_add_f32_e32 v40, v141, v153
	v_mul_f32_e32 v40, 0xbfb8aa3b, v40
	v_exp_f32_e32 v40, v40
	v_add_f32_e32 v45, v149, v157
	v_mul_f32_e32 v45, 0xbfb8aa3b, v45
	v_exp_f32_e32 v45, v45
	v_add_f32_e32 v40, 1.0, v40
	v_rcp_f32_e32 v40, v40
	v_add_f32_e32 v45, 1.0, v45
	v_rcp_f32_e32 v45, v45
	v_mul_f32_e32 v40, 0xc1000000, v40
	v_mul_f32_e32 v40, v160, v40
	v_mul_f32_e32 v40, 0x3fb8aa3b, v40
	v_exp_f32_e32 v40, v40
	s_nop 0
	v_sub_f32_e32 v46, 1.0, v40
	v_add_f32_e32 v53, 1.0, v40
	v_mul_f32_e32 v46, v46, v53
	v_max_f32_e32 v46, 0, v46
	v_sqrt_f32_e32 v46, v46
	s_nop 0
	v_mul_f32_e32 v45, v45, v46
	v_mul_f32_e32 v41, v45, v41
	ds_write2_b64 v191, v[24:25], v[40:41] offset0:32 offset1:49
	v_add_f32_e32 v24, v142, v154
	v_mul_f32_e32 v24, 0xbfb8aa3b, v24
	v_exp_f32_e32 v24, v24
	v_add_f32_e32 v25, v150, v158
	v_mul_f32_e32 v25, 0xbfb8aa3b, v25
	v_exp_f32_e32 v25, v25
	v_add_f32_e32 v24, 1.0, v24
	v_rcp_f32_e32 v24, v24
	v_add_f32_e32 v25, 1.0, v25
	v_rcp_f32_e32 v25, v25
	v_mul_f32_e32 v24, 0xc1000000, v24
	v_mul_f32_e32 v24, v180, v24
	v_mul_f32_e32 v24, 0x3fb8aa3b, v24
	v_exp_f32_e32 v24, v24
	s_nop 0
	v_sub_f32_e32 v40, 1.0, v24
	v_add_f32_e32 v41, 1.0, v24
	v_mul_f32_e32 v40, v40, v41
	v_max_f32_e32 v40, 0, v40
	v_sqrt_f32_e32 v40, v40
	v_add_f32_e32 v41, v151, v159
	v_mul_f32_e32 v41, 0xbfb8aa3b, v41
	v_exp_f32_e32 v41, v41
	v_mul_f32_e32 v25, v25, v40
	v_add_f32_e32 v40, v143, v155
	v_mul_f32_e32 v40, 0xbfb8aa3b, v40
	v_exp_f32_e32 v40, v40
	v_mul_f32_e32 v25, v25, v42
	v_add_f32_e32 v41, 1.0, v41
	v_rcp_f32_e32 v41, v41
	v_add_f32_e32 v40, 1.0, v40
	v_rcp_f32_e32 v40, v40
	v_mfma_f32_16x16x32_bf16 v[140:143], v[72:75], v[136:139], 0
	v_mul_f32_e32 v40, 0xc1000000, v40
	v_mul_f32_e32 v40, v183, v40
	v_mul_f32_e32 v40, 0x3fb8aa3b, v40
	v_exp_f32_e32 v40, v40
	v_mfma_f32_16x16x32_bf16 v[136:139], v[68:71], v[136:139], 0
	v_sub_f32_e32 v42, 1.0, v40
	v_add_f32_e32 v45, 1.0, v40
	v_mul_f32_e32 v42, v42, v45
	v_max_f32_e32 v42, 0, v42
	v_sqrt_f32_e32 v42, v42
	v_mfma_f32_16x16x32_bf16 v[140:143], v[80:83], v[144:147], v[140:143]
	v_mul_f32_e32 v41, v41, v42
	v_mul_f32_e32 v41, v41, v44
	ds_write2_b64 v191, v[24:25], v[40:41] offset0:66 offset1:83
	v_mfma_f32_16x16x32_bf16 v[136:139], v[76:79], v[144:147], v[136:139]
	global_load_dwordx4 v[148:151], v[4:5], off offset:192
	global_load_dwordx4 v[144:147], v[0:1], off offset:192
	ds_read_b64 v[24:25], v2 offset:8800
	s_waitcnt lgkmcnt(0)
	v_lshlrev_b32_e32 v41, 16, v24
	v_and_b32_e32 v42, 0xffff0000, v24
	v_lshlrev_b32_e32 v46, 16, v25
	v_and_b32_e32 v40, 0xffff0000, v25
	s_waitcnt vmcnt(1)
	v_add_f32_e32 v24, v140, v148
	v_mul_f32_e32 v24, 0xbfb8aa3b, v24
	v_exp_f32_e32 v24, v24
	s_waitcnt vmcnt(0)
	v_add_f32_e32 v25, v136, v144
	v_mul_f32_e32 v25, 0xbfb8aa3b, v25
	v_exp_f32_e32 v25, v25
	v_add_f32_e32 v24, 1.0, v24
	v_rcp_f32_e32 v24, v24
	v_add_f32_e32 v25, 1.0, v25
	v_rcp_f32_e32 v25, v25
	v_mul_f32_e32 v24, 0xc1000000, v24
	v_mul_f32_e32 v24, v62, v24
	v_mul_f32_e32 v24, 0x3fb8aa3b, v24
	v_exp_f32_e32 v24, v24
	s_nop 0
	v_sub_f32_e32 v44, 1.0, v24
	v_add_f32_e32 v45, 1.0, v24
	v_mul_f32_e32 v44, v44, v45
	v_max_f32_e32 v44, 0, v44
	v_sqrt_f32_e32 v44, v44
	s_nop 0
	v_mul_f32_e32 v25, v25, v44
	v_mul_f32_e32 v25, v25, v41
	v_add_f32_e32 v41, v141, v149
	v_mul_f32_e32 v41, 0xbfb8aa3b, v41
	v_exp_f32_e32 v41, v41
	v_add_f32_e32 v44, v137, v145
	v_mul_f32_e32 v44, 0xbfb8aa3b, v44
	v_exp_f32_e32 v44, v44
	v_add_f32_e32 v41, 1.0, v41
	v_rcp_f32_e32 v41, v41
	v_add_f32_e32 v44, 1.0, v44
	v_rcp_f32_e32 v45, v44
	v_mul_f32_e32 v41, 0xc1000000, v41
	v_mul_f32_e32 v41, v64, v41
	v_mul_f32_e32 v41, 0x3fb8aa3b, v41
	v_exp_f32_e32 v44, v41
	s_nop 0
	v_sub_f32_e32 v41, 1.0, v44
	v_add_f32_e32 v53, 1.0, v44
	v_mul_f32_e32 v41, v41, v53
	v_max_f32_e32 v41, 0, v41
	v_sqrt_f32_e32 v41, v41
	s_nop 0
	v_mul_f32_e32 v41, v45, v41
	v_mul_f32_e32 v45, v41, v42
	ds_write2_b64 v190, v[24:25], v[44:45] offset0:48 offset1:65
	v_add_f32_e32 v24, v142, v150
	v_mul_f32_e32 v24, 0xbfb8aa3b, v24
	v_exp_f32_e32 v24, v24
	v_add_f32_e32 v25, v138, v146
	v_mul_f32_e32 v25, 0xbfb8aa3b, v25
	v_exp_f32_e32 v25, v25
	v_add_f32_e32 v24, 1.0, v24
	v_rcp_f32_e32 v24, v24
	v_add_f32_e32 v25, 1.0, v25
	v_rcp_f32_e32 v25, v25
	v_mul_f32_e32 v24, 0xc1000000, v24
	v_mul_f32_e32 v24, v65, v24
	v_mul_f32_e32 v24, 0x3fb8aa3b, v24
	v_exp_f32_e32 v24, v24
	s_nop 0
	v_sub_f32_e32 v41, 1.0, v24
	v_add_f32_e32 v42, 1.0, v24
	v_mul_f32_e32 v41, v41, v42
	v_max_f32_e32 v41, 0, v41
	v_sqrt_f32_e32 v41, v41
	v_add_f32_e32 v42, v139, v147
	v_mul_f32_e32 v42, 0xbfb8aa3b, v42
	v_exp_f32_e32 v42, v42
	v_mul_f32_e32 v25, v25, v41
	v_add_f32_e32 v41, v143, v151
	v_mul_f32_e32 v41, 0xbfb8aa3b, v41
	v_exp_f32_e32 v41, v41
	v_add_f32_e32 v42, 1.0, v42
	v_rcp_f32_e32 v42, v42
	v_mul_f32_e32 v25, v25, v46
	v_add_f32_e32 v41, 1.0, v41
	v_rcp_f32_e32 v41, v41
	s_nop 0
	v_mul_f32_e32 v41, 0xc1000000, v41
	v_mul_f32_e32 v41, v66, v41
	v_mul_f32_e32 v41, 0x3fb8aa3b, v41
	v_exp_f32_e32 v44, v41
	s_nop 0
	v_sub_f32_e32 v41, 1.0, v44
	v_add_f32_e32 v45, 1.0, v44
	v_mul_f32_e32 v41, v41, v45
	v_max_f32_e32 v41, 0, v41
	v_sqrt_f32_e32 v41, v41
	s_nop 0
	v_mul_f32_e32 v41, v42, v41
	v_mul_f32_e32 v45, v41, v40
	ds_write2_b64 v190, v[24:25], v[44:45] offset0:82 offset1:99
	s_waitcnt lgkmcnt(0)
	s_barrier
	global_load_ushort v25, v[8:9], off
	ds_read2_b64 v[136:139], v196 offset1:1
	s_waitcnt lgkmcnt(0)
	v_fma_f32 v42, v135, v138, v139
	v_add_f32_e32 v24, v67, v42
	v_fmac_f32_e32 v137, v42, v136
	ds_read2_b64 v[138:141], v195 offset1:1
	v_add_f32_e32 v38, v38, v137
	s_waitcnt vmcnt(0)
	v_lshlrev_b32_e32 v25, 16, v25
	v_mul_f32_e32 v24, v24, v25
	v_cvt_pk_bf16_f32 v46, v24, s0
	v_add_co_u32_e32 v24, vcc, s11, v8
	s_lshl_b64 s[0:1], s[0:1], 11
	s_nop 0
	v_addc_co_u32_e32 v25, vcc, -1, v9, vcc
	global_load_ushort v53, v[24:25], off offset:-3072
	v_add_co_u32_e32 v24, vcc, s22, v8
	v_lshl_add_u64 v[40:41], v[16:17], 0, s[0:1]
	s_nop 0
	v_addc_co_u32_e32 v25, vcc, -1, v9, vcc
	global_load_ushort v54, v[24:25], off offset:-2048
	v_add_co_u32_e32 v24, vcc, s13, v8
	s_mov_b32 s1, s5
	s_nop 0
	v_addc_co_u32_e32 v25, vcc, -1, v9, vcc
	global_load_ushort v58, v[24:25], off offset:-1024
	v_add_co_u32_e32 v24, vcc, s12, v8
	s_nop 1
	v_addc_co_u32_e32 v25, vcc, -1, v9, vcc
	global_load_ushort v60, v[24:25], off
	v_add_co_u32_e32 v24, vcc, s10, v8
	s_nop 1
	v_addc_co_u32_e32 v25, vcc, -1, v9, vcc
	global_load_ushort v61, v[24:25], off offset:-3072
	v_add_co_u32_e32 v24, vcc, s33, v8
	s_nop 1
	v_addc_co_u32_e32 v25, vcc, -1, v9, vcc
	global_load_ushort v67, v[24:25], off offset:-2048
	v_add_co_u32_e32 v24, vcc, s38, v8
	s_nop 1
	v_addc_co_u32_e32 v25, vcc, -1, v9, vcc
	global_load_ushort v133, v[24:25], off offset:-1024
	v_add_co_u32_e32 v24, vcc, s39, v8
	s_nop 1
	v_addc_co_u32_e32 v25, vcc, -1, v9, vcc
	global_load_ushort v142, v[24:25], off
	v_add_co_u32_e32 v24, vcc, s42, v8
	s_nop 1
	v_addc_co_u32_e32 v25, vcc, -1, v9, vcc
	global_load_ushort v143, v[24:25], off offset:-3072
	v_add_co_u32_e32 v24, vcc, s43, v8
	s_nop 1
	v_addc_co_u32_e32 v25, vcc, -1, v9, vcc
	global_load_ushort v144, v[24:25], off offset:-2048
	v_add_co_u32_e32 v24, vcc, s56, v8
	s_nop 1
	v_addc_co_u32_e32 v25, vcc, -1, v9, vcc
	global_load_ushort v145, v[24:25], off offset:-1024
	v_add_co_u32_e32 v24, vcc, s57, v8
	s_nop 1
	v_addc_co_u32_e32 v25, vcc, -1, v9, vcc
	global_load_ushort v146, v[24:25], off
	v_add_co_u32_e32 v24, vcc, s58, v8
	s_nop 1
	v_addc_co_u32_e32 v25, vcc, -1, v9, vcc
	global_load_ushort v147, v[24:25], off offset:-3072
	v_add_co_u32_e32 v24, vcc, s7, v8
	s_nop 1
	v_addc_co_u32_e32 v25, vcc, -1, v9, vcc
	global_load_ushort v25, v[24:25], off offset:-2048
	v_add_co_u32_e32 v44, vcc, s59, v8
	s_waitcnt vmcnt(0)
	v_lshlrev_b32_e32 v25, 16, v25
	v_addc_co_u32_e32 v45, vcc, -1, v9, vcc
	global_load_ushort v24, v[44:45], off offset:-1024
	s_waitcnt vmcnt(0)
	v_lshlrev_b32_e32 v24, 16, v24
	global_store_short v[40:41], v46, off
	v_lshlrev_b32_e32 v40, 16, v53
	v_mul_f32_e32 v38, v38, v40
	v_cvt_pk_bf16_f32 v38, v38, s0
	s_or_b32 s0, s4, 0xf000
	v_lshl_add_u64 v[40:41], v[16:17], 0, s[0:1]
	global_store_short v[40:41], v38, off
	s_waitcnt lgkmcnt(0)
	v_fma_f32 v38, v137, v140, v141
	v_add_f32_e32 v40, v63, v38
	v_lshlrev_b32_e32 v41, 16, v54
	v_fmac_f32_e32 v139, v38, v138
	ds_read2_b64 v[134:137], v194 offset1:1
	v_mul_f32_e32 v40, v40, v41
	v_add_f32_e32 v37, v37, v139
	v_lshlrev_b32_e32 v38, 16, v58
	v_cvt_pk_bf16_f32 v42, v40, s0
	s_or_b32 s0, s4, 0xe800
	v_mul_f32_e32 v37, v37, v38
	v_lshl_add_u64 v[40:41], v[16:17], 0, s[0:1]
	v_cvt_pk_bf16_f32 v37, v37, s0
	s_or_b32 s0, s4, 0xe000
	global_store_short v[40:41], v42, off
	v_lshl_add_u64 v[40:41], v[16:17], 0, s[0:1]
	global_store_short v[40:41], v37, off
	s_waitcnt lgkmcnt(0)
	v_fma_f32 v37, v139, v136, v137
	v_add_f32_e32 v38, v59, v37
	v_lshlrev_b32_e32 v40, 16, v60
	v_mul_f32_e32 v38, v38, v40
	v_fmac_f32_e32 v135, v37, v134
	v_lshlrev_b32_e32 v37, 16, v61
	ds_read2_b64 v[58:61], v193 offset1:1
	v_cvt_pk_bf16_f32 v38, v38, s0
	s_or_b32 s0, s4, 0xd800
	v_add_f32_e32 v36, v36, v135
	v_lshl_add_u64 v[40:41], v[16:17], 0, s[0:1]
	v_mul_f32_e32 v36, v36, v37
	global_store_short v[40:41], v38, off
	v_cvt_pk_bf16_f32 v38, v36, s0
	s_or_b32 s0, s4, 0xd000
	v_lshl_add_u64 v[36:37], v[16:17], 0, s[0:1]
	global_store_short v[36:37], v38, off
	s_waitcnt lgkmcnt(0)
	v_fma_f32 v38, v135, v60, v61
	v_add_f32_e32 v36, v55, v38
	v_lshlrev_b32_e32 v37, 16, v67
	v_mul_f32_e32 v36, v36, v37
	v_cvt_pk_bf16_f32 v40, v36, s0
	s_or_b32 s0, s4, 0xc800
	v_lshl_add_u64 v[36:37], v[16:17], 0, s[0:1]
	v_fmac_f32_e32 v59, v38, v58
	ds_read2_b64 v[134:137], v189 offset1:1
	global_store_short v[36:37], v40, off
	v_add_f32_e32 v34, v34, v59
	v_lshlrev_b32_e32 v36, 16, v133
	v_mul_f32_e32 v34, v34, v36
	v_cvt_pk_bf16_f32 v34, v34, s0
	s_or_b32 s0, s4, 0xc000
	v_lshl_add_u64 v[36:37], v[16:17], 0, s[0:1]
	global_store_short v[36:37], v34, off
	s_waitcnt lgkmcnt(0)
	v_fma_f32 v34, v59, v136, v137
	v_add_f32_e32 v36, v51, v34
	v_lshlrev_b32_e32 v37, 16, v142
	v_fmac_f32_e32 v135, v34, v134
	ds_read2_b64 v[58:61], v185 offset1:1
	v_mul_f32_e32 v36, v36, v37
	v_add_f32_e32 v33, v33, v135
	v_lshlrev_b32_e32 v34, 16, v143
	v_cvt_pk_bf16_f32 v38, v36, s0
	s_or_b32 s0, s4, 0xb800
	v_mul_f32_e32 v33, v33, v34
	v_lshl_add_u64 v[36:37], v[16:17], 0, s[0:1]
	v_cvt_pk_bf16_f32 v33, v33, s0
	s_or_b32 s0, s4, 0xb000
	global_store_short v[36:37], v38, off
	v_lshl_add_u64 v[36:37], v[16:17], 0, s[0:1]
	global_store_short v[36:37], v33, off
	s_waitcnt lgkmcnt(0)
	v_fma_f32 v33, v135, v60, v61
	v_add_f32_e32 v34, v47, v33
	v_lshlrev_b32_e32 v36, 16, v144
	v_mul_f32_e32 v34, v34, v36
	v_fmac_f32_e32 v59, v33, v58
	ds_read2_b64 v[44:47], v181 offset1:1
	v_cvt_pk_bf16_f32 v34, v34, s0
	s_or_b32 s0, s4, 0xa800
	v_add_f32_e32 v32, v32, v59
	v_lshlrev_b32_e32 v33, 16, v145
	v_lshl_add_u64 v[36:37], v[16:17], 0, s[0:1]
	v_mul_f32_e32 v32, v32, v33
	global_store_short v[36:37], v34, off
	v_cvt_pk_bf16_f32 v34, v32, s0
	s_or_b32 s0, s4, 0xa000
	v_lshl_add_u64 v[32:33], v[16:17], 0, s[0:1]
	global_store_short v[32:33], v34, off
	s_waitcnt lgkmcnt(0)
	v_fma_f32 v34, v59, v46, v47
	v_add_f32_e32 v32, v43, v34
	v_lshlrev_b32_e32 v33, 16, v146
	v_mul_f32_e32 v32, v32, v33
	v_cvt_pk_bf16_f32 v36, v32, s0
	s_or_b32 s0, s4, 0x9800
	v_lshl_add_u64 v[32:33], v[16:17], 0, s[0:1]
	v_fmac_f32_e32 v45, v34, v44
	ds_read2_b64 v[40:43], v188 offset1:1
	global_store_short v[32:33], v36, off
	v_add_f32_e32 v30, v30, v45
	v_lshlrev_b32_e32 v32, 16, v147
	v_mul_f32_e32 v30, v30, v32
	v_cvt_pk_bf16_f32 v30, v30, s0
	s_or_b32 s0, s4, 0x9000
	v_lshl_add_u64 v[32:33], v[16:17], 0, s[0:1]
	global_store_short v[32:33], v30, off
	s_waitcnt lgkmcnt(0)
	v_fma_f32 v30, v45, v42, v43
	v_add_f32_e32 v32, v39, v30
	v_mul_f32_e32 v25, v32, v25
	v_cvt_pk_bf16_f32 v25, v25, s0
	s_or_b32 s0, s4, 0x8800
	v_lshl_add_u64 v[32:33], v[16:17], 0, s[0:1]
	v_fmac_f32_e32 v41, v30, v40
	global_store_short v[32:33], v25, off
	v_add_f32_e32 v25, v29, v41
	v_mul_f32_e32 v24, v25, v24
	v_cvt_pk_bf16_f32 v29, v24, s0
	s_or_b32 s0, s4, 0x8000
	v_lshl_add_u64 v[24:25], v[16:17], 0, s[0:1]
	global_store_short v[24:25], v29, off
	s_barrier
	ds_read_b128 v[36:39], v57
	ds_read_b128 v[42:45], v57 offset:64
	s_waitcnt lgkmcnt(1)
	v_mfma_f32_16x16x32_bf16 v[116:119], v[116:119], v[36:39], 0
	s_mov_b32 s0, 0xfffe4000
	v_mfma_f32_16x16x32_bf16 v[58:61], v[120:123], v[36:39], 0
	s_waitcnt lgkmcnt(0)
	v_mfma_f32_16x16x32_bf16 v[116:119], v[124:127], v[42:45], v[116:119]
	v_mov_b32_e32 v120, v240
	v_mov_b32_e32 v121, v241
	v_mov_b32_e32 v122, v242
	v_mov_b32_e32 v123, v243
	v_mov_b32_e32 v124, v244
	v_mov_b32_e32 v125, v245
	v_mov_b32_e32 v126, v246
	v_mov_b32_e32 v127, v247
	ds_read_b64 v[24:25], v2
	s_waitcnt lgkmcnt(0)
	v_lshlrev_b32_e32 v29, 16, v24
	v_mfma_f32_16x16x32_bf16 v[58:61], v[128:131], v[42:45], v[58:61]
	v_and_b32_e32 v30, 0xffff0000, v24
	v_lshlrev_b32_e32 v34, 16, v25
	v_and_b32_e32 v40, 0xffff0000, v25
	s_waitcnt vmcnt(0)
	v_add_f32_e32 v25, v116, v124
	s_nop 2
	v_add_f32_e32 v24, v58, v120
	v_mul_f32_e32 v24, 0xbfb8aa3b, v24
	v_exp_f32_e32 v24, v24
	v_mul_f32_e32 v25, 0xbfb8aa3b, v25
	v_exp_f32_e32 v25, v25
	v_add_f32_e32 v24, 1.0, v24
	v_rcp_f32_e32 v24, v24
	v_add_f32_e32 v25, 1.0, v25
	v_rcp_f32_e32 v25, v25
	v_mul_f32_e32 v24, 0xc1000000, v24
	v_mul_f32_e32 v24, v48, v24
	v_mul_f32_e32 v24, 0x3fb8aa3b, v24
	v_exp_f32_e32 v24, v24
	s_nop 0
	v_sub_f32_e32 v32, 1.0, v24
	v_add_f32_e32 v33, 1.0, v24
	v_mul_f32_e32 v32, v32, v33
	v_max_f32_e32 v32, 0, v32
	v_sqrt_f32_e32 v32, v32
	s_nop 0
	v_mul_f32_e32 v25, v25, v32
	v_mul_f32_e32 v25, v25, v29
	v_add_f32_e32 v29, v59, v121
	v_mul_f32_e32 v29, 0xbfb8aa3b, v29
	v_exp_f32_e32 v29, v29
	v_add_f32_e32 v32, v117, v125
	v_mul_f32_e32 v32, 0xbfb8aa3b, v32
	v_exp_f32_e32 v32, v32
	v_add_f32_e32 v29, 1.0, v29
	v_rcp_f32_e32 v29, v29
	v_add_f32_e32 v32, 1.0, v32
	v_rcp_f32_e32 v33, v32
	v_mul_f32_e32 v29, 0xc1000000, v29
	v_mul_f32_e32 v29, v49, v29
	v_mul_f32_e32 v29, 0x3fb8aa3b, v29
	v_exp_f32_e32 v32, v29
	s_nop 0
	v_sub_f32_e32 v29, 1.0, v32
	v_add_f32_e32 v46, 1.0, v32
	v_mul_f32_e32 v29, v29, v46
	v_max_f32_e32 v29, 0, v29
	v_sqrt_f32_e32 v29, v29
	v_mfma_f32_16x16x32_bf16 v[46:49], v[104:107], v[36:39], 0
	v_mul_f32_e32 v29, v33, v29
	v_mul_f32_e32 v33, v29, v30
	ds_write2_b64 v56, v[24:25], v[32:33] offset1:17
	v_add_f32_e32 v24, v60, v122
	v_mul_f32_e32 v24, 0xbfb8aa3b, v24
	v_exp_f32_e32 v24, v24
	v_add_f32_e32 v25, v118, v126
	v_mul_f32_e32 v25, 0xbfb8aa3b, v25
	v_exp_f32_e32 v25, v25
	v_add_f32_e32 v24, 1.0, v24
	v_rcp_f32_e32 v24, v24
	v_add_f32_e32 v25, 1.0, v25
	v_rcp_f32_e32 v25, v25
	v_mul_f32_e32 v24, 0xc1000000, v24
	v_mul_f32_e32 v24, v50, v24
	v_mul_f32_e32 v24, 0x3fb8aa3b, v24
	v_exp_f32_e32 v24, v24
	s_nop 0
	v_sub_f32_e32 v29, 1.0, v24
	v_add_f32_e32 v30, 1.0, v24
	v_mul_f32_e32 v29, v29, v30
	v_max_f32_e32 v29, 0, v29
	v_sqrt_f32_e32 v29, v29
	v_add_f32_e32 v30, v119, v127
	v_mul_f32_e32 v30, 0xbfb8aa3b, v30
	v_exp_f32_e32 v30, v30
	v_mul_f32_e32 v25, v25, v29
	v_add_f32_e32 v29, v61, v123
	v_mul_f32_e32 v29, 0xbfb8aa3b, v29
	v_exp_f32_e32 v29, v29
	v_add_f32_e32 v30, 1.0, v30
	v_rcp_f32_e32 v30, v30
	v_mul_f32_e32 v25, v25, v34
	v_add_f32_e32 v29, 1.0, v29
	v_rcp_f32_e32 v29, v29
	s_nop 0
	v_mul_f32_e32 v29, 0xc1000000, v29
	v_mul_f32_e32 v29, v52, v29
	v_mul_f32_e32 v29, 0x3fb8aa3b, v29
	v_exp_f32_e32 v32, v29
	v_mfma_f32_16x16x32_bf16 v[50:53], v[112:115], v[42:45], v[46:49]
	v_sub_f32_e32 v29, 1.0, v32
	v_add_f32_e32 v33, 1.0, v32
	v_mul_f32_e32 v29, v29, v33
	v_max_f32_e32 v29, 0, v29
	v_sqrt_f32_e32 v29, v29
	v_mfma_f32_16x16x32_bf16 v[46:49], v[100:103], v[36:39], 0
	v_mul_f32_e32 v29, v30, v29
	v_mul_f32_e32 v33, v29, v40
	ds_write2_b64 v56, v[24:25], v[32:33] offset0:34 offset1:51
	v_mov_b32_e32 v54, v248
	v_mov_b32_e32 v55, v249
	v_mov_b32_e32 v56, v250
	v_mov_b32_e32 v57, v251
	v_mov_b32_e32 v58, v224
	v_mov_b32_e32 v59, v225
	v_mov_b32_e32 v60, v226
	v_mov_b32_e32 v61, v227
	ds_read_b64 v[24:25], v2 offset:32
	v_mfma_f32_16x16x32_bf16 v[46:49], v[108:111], v[42:45], v[46:49]
	s_waitcnt lgkmcnt(0)
	v_lshlrev_b32_e32 v29, 16, v24
	v_and_b32_e32 v30, 0xffff0000, v24
	v_lshlrev_b32_e32 v34, 16, v25
	v_and_b32_e32 v40, 0xffff0000, v25
	s_waitcnt vmcnt(1)
	v_add_f32_e32 v24, v50, v54
	v_mul_f32_e32 v24, 0xbfb8aa3b, v24
	v_exp_f32_e32 v24, v24
	s_waitcnt vmcnt(0)
	v_add_f32_e32 v25, v46, v58
	v_mul_f32_e32 v25, 0xbfb8aa3b, v25
	v_exp_f32_e32 v25, v25
	v_add_f32_e32 v24, 1.0, v24
	v_rcp_f32_e32 v24, v24
	v_add_f32_e32 v25, 1.0, v25
	v_rcp_f32_e32 v25, v25
	v_mul_f32_e32 v24, 0xc1000000, v24
	v_mul_f32_e32 v24, v182, v24
	v_mul_f32_e32 v24, 0x3fb8aa3b, v24
	v_exp_f32_e32 v24, v24
	s_nop 0
	v_sub_f32_e32 v32, 1.0, v24
	v_add_f32_e32 v33, 1.0, v24
	v_mul_f32_e32 v32, v32, v33
	v_max_f32_e32 v32, 0, v32
	v_sqrt_f32_e32 v32, v32
	s_nop 0
	v_mul_f32_e32 v25, v25, v32
	v_mul_f32_e32 v25, v25, v29
	v_add_f32_e32 v29, v51, v55
	v_mul_f32_e32 v29, 0xbfb8aa3b, v29
	v_exp_f32_e32 v29, v29
	v_add_f32_e32 v32, v47, v59
	v_mul_f32_e32 v32, 0xbfb8aa3b, v32
	v_exp_f32_e32 v32, v32
	v_add_f32_e32 v29, 1.0, v29
	v_rcp_f32_e32 v29, v29
	v_add_f32_e32 v32, 1.0, v32
	v_rcp_f32_e32 v33, v32
	v_mul_f32_e32 v29, 0xc1000000, v29
	v_mul_f32_e32 v29, v184, v29
	v_mul_f32_e32 v29, 0x3fb8aa3b, v29
	v_exp_f32_e32 v32, v29
	s_nop 0
	v_sub_f32_e32 v29, 1.0, v32
	v_add_f32_e32 v46, 1.0, v32
	v_mul_f32_e32 v29, v29, v46
	v_max_f32_e32 v29, 0, v29
	v_sqrt_f32_e32 v29, v29
	s_nop 0
	v_mul_f32_e32 v29, v33, v29
	v_mul_f32_e32 v33, v29, v30
	ds_write2_b64 v192, v[24:25], v[32:33] offset0:16 offset1:33
	v_add_f32_e32 v24, v52, v56
	v_mul_f32_e32 v24, 0xbfb8aa3b, v24
	v_exp_f32_e32 v24, v24
	v_add_f32_e32 v25, v48, v60
	v_mul_f32_e32 v25, 0xbfb8aa3b, v25
	v_exp_f32_e32 v25, v25
	v_add_f32_e32 v24, 1.0, v24
	v_rcp_f32_e32 v24, v24
	v_add_f32_e32 v25, 1.0, v25
	v_rcp_f32_e32 v25, v25
	v_mul_f32_e32 v24, 0xc1000000, v24
	v_mul_f32_e32 v24, v186, v24
	v_mul_f32_e32 v24, 0x3fb8aa3b, v24
	v_exp_f32_e32 v24, v24
	s_nop 0
	v_sub_f32_e32 v29, 1.0, v24
	v_add_f32_e32 v30, 1.0, v24
	v_mul_f32_e32 v29, v29, v30
	v_max_f32_e32 v29, 0, v29
	v_sqrt_f32_e32 v29, v29
	v_add_f32_e32 v30, v49, v61
	v_mul_f32_e32 v30, 0xbfb8aa3b, v30
	v_exp_f32_e32 v30, v30
	v_mul_f32_e32 v25, v25, v29
	v_add_f32_e32 v29, v53, v57
	v_mul_f32_e32 v29, 0xbfb8aa3b, v29
	v_exp_f32_e32 v29, v29
	v_add_f32_e32 v30, 1.0, v30
	v_rcp_f32_e32 v30, v30
	v_mul_f32_e32 v25, v25, v34
	v_add_f32_e32 v29, 1.0, v29
	v_rcp_f32_e32 v29, v29
	v_mfma_f32_16x16x32_bf16 v[46:49], v[88:91], v[36:39], 0
	v_mul_f32_e32 v29, 0xc1000000, v29
	v_mul_f32_e32 v29, v187, v29
	v_mul_f32_e32 v29, 0x3fb8aa3b, v29
	v_exp_f32_e32 v32, v29
	v_mfma_f32_16x16x32_bf16 v[50:53], v[96:99], v[42:45], v[46:49]
	v_sub_f32_e32 v29, 1.0, v32
	v_add_f32_e32 v33, 1.0, v32
	v_mul_f32_e32 v29, v29, v33
	v_max_f32_e32 v29, 0, v29
	v_sqrt_f32_e32 v29, v29
	v_mfma_f32_16x16x32_bf16 v[46:49], v[84:87], v[36:39], 0
	v_mul_f32_e32 v29, v30, v29
	v_mul_f32_e32 v33, v29, v40
	ds_write2_b64 v192, v[24:25], v[32:33] offset0:50 offset1:67
	v_mov_b32_e32 v54, v223
	v_mov_b32_e32 v55, v229
	v_mov_b32_e32 v56, v230
	v_mov_b32_e32 v57, v231
	v_mov_b32_e32 v58, v232
	v_mov_b32_e32 v59, v237
	v_mov_b32_e32 v60, v238
	v_mov_b32_e32 v61, v239
	ds_read_b64 v[24:25], v2 offset:64
	v_mfma_f32_16x16x32_bf16 v[46:49], v[92:95], v[42:45], v[46:49]
	s_waitcnt lgkmcnt(0)
	v_lshlrev_b32_e32 v29, 16, v24
	v_and_b32_e32 v30, 0xffff0000, v24
	v_lshlrev_b32_e32 v34, 16, v25
	v_and_b32_e32 v40, 0xffff0000, v25
	s_waitcnt vmcnt(1)
	v_add_f32_e32 v24, v50, v54
	v_mul_f32_e32 v24, 0xbfb8aa3b, v24
	v_exp_f32_e32 v24, v24
	s_waitcnt vmcnt(0)
	v_add_f32_e32 v25, v46, v58
	v_mul_f32_e32 v25, 0xbfb8aa3b, v25
	v_exp_f32_e32 v25, v25
	v_add_f32_e32 v24, 1.0, v24
	v_rcp_f32_e32 v24, v24
	v_add_f32_e32 v25, 1.0, v25
	v_rcp_f32_e32 v25, v25
	v_mul_f32_e32 v24, 0xc1000000, v24
	v_mul_f32_e32 v24, v132, v24
	v_mul_f32_e32 v24, 0x3fb8aa3b, v24
	v_exp_f32_e32 v24, v24
	s_nop 0
	v_sub_f32_e32 v32, 1.0, v24
	v_add_f32_e32 v33, 1.0, v24
	v_mul_f32_e32 v32, v32, v33
	v_max_f32_e32 v32, 0, v32
	v_sqrt_f32_e32 v32, v32
	s_nop 0
	v_mul_f32_e32 v25, v25, v32
	v_mul_f32_e32 v25, v25, v29
	v_add_f32_e32 v29, v51, v55
	v_mul_f32_e32 v29, 0xbfb8aa3b, v29
	v_exp_f32_e32 v29, v29
	v_add_f32_e32 v32, v47, v59
	v_mul_f32_e32 v32, 0xbfb8aa3b, v32
	v_exp_f32_e32 v32, v32
	v_add_f32_e32 v29, 1.0, v29
	v_rcp_f32_e32 v29, v29
	v_add_f32_e32 v32, 1.0, v32
	v_rcp_f32_e32 v33, v32
	v_mul_f32_e32 v29, 0xc1000000, v29
	v_mul_f32_e32 v29, v160, v29
	v_mul_f32_e32 v29, 0x3fb8aa3b, v29
	v_exp_f32_e32 v32, v29
	s_nop 0
	v_sub_f32_e32 v29, 1.0, v32
	v_add_f32_e32 v46, 1.0, v32
	v_mul_f32_e32 v29, v29, v46
	v_max_f32_e32 v29, 0, v29
	v_sqrt_f32_e32 v29, v29
	s_nop 0
	v_mul_f32_e32 v29, v33, v29
	v_mul_f32_e32 v33, v29, v30
	ds_write2_b64 v191, v[24:25], v[32:33] offset0:32 offset1:49
	v_add_f32_e32 v24, v52, v56
	v_mul_f32_e32 v24, 0xbfb8aa3b, v24
	v_exp_f32_e32 v24, v24
	v_add_f32_e32 v25, v48, v60
	v_mul_f32_e32 v25, 0xbfb8aa3b, v25
	v_exp_f32_e32 v25, v25
	v_add_f32_e32 v24, 1.0, v24
	v_rcp_f32_e32 v24, v24
	v_add_f32_e32 v25, 1.0, v25
	v_rcp_f32_e32 v25, v25
	v_mul_f32_e32 v24, 0xc1000000, v24
	v_mul_f32_e32 v24, v180, v24
	v_mul_f32_e32 v24, 0x3fb8aa3b, v24
	v_exp_f32_e32 v24, v24
	s_nop 0
	v_sub_f32_e32 v29, 1.0, v24
	v_add_f32_e32 v30, 1.0, v24
	v_mul_f32_e32 v29, v29, v30
	v_max_f32_e32 v29, 0, v29
	v_sqrt_f32_e32 v29, v29
	v_add_f32_e32 v30, v49, v61
	v_mul_f32_e32 v30, 0xbfb8aa3b, v30
	v_exp_f32_e32 v30, v30
	v_mul_f32_e32 v25, v25, v29
	v_add_f32_e32 v29, v53, v57
	v_mul_f32_e32 v29, 0xbfb8aa3b, v29
	v_exp_f32_e32 v29, v29
	v_add_f32_e32 v30, 1.0, v30
	v_rcp_f32_e32 v30, v30
	v_mfma_f32_16x16x32_bf16 v[46:49], v[72:75], v[36:39], 0
	v_add_f32_e32 v29, 1.0, v29
	v_rcp_f32_e32 v29, v29
	v_mul_f32_e32 v25, v25, v34
	v_mfma_f32_16x16x32_bf16 v[36:39], v[68:71], v[36:39], 0
	v_mul_f32_e32 v29, 0xc1000000, v29
	v_mul_f32_e32 v29, v183, v29
	v_mul_f32_e32 v29, 0x3fb8aa3b, v29
	v_exp_f32_e32 v32, v29
	v_mfma_f32_16x16x32_bf16 v[46:49], v[80:83], v[42:45], v[46:49]
	v_sub_f32_e32 v29, 1.0, v32
	v_add_f32_e32 v33, 1.0, v32
	v_mul_f32_e32 v29, v29, v33
	v_max_f32_e32 v29, 0, v29
	v_sqrt_f32_e32 v29, v29
	v_mfma_f32_16x16x32_bf16 v[36:39], v[76:79], v[42:45], v[36:39]
	v_mul_f32_e32 v29, v30, v29
	v_mul_f32_e32 v33, v29, v40
	ds_write2_b64 v191, v[24:25], v[32:33] offset0:66 offset1:83
	global_load_dwordx4 v[42:45], v[4:5], off offset:192
	global_load_dwordx4 v[50:53], v[0:1], off offset:192
	ds_read_b64 v[0:1], v2 offset:96
	s_waitcnt lgkmcnt(0)
	v_lshlrev_b32_e32 v2, 16, v0
	v_and_b32_e32 v5, 0xffff0000, v0
	v_lshlrev_b32_e32 v24, 16, v1
	v_and_b32_e32 v25, 0xffff0000, v1
	s_waitcnt vmcnt(1)
	v_add_f32_e32 v0, v46, v42
	v_mul_f32_e32 v0, 0xbfb8aa3b, v0
	v_exp_f32_e32 v0, v0
	s_waitcnt vmcnt(0)
	v_add_f32_e32 v1, v36, v50
	v_mul_f32_e32 v1, 0xbfb8aa3b, v1
	v_exp_f32_e32 v1, v1
	v_add_f32_e32 v0, 1.0, v0
	v_rcp_f32_e32 v0, v0
	v_add_f32_e32 v1, 1.0, v1
	v_rcp_f32_e32 v1, v1
	v_mul_f32_e32 v0, 0xc1000000, v0
	v_mul_f32_e32 v0, v62, v0
	v_mul_f32_e32 v0, 0x3fb8aa3b, v0
	v_exp_f32_e32 v0, v0
	s_nop 0
	v_sub_f32_e32 v4, 1.0, v0
	v_add_f32_e32 v29, 1.0, v0
	v_mul_f32_e32 v4, v4, v29
	v_max_f32_e32 v4, 0, v4
	v_sqrt_f32_e32 v4, v4
	s_nop 0
	v_mul_f32_e32 v1, v1, v4
	v_mul_f32_e32 v1, v1, v2
	v_add_f32_e32 v2, v47, v43
	v_mul_f32_e32 v2, 0xbfb8aa3b, v2
	v_exp_f32_e32 v2, v2
	v_add_f32_e32 v4, v37, v51
	v_mul_f32_e32 v4, 0xbfb8aa3b, v4
	v_exp_f32_e32 v4, v4
	v_add_f32_e32 v2, 1.0, v2
	v_rcp_f32_e32 v2, v2
	v_add_f32_e32 v4, 1.0, v4
	v_rcp_f32_e32 v29, v4
	v_mul_f32_e32 v2, 0xc1000000, v2
	v_mul_f32_e32 v2, v64, v2
	v_mul_f32_e32 v2, 0x3fb8aa3b, v2
	v_exp_f32_e32 v4, v2
	s_nop 0
	v_sub_f32_e32 v2, 1.0, v4
	v_add_f32_e32 v30, 1.0, v4
	v_mul_f32_e32 v2, v2, v30
	v_max_f32_e32 v2, 0, v2
	v_sqrt_f32_e32 v2, v2
	s_nop 0
	v_mul_f32_e32 v2, v29, v2
	v_mul_f32_e32 v5, v2, v5
	ds_write2_b64 v190, v[0:1], v[4:5] offset0:48 offset1:65
	v_add_f32_e32 v0, v48, v44
	v_mul_f32_e32 v0, 0xbfb8aa3b, v0
	v_exp_f32_e32 v0, v0
	v_add_f32_e32 v1, v38, v52
	v_mul_f32_e32 v1, 0xbfb8aa3b, v1
	v_exp_f32_e32 v1, v1
	v_add_f32_e32 v0, 1.0, v0
	v_rcp_f32_e32 v0, v0
	v_add_f32_e32 v1, 1.0, v1
	v_rcp_f32_e32 v1, v1
	v_mul_f32_e32 v0, 0xc1000000, v0
	v_mul_f32_e32 v0, v65, v0
	v_mul_f32_e32 v0, 0x3fb8aa3b, v0
	v_exp_f32_e32 v0, v0
	s_nop 0
	v_sub_f32_e32 v2, 1.0, v0
	v_add_f32_e32 v4, 1.0, v0
	v_mul_f32_e32 v2, v2, v4
	v_max_f32_e32 v2, 0, v2
	v_sqrt_f32_e32 v2, v2
	v_add_f32_e32 v4, v39, v53
	v_mul_f32_e32 v4, 0xbfb8aa3b, v4
	v_exp_f32_e32 v4, v4
	v_mul_f32_e32 v1, v1, v2
	v_add_f32_e32 v2, v49, v45
	v_mul_f32_e32 v2, 0xbfb8aa3b, v2
	v_exp_f32_e32 v2, v2
	v_add_f32_e32 v4, 1.0, v4
	v_rcp_f32_e32 v5, v4
	v_mul_f32_e32 v1, v1, v24
	v_add_f32_e32 v2, 1.0, v2
	v_rcp_f32_e32 v2, v2
	s_nop 0
	v_mul_f32_e32 v2, 0xc1000000, v2
	v_mul_f32_e32 v2, v66, v2
	v_mul_f32_e32 v2, 0x3fb8aa3b, v2
	v_exp_f32_e32 v4, v2
	s_nop 0
	v_sub_f32_e32 v2, 1.0, v4
	v_add_f32_e32 v24, 1.0, v4
	v_mul_f32_e32 v2, v2, v24
	v_max_f32_e32 v2, 0, v2
	v_sqrt_f32_e32 v2, v2
	s_nop 0
	v_mul_f32_e32 v2, v5, v2
	v_mul_f32_e32 v5, v2, v25
	ds_write2_b64 v190, v[0:1], v[4:5] offset0:82 offset1:99
	v_add_co_u32_e32 v0, vcc, s0, v8
	s_waitcnt lgkmcnt(0)
	s_nop 0
	v_addc_co_u32_e32 v1, vcc, -1, v9, vcc
	s_barrier
	global_load_ushort v0, v[0:1], off
	ds_read2_b64 v[36:39], v196 offset1:1
	s_waitcnt lgkmcnt(0)
	v_fma_f32 v2, v41, v38, v39
	v_add_f32_e32 v4, v35, v2
	v_fmac_f32_e32 v37, v2, v36
	v_add_f32_e32 v2, v28, v37
	s_waitcnt vmcnt(0)
	v_lshlrev_b32_e32 v0, 16, v0
	v_mul_f32_e32 v0, v4, v0
	v_cvt_pk_bf16_f32 v24, v0, s0
	s_or_b32 s0, s4, 0x7800
	v_lshl_add_u64 v[4:5], v[16:17], 0, s[0:1]
	s_mov_b32 s0, 0xfffe3000
	v_add_co_u32_e32 v0, vcc, s0, v8
	s_mov_b32 s0, 0xfffe1000
	s_nop 0
	v_addc_co_u32_e32 v1, vcc, -1, v9, vcc
	global_load_ushort v25, v[0:1], off offset:-3072
	v_add_co_u32_e32 v0, vcc, s0, v8
	s_mov_b32 s0, 0xfffdf000
	s_nop 0
	v_addc_co_u32_e32 v1, vcc, -1, v9, vcc
	global_load_ushort v29, v[0:1], off offset:-2048
	v_add_co_u32_e32 v0, vcc, s0, v8
	s_mov_b32 s0, 0xfffdd000
	s_nop 0
	v_addc_co_u32_e32 v1, vcc, -1, v9, vcc
	global_load_ushort v30, v[0:1], off offset:-1024
	v_add_co_u32_e32 v0, vcc, s0, v8
	s_mov_b32 s0, 0xfffdc000
	s_nop 0
	v_addc_co_u32_e32 v1, vcc, -1, v9, vcc
	global_load_ushort v38, v[0:1], off
	v_add_co_u32_e32 v0, vcc, s0, v8
	s_mov_b32 s0, 0xfffda000
	s_nop 0
	v_addc_co_u32_e32 v1, vcc, -1, v9, vcc
	global_load_ushort v39, v[0:1], off offset:-3072
	v_add_co_u32_e32 v0, vcc, s0, v8
	s_mov_b32 s0, 0xfffd8000
	s_nop 0
	v_addc_co_u32_e32 v1, vcc, -1, v9, vcc
	global_load_ushort v40, v[0:1], off offset:-2048
	v_add_co_u32_e32 v0, vcc, s0, v8
	s_mov_b32 s0, 0xfffd6000
	s_nop 0
	v_addc_co_u32_e32 v1, vcc, -1, v9, vcc
	global_load_ushort v41, v[0:1], off offset:-1024
	v_add_co_u32_e32 v0, vcc, s0, v8
	s_mov_b32 s0, 0xfffd5000
	s_nop 0
	v_addc_co_u32_e32 v1, vcc, -1, v9, vcc
	global_load_ushort v42, v[0:1], off
	v_add_co_u32_e32 v0, vcc, s0, v8
	s_mov_b32 s0, 0xfffd3000
	s_nop 0
	v_addc_co_u32_e32 v1, vcc, -1, v9, vcc
	global_load_ushort v43, v[0:1], off offset:-3072
	v_add_co_u32_e32 v0, vcc, s0, v8
	s_mov_b32 s0, 0xfffd1000
	s_nop 0
	v_addc_co_u32_e32 v1, vcc, -1, v9, vcc
	global_load_ushort v44, v[0:1], off offset:-2048
	v_add_co_u32_e32 v0, vcc, s0, v8
	s_mov_b32 s0, 0xfffcf000
	s_nop 0
	v_addc_co_u32_e32 v1, vcc, -1, v9, vcc
	global_load_ushort v45, v[0:1], off offset:-1024
	v_add_co_u32_e32 v0, vcc, s0, v8
	s_mov_b32 s0, 0xfffce000
	s_nop 0
	v_addc_co_u32_e32 v1, vcc, -1, v9, vcc
	global_load_ushort v46, v[0:1], off
	v_add_co_u32_e32 v0, vcc, s0, v8
	s_mov_b32 s0, 0xfffcc000
	s_nop 0
	v_addc_co_u32_e32 v1, vcc, -1, v9, vcc
	global_load_ushort v47, v[0:1], off offset:-3072
	v_add_co_u32_e32 v0, vcc, s0, v8
	s_nop 1
	v_addc_co_u32_e32 v1, vcc, -1, v9, vcc
	global_load_ushort v1, v[0:1], off offset:-2048
	s_nop 0
	global_load_ushort v0, v[12:13], off
	ds_read2_b64 v[32:35], v195 offset1:1
	global_store_short v[4:5], v24, off
	s_waitcnt vmcnt(15)
	v_lshlrev_b32_e32 v4, 16, v25
	v_mul_f32_e32 v2, v2, v4
	v_cvt_pk_bf16_f32 v2, v2, s0
	s_or_b32 s0, s4, 0x7000
	v_lshl_add_u64 v[4:5], v[16:17], 0, s[0:1]
	global_store_short v[4:5], v2, off
	s_waitcnt lgkmcnt(0)
	v_fma_f32 v2, v37, v34, v35
	v_add_f32_e32 v4, v31, v2
	s_waitcnt vmcnt(15)
	v_lshlrev_b32_e32 v5, 16, v29
	v_mul_f32_e32 v4, v4, v5
	v_cvt_pk_bf16_f32 v8, v4, s0
	s_or_b32 s0, s4, 0x6800
	v_lshl_add_u64 v[4:5], v[16:17], 0, s[0:1]
	global_store_short v[4:5], v8, off
	v_fmac_f32_e32 v33, v2, v32
	s_waitcnt vmcnt(15)
	v_lshlrev_b32_e32 v4, 16, v30
	ds_read2_b64 v[28:31], v194 offset1:1
	v_add_f32_e32 v2, v26, v33
	v_mul_f32_e32 v2, v2, v4
	v_cvt_pk_bf16_f32 v2, v2, s0
	s_or_b32 s0, s4, 0x6000
	v_lshl_add_u64 v[4:5], v[16:17], 0, s[0:1]
	global_store_short v[4:5], v2, off
	s_waitcnt lgkmcnt(0)
	v_fma_f32 v2, v33, v30, v31
	v_add_f32_e32 v4, v27, v2
	s_waitcnt vmcnt(15)
	v_lshlrev_b32_e32 v5, 16, v38
	v_mul_f32_e32 v4, v4, v5
	v_cvt_pk_bf16_f32 v8, v4, s0
	s_or_b32 s0, s4, 0x5800
	v_lshl_add_u64 v[4:5], v[16:17], 0, s[0:1]
	v_fmac_f32_e32 v29, v2, v28
	ds_read2_b64 v[24:27], v193 offset1:1
	global_store_short v[4:5], v8, off
	v_add_f32_e32 v2, v22, v29
	s_waitcnt vmcnt(15)
	v_lshlrev_b32_e32 v4, 16, v39
	v_mul_f32_e32 v2, v2, v4
	v_cvt_pk_bf16_f32 v2, v2, s0
	s_or_b32 s0, s4, 0x5000
	v_lshl_add_u64 v[4:5], v[16:17], 0, s[0:1]
	global_store_short v[4:5], v2, off
	s_waitcnt lgkmcnt(0)
	v_fma_f32 v2, v29, v26, v27
	v_add_f32_e32 v4, v23, v2
	s_waitcnt vmcnt(15)
	v_lshlrev_b32_e32 v5, 16, v40
	v_mul_f32_e32 v4, v4, v5
	v_cvt_pk_bf16_f32 v8, v4, s0
	s_or_b32 s0, s4, 0x4800
	v_lshl_add_u64 v[4:5], v[16:17], 0, s[0:1]
	v_fmac_f32_e32 v25, v2, v24
	ds_read2_b64 v[26:29], v189 offset1:1
	global_store_short v[4:5], v8, off
	v_add_f32_e32 v2, v18, v25
	s_waitcnt vmcnt(15)
	v_lshlrev_b32_e32 v4, 16, v41
	v_mul_f32_e32 v2, v2, v4
	v_cvt_pk_bf16_f32 v2, v2, s0
	s_or_b32 s0, s4, 0x4000
	v_lshl_add_u64 v[4:5], v[16:17], 0, s[0:1]
	global_store_short v[4:5], v2, off
	s_waitcnt lgkmcnt(0)
	v_fma_f32 v2, v25, v28, v29
	v_add_f32_e32 v4, v19, v2
	s_waitcnt vmcnt(15)
	v_lshlrev_b32_e32 v5, 16, v42
	v_mul_f32_e32 v4, v4, v5
	v_cvt_pk_bf16_f32 v8, v4, s0
	s_or_b32 s0, s4, 0x3800
	v_lshl_add_u64 v[4:5], v[16:17], 0, s[0:1]
	v_fmac_f32_e32 v27, v2, v26
	ds_read2_b64 v[22:25], v185 offset1:1
	global_store_short v[4:5], v8, off
	v_add_f32_e32 v2, v14, v27
	s_waitcnt vmcnt(15)
	v_lshlrev_b32_e32 v4, 16, v43
	v_mul_f32_e32 v2, v2, v4
	v_cvt_pk_bf16_f32 v2, v2, s0
	s_or_b32 s0, s4, 0x3000
	v_lshl_add_u64 v[4:5], v[16:17], 0, s[0:1]
	global_store_short v[4:5], v2, off
	s_waitcnt lgkmcnt(0)
	v_fma_f32 v2, v27, v24, v25
	v_add_f32_e32 v4, v15, v2
	s_waitcnt vmcnt(15)
	v_lshlrev_b32_e32 v5, 16, v44
	v_mul_f32_e32 v4, v4, v5
	v_cvt_pk_bf16_f32 v8, v4, s0
	s_or_b32 s0, s4, 0x2800
	v_lshl_add_u64 v[4:5], v[16:17], 0, s[0:1]
	v_fmac_f32_e32 v23, v2, v22
	ds_read2_b64 v[12:15], v181 offset1:1
	global_store_short v[4:5], v8, off
	v_add_f32_e32 v2, v10, v23
	s_waitcnt vmcnt(15)
	v_lshlrev_b32_e32 v4, 16, v45
	v_mul_f32_e32 v2, v2, v4
	v_cvt_pk_bf16_f32 v2, v2, s0
	s_or_b32 s0, s4, 0x2000
	v_lshl_add_u64 v[4:5], v[16:17], 0, s[0:1]
	global_store_short v[4:5], v2, off
	s_waitcnt lgkmcnt(0)
	v_fma_f32 v2, v23, v14, v15
	v_add_f32_e32 v4, v11, v2
	s_waitcnt vmcnt(15)
	v_lshlrev_b32_e32 v5, 16, v46
	v_mul_f32_e32 v4, v4, v5
	v_cvt_pk_bf16_f32 v8, v4, s0
	s_or_b32 s0, s4, 0x1800
	v_lshl_add_u64 v[4:5], v[16:17], 0, s[0:1]
	global_store_short v[4:5], v8, off
	v_fmac_f32_e32 v13, v2, v12
	ds_read2_b64 v[8:11], v188 offset1:1
	v_add_f32_e32 v2, v6, v13
	s_waitcnt vmcnt(15)
	v_lshlrev_b32_e32 v4, 16, v47
	v_mul_f32_e32 v2, v2, v4
	v_cvt_pk_bf16_f32 v2, v2, s0
	s_or_b32 s0, s4, 0x1000
	v_lshl_add_u64 v[4:5], v[16:17], 0, s[0:1]
	global_store_short v[4:5], v2, off
	s_waitcnt lgkmcnt(0)
	v_fma_f32 v2, v13, v10, v11
	v_add_f32_e32 v4, v7, v2
	s_waitcnt vmcnt(15)
	v_lshlrev_b32_e32 v1, 16, v1
	v_mul_f32_e32 v1, v4, v1
	s_bitset1_b32 s4, 11
	v_cvt_pk_bf16_f32 v1, v1, s0
	v_lshl_add_u64 v[4:5], v[16:17], 0, s[4:5]
	v_fmac_f32_e32 v9, v2, v8
	global_store_short v[4:5], v1, off
	v_add_f32_e32 v1, v220, v9
	s_waitcnt vmcnt(15)
	v_lshlrev_b32_e32 v0, 16, v0
	v_mul_f32_e32 v0, v1, v0
	v_cvt_pk_bf16_f32 v0, v0, s0
	global_store_short v[20:21], v0, off
	s_barrier
	v_mov_b32_e32 v223, 0x358637bd
	v_mov_b32_e32 v224, 0x1000
	v_mov_b32_e32 v225, 0x2000
	v_mov_b32_e32 v226, 1
	v_mov_b32_e32 v227, 0x3727c5ac
	v_bfrev_b32_e32 v229, 0.5
	v_mov_b32_e32 v230, 0x41b17218
	v_mov_b32_e32 v231, 0x3e8293ee
	v_mov_b32_e32 v232, 0xfffff000
	v_mov_b32_e32 v237, 0x1dc0000
	v_mov_b32_e32 v238, 0x1100
